# stack: SSD sb-loop LDS prefetch + scalar muls, SSD dt wait moved, EpiKV/EpiQ stat loads hoisted, attention loads spread + packed adds split, store-aware first waits per tile
# speedup vs baseline: 1.0075x; 1.0047x over previous
; #define SEAM(k) do { if (IN(k) && IN((k) + 1)) { xcd_barrier(xbar); } } while (0)
; __device__ __forceinline__ void xcd_barrier(const XcdBarrier& b) {
;     ...
;     __syncthreads();
; __global__ void __launch_bounds__(512, 2) fwd_kernel(Args a) {
;     ...
;     if (IN(0)) { p0_prologue(a, lds); } SEAM(0);
;     if (IN(1)) { pg8::Gemm g{(const bf16_t*)(ws + WS_U), (const bf16_t*)(ws + WS_WIN), M, PROJ_LD, DM, DM}; pg8::StaticOrder S; S.init(M, PROJ_LD, G, (int)blockIdx.x);
.LBB0_466:
	s_or_b64 exec, exec, s[2:3]
	s_waitcnt lgkmcnt(0)
	s_barrier
	s_mov_b32 s32, 0

; #define PG8_MMA(ai, bj, At, Bt) do { __builtin_amdgcn_s_setprio(1); _Pragma("unroll") for (int m = 0; m < 4; ++m) _Pragma("unroll") for (int n = 0; n < 2; ++n) _Pragma("unroll") for (int k = 0; k < 2; ++k) \
;         acc[ai][bj][m][n] = __builtin_amdgcn_mfma_f32_16x16x32_bf16(Bt[n][k], At[m][k], acc[ai][bj][m][n], 0, 0, 0); __builtin_amdgcn_s_setprio(0); } while (0)
; #define PG8_WAIT_V(n) asm volatile("s_waitcnt vmcnt(" #n ")" ::: "memory")
; #define PG8_WAIT_L(n) asm volatile("s_waitcnt lgkmcnt(" #n ")" ::: "memory")
; #define PG8_BAR __builtin_amdgcn_s_barrier()
; #define PG8_SCHED __builtin_amdgcn_sched_barrier(0)
; template <class Epi, bool SEG = false>
; __device__ __forceinline__ void gemm_phase(LAS unsigned char* lds, const Gemm g, const StaticOrder& S, const Epi& E, const float* stat2 = nullptr) {
;     ...
;             PG8_WAIT_V(8); PG8_WAIT_L(0); PG8_BAR; PG8_MMA(0, 0, At, B0); PG8_MMA(0, 1, At, B1); PG8_BAR; PG8_SCHED;
.Lt1_rx0_0:
	s_waitcnt vmcnt(24)
	s_branch .Lt1_j0_0
.Lt1_rx0_1:
	s_waitcnt vmcnt(24)
	s_mov_b32 s32, 0
	s_branch .Lt1_j0_1

; #define PG8_STAGE(bufoff, gbase, voff) do { _Pragma("unroll") for (int _i = 0; _i < 2; ++_i) \
;         __builtin_amdgcn_global_load_lds((const unsigned*)((const char*)(gbase) + (voff)[_i]), (LAS unsigned*)(lds + (bufoff) + ldsw + _i * 8192), 16, 0, 0); } while (0)
; #define PG8_LDA(dst, b, h) do { _Pragma("unroll") for (int m = 0; m < 4; ++m) _Pragma("unroll") for (int k = 0; k < 2; ++k) dst[m][k] = *(const LAS bf16x8*)(lds + PG8_SA(b, h) + aoff + m * 2048 + k * 1024); } while (0)
; #define PG8_LDB(dst, b, h) do { _Pragma("unroll") for (int n = 0; n < 2; ++n) _Pragma("unroll") for (int k = 0; k < 2; ++k) dst[n][k] = *(const LAS bf16x8*)(lds + PG8_SB(b, h) + boff + n * 2048 + k * 1024); } while (0)
; #define PG8_MMA(ai, bj, At, Bt) do { __builtin_amdgcn_s_setprio(1); _Pragma("unroll") for (int m = 0; m < 4; ++m) _Pragma("unroll") for (int n = 0; n < 2; ++n) _Pragma("unroll") for (int k = 0; k < 2; ++k) \
;         acc[ai][bj][m][n] = __builtin_amdgcn_mfma_f32_16x16x32_bf16(Bt[n][k], At[m][k], acc[ai][bj][m][n], 0, 0, 0); __builtin_amdgcn_s_setprio(0); } while (0)
; #define PG8_WAIT_V(n) asm volatile("s_waitcnt vmcnt(" #n ")" ::: "memory")
; #define PG8_WAIT_L(n) asm volatile("s_waitcnt lgkmcnt(" #n ")" ::: "memory")
; #define PG8_BAR __builtin_amdgcn_s_barrier()
; #define PG8_SCHED __builtin_amdgcn_sched_barrier(0)
; template <class Epi, bool SEG = false>
; __device__ __forceinline__ void gemm_phase(LAS unsigned char* lds, const Gemm g, const StaticOrder& S, const Epi& E, const float* stat2 = nullptr) {
;     ...
;         for (int t = tb; t < te; t += 2) {
;             const bool last = (t == nt - 2);
;             const char* a1 = cA + (size_t)(t + 1) * kstep;
;             const char* a2 = last ? nA : cA + (size_t)(t + 2) * kstep; const char* b2 = last ? nB : cB + (size_t)(t + 2) * kstep;
;             const char* a3 = a2 + kstep; const char* b3 = b2 + kstep;
;             PG8_LDB(B0, 0, 0); PG8_LDB(B1, 0, 1); PG8_SCHED; PG8_LDA(At, 0, 0); PG8_STAGE(PG8_SA(1, 1), a1 + hstepA, voffA);
;             PG8_WAIT_V(8); PG8_WAIT_L(0); PG8_BAR; PG8_MMA(0, 0, At, B0); PG8_MMA(0, 1, At, B1); PG8_BAR; PG8_SCHED;
;             PG8_LDA(At, 0, 1); PG8_STAGE(PG8_SB(0, 0), b2, voffB); PG8_STAGE(PG8_SB(0, 1), b2 + hstepB, voffB); PG8_STAGE(PG8_SA(0, 0), a2, voffA);
.LBB0_479:
	ds_read_b128 v[146:149], v153
	ds_read_b128 v[158:161], v153 offset:1024
	ds_read_b128 v[162:165], v153 offset:2048
	ds_read_b128 v[166:169], v153 offset:3072
	ds_read_b128 v[170:173], v154
	ds_read_b128 v[174:177], v154 offset:1024
	ds_read_b128 v[178:181], v154 offset:2048
	ds_read_b128 v[182:185], v154 offset:3072
	s_add_u32 s30, s54, 0xfff80080
	s_addc_u32 s31, s55, -1
	s_cmp_eq_u32 s94, 28
	s_cselect_b32 s59, s5, s31
	s_cselect_b32 s58, s23, s30
	s_cselect_b32 s57, s21, s93
	s_cselect_b32 s56, s91, s92
	v_lshl_add_u64 v[218:219], s[54:55], 0, v[138:139]
	s_add_i32 m0, s63, 0xc000
	ds_read_b128 v[186:189], v155
	ds_read_b128 v[190:193], v155 offset:1024
	ds_read_b128 v[194:197], v155 offset:2048
	ds_read_b128 v[198:201], v155 offset:3072
	ds_read_b128 v[202:205], v155 offset:4096
	ds_read_b128 v[206:209], v155 offset:5120
	ds_read_b128 v[210:213], v155 offset:6144
	ds_read_b128 v[214:217], v155 offset:7168
	global_load_lds_dwordx4 v[218:219], off
	v_lshl_add_u64 v[218:219], s[54:55], 0, v[140:141]
	s_add_i32 m0, s63, 0xe000
	s_nop 0
	global_load_lds_dwordx4 v[218:219], off
	s_cmp_eq_u32 s32, 0
	s_cbranch_scc0 .Lt1_rx0_0
	s_waitcnt vmcnt(8)
.Lt1_j0_0:
	s_waitcnt lgkmcnt(0)
	s_barrier
	s_setprio 1
	s_waitcnt lgkmcnt(0)
	v_mfma_f32_16x16x32_bf16 v[126:129], v[146:149], v[186:189], v[126:129]
	v_mfma_f32_16x16x32_bf16 v[122:125], v[162:165], v[186:189], v[122:125]
	v_mfma_f32_16x16x32_bf16 v[110:113], v[146:149], v[194:197], v[110:113]
	v_mfma_f32_16x16x32_bf16 v[106:109], v[162:165], v[194:197], v[106:109]
	v_mfma_f32_16x16x32_bf16 v[94:97], v[146:149], v[202:205], v[94:97]
	v_mfma_f32_16x16x32_bf16 v[90:93], v[162:165], v[202:205], v[90:93]
	v_mfma_f32_16x16x32_bf16 v[78:81], v[146:149], v[210:213], v[78:81]
	v_mfma_f32_16x16x32_bf16 v[74:77], v[162:165], v[210:213], v[74:77]
	v_mfma_f32_16x16x32_bf16 v[126:129], v[158:161], v[190:193], v[126:129]
	v_mfma_f32_16x16x32_bf16 v[122:125], v[166:169], v[190:193], v[122:125]
	v_mfma_f32_16x16x32_bf16 v[110:113], v[158:161], v[198:201], v[110:113]
	v_mfma_f32_16x16x32_bf16 v[106:109], v[166:169], v[198:201], v[106:109]
	v_mfma_f32_16x16x32_bf16 v[94:97], v[158:161], v[206:209], v[94:97]
	v_mfma_f32_16x16x32_bf16 v[90:93], v[166:169], v[206:209], v[90:93]
	v_mfma_f32_16x16x32_bf16 v[78:81], v[158:161], v[214:217], v[78:81]
	v_mfma_f32_16x16x32_bf16 v[74:77], v[166:169], v[214:217], v[74:77]
	s_setprio 0
	s_setprio 1
	v_mfma_f32_16x16x32_bf16 v[118:121], v[170:173], v[186:189], v[118:121]
	v_mfma_f32_16x16x32_bf16 v[114:117], v[178:181], v[186:189], v[114:117]
	v_mfma_f32_16x16x32_bf16 v[102:105], v[170:173], v[194:197], v[102:105]
	v_mfma_f32_16x16x32_bf16 v[98:101], v[178:181], v[194:197], v[98:101]
	v_mfma_f32_16x16x32_bf16 v[86:89], v[170:173], v[202:205], v[86:89]
	v_mfma_f32_16x16x32_bf16 v[82:85], v[178:181], v[202:205], v[82:85]
	v_mfma_f32_16x16x32_bf16 v[70:73], v[170:173], v[210:213], v[70:73]
	v_mfma_f32_16x16x32_bf16 v[66:69], v[178:181], v[210:213], v[66:69]
	v_mfma_f32_16x16x32_bf16 v[118:121], v[174:177], v[190:193], v[118:121]
	v_mfma_f32_16x16x32_bf16 v[114:117], v[182:185], v[190:193], v[114:117]
	v_mfma_f32_16x16x32_bf16 v[102:105], v[174:177], v[198:201], v[102:105]
	v_mfma_f32_16x16x32_bf16 v[98:101], v[182:185], v[198:201], v[98:101]
	v_mfma_f32_16x16x32_bf16 v[86:89], v[174:177], v[206:209], v[86:89]
	v_mfma_f32_16x16x32_bf16 v[82:85], v[182:185], v[206:209], v[82:85]
	v_mfma_f32_16x16x32_bf16 v[70:73], v[174:177], v[214:217], v[70:73]
	v_mfma_f32_16x16x32_bf16 v[66:69], v[182:185], v[214:217], v[66:69]
	s_setprio 0
	s_barrier
	s_add_i32 s30, s87, s62
	v_lshl_add_u64 v[218:219], s[56:57], 0, v[132:133]
	s_mov_b32 m0, s30
	ds_read_b128 v[186:189], v155 offset:16384
	ds_read_b128 v[190:193], v155 offset:17408
	ds_read_b128 v[194:197], v155 offset:18432
	ds_read_b128 v[198:201], v155 offset:19456
	ds_read_b128 v[202:205], v155 offset:20480
	ds_read_b128 v[206:209], v155 offset:21504
	ds_read_b128 v[210:213], v155 offset:22528
	ds_read_b128 v[214:217], v155 offset:23552
	global_load_lds_dwordx4 v[218:219], off
	s_add_i32 m0, s30, 0x2000
	s_add_u32 s30, s56, 0x80000
	v_lshl_add_u64 v[220:221], s[56:57], 0, v[136:137]
	s_addc_u32 s31, s57, 0
	s_add_i32 s95, s88, s62
	global_load_lds_dwordx4 v[220:221], off
	v_lshl_add_u64 v[222:223], s[30:31], 0, v[132:133]
	s_mov_b32 m0, s95
	v_lshl_add_u64 v[224:225], s[58:59], 0, v[134:135]
	global_load_lds_dwordx4 v[222:223], off
	v_lshl_add_u64 v[222:223], s[30:31], 0, v[136:137]
	s_add_i32 m0, s95, 0x2000
	s_nop 0
	global_load_lds_dwordx4 v[222:223], off
	v_lshl_add_u64 v[222:223], s[58:59], 0, v[130:131]
	s_mov_b32 m0, s63
	s_nop 0
	global_load_lds_dwordx4 v[222:223], off
	s_mov_b32 m0, s64
	s_nop 0
	global_load_lds_dwordx4 v[224:225], off
	s_cmp_eq_u32 s32, 0
	s_cbranch_scc0 .Lt1_rx0_1
	s_waitcnt vmcnt(8)
; #define PG8_STAGE(bufoff, gbase, voff) do { _Pragma("unroll") for (int _i = 0; _i < 2; ++_i) \
;         __builtin_amdgcn_global_load_lds((const unsigned*)((const char*)(gbase) + (voff)[_i]), (LAS unsigned*)(lds + (bufoff) + ldsw + _i * 8192), 16, 0, 0); } while (0)
; #define PG8_LDA(dst, b, h) do { _Pragma("unroll") for (int m = 0; m < 4; ++m) _Pragma("unroll") for (int k = 0; k < 2; ++k) dst[m][k] = *(const LAS bf16x8*)(lds + PG8_SA(b, h) + aoff + m * 2048 + k * 1024); } while (0)
; #define PG8_LDB(dst, b, h) do { _Pragma("unroll") for (int n = 0; n < 2; ++n) _Pragma("unroll") for (int k = 0; k < 2; ++k) dst[n][k] = *(const LAS bf16x8*)(lds + PG8_SB(b, h) + boff + n * 2048 + k * 1024); } while (0)
; #define PG8_MMA(ai, bj, At, Bt) do { __builtin_amdgcn_s_setprio(1); _Pragma("unroll") for (int m = 0; m < 4; ++m) _Pragma("unroll") for (int n = 0; n < 2; ++n) _Pragma("unroll") for (int k = 0; k < 2; ++k) \
;         acc[ai][bj][m][n] = __builtin_amdgcn_mfma_f32_16x16x32_bf16(Bt[n][k], At[m][k], acc[ai][bj][m][n], 0, 0, 0); __builtin_amdgcn_s_setprio(0); } while (0)
; #define PG8_WAIT_V(n) asm volatile("s_waitcnt vmcnt(" #n ")" ::: "memory")
; #define PG8_WAIT_L(n) asm volatile("s_waitcnt lgkmcnt(" #n ")" ::: "memory")
; #define PG8_BAR __builtin_amdgcn_s_barrier()
; #define PG8_SCHED __builtin_amdgcn_sched_barrier(0)
; template <class Epi, bool SEG = false>
; __device__ __forceinline__ void gemm_phase(LAS unsigned char* lds, const Gemm g, const StaticOrder& S, const Epi& E, const float* stat2 = nullptr) {
;     ...
;             PG8_WAIT_V(8); PG8_WAIT_L(0); PG8_BAR; PG8_MMA(1, 0, At, B0); PG8_MMA(1, 1, At, B1); PG8_BAR; PG8_SCHED;
;             PG8_LDB(B0, 1, 0); PG8_LDB(B1, 1, 1); PG8_SCHED; PG8_LDA(At, 1, 0); PG8_STAGE(PG8_SA(0, 1), a2 + hstepA, voffA);
;             PG8_WAIT_V(8); PG8_WAIT_L(0); PG8_BAR; PG8_MMA(0, 0, At, B0); PG8_MMA(0, 1, At, B1); PG8_BAR; PG8_SCHED;
.Lt1_j0_1:
	s_waitcnt lgkmcnt(0)
	s_barrier
	s_setprio 1
	s_waitcnt lgkmcnt(0)
	v_mfma_f32_16x16x32_bf16 v[62:65], v[146:149], v[186:189], v[62:65]
	v_mfma_f32_16x16x32_bf16 v[58:61], v[162:165], v[186:189], v[58:61]
	v_mfma_f32_16x16x32_bf16 v[46:49], v[146:149], v[194:197], v[46:49]
	v_mfma_f32_16x16x32_bf16 v[42:45], v[162:165], v[194:197], v[42:45]
	v_mfma_f32_16x16x32_bf16 v[30:33], v[146:149], v[202:205], v[30:33]
	v_mfma_f32_16x16x32_bf16 v[26:29], v[162:165], v[202:205], v[26:29]
	v_mfma_f32_16x16x32_bf16 v[14:17], v[146:149], v[210:213], v[14:17]
	v_mfma_f32_16x16x32_bf16 v[10:13], v[162:165], v[210:213], v[10:13]
	v_mfma_f32_16x16x32_bf16 v[62:65], v[158:161], v[190:193], v[62:65]
	v_mfma_f32_16x16x32_bf16 v[58:61], v[166:169], v[190:193], v[58:61]
	v_mfma_f32_16x16x32_bf16 v[46:49], v[158:161], v[198:201], v[46:49]
	v_mfma_f32_16x16x32_bf16 v[42:45], v[166:169], v[198:201], v[42:45]
	v_mfma_f32_16x16x32_bf16 v[30:33], v[158:161], v[206:209], v[30:33]
	v_mfma_f32_16x16x32_bf16 v[26:29], v[166:169], v[206:209], v[26:29]
	v_mfma_f32_16x16x32_bf16 v[14:17], v[158:161], v[214:217], v[14:17]
	v_mfma_f32_16x16x32_bf16 v[10:13], v[166:169], v[214:217], v[10:13]
	s_setprio 0
	s_setprio 1
	v_mfma_f32_16x16x32_bf16 v[54:57], v[170:173], v[186:189], v[54:57]
	v_mfma_f32_16x16x32_bf16 v[50:53], v[178:181], v[186:189], v[50:53]
	v_mfma_f32_16x16x32_bf16 v[38:41], v[170:173], v[194:197], v[38:41]
	v_mfma_f32_16x16x32_bf16 v[34:37], v[178:181], v[194:197], v[34:37]
	v_mfma_f32_16x16x32_bf16 v[22:25], v[170:173], v[202:205], v[22:25]
	v_mfma_f32_16x16x32_bf16 v[18:21], v[178:181], v[202:205], v[18:21]
	v_mfma_f32_16x16x32_bf16 v[6:9], v[170:173], v[210:213], v[6:9]
	v_mfma_f32_16x16x32_bf16 v[2:5], v[178:181], v[210:213], v[2:5]
	v_mfma_f32_16x16x32_bf16 v[54:57], v[174:177], v[190:193], v[54:57]
	v_mfma_f32_16x16x32_bf16 v[50:53], v[182:185], v[190:193], v[50:53]
	v_mfma_f32_16x16x32_bf16 v[38:41], v[174:177], v[198:201], v[38:41]
	v_mfma_f32_16x16x32_bf16 v[34:37], v[182:185], v[198:201], v[34:37]
	v_mfma_f32_16x16x32_bf16 v[22:25], v[174:177], v[206:209], v[22:25]
	v_mfma_f32_16x16x32_bf16 v[18:21], v[182:185], v[206:209], v[18:21]
	v_mfma_f32_16x16x32_bf16 v[6:9], v[174:177], v[214:217], v[6:9]
	v_mfma_f32_16x16x32_bf16 v[2:5], v[182:185], v[214:217], v[2:5]
	s_setprio 0
	s_barrier
	s_add_i32 s95, 0, 0x18000
	v_add_u32_e32 v157, s95, v151
	s_add_i32 s96, 0, 0x1c000
	ds_read_b128 v[146:149], v157
	ds_read_b128 v[158:161], v157 offset:1024
	ds_read_b128 v[162:165], v157 offset:2048
	ds_read_b128 v[166:169], v157 offset:3072
	v_add_u32_e32 v157, s96, v151
	ds_read_b128 v[170:173], v157
	ds_read_b128 v[174:177], v157 offset:1024
	ds_read_b128 v[178:181], v157 offset:2048
	ds_read_b128 v[182:185], v157 offset:3072
	s_add_u32 s30, s58, 0x80000
	s_addc_u32 s31, s59, 0
	s_mov_b32 m0, s33
	v_lshl_add_u64 v[226:227], s[30:31], 0, v[130:131]
	ds_read_b128 v[186:189], v155 offset:32768
	ds_read_b128 v[190:193], v155 offset:33792
	ds_read_b128 v[194:197], v155 offset:34816
	ds_read_b128 v[198:201], v155 offset:35840
	ds_read_b128 v[202:205], v155 offset:36864
	ds_read_b128 v[206:209], v155 offset:37888
	ds_read_b128 v[210:213], v155 offset:38912
	ds_read_b128 v[214:217], v155 offset:39936
	global_load_lds_dwordx4 v[226:227], off
	v_lshl_add_u64 v[226:227], s[30:31], 0, v[134:135]
	s_mov_b32 m0, s65
	s_nop 0
	global_load_lds_dwordx4 v[226:227], off
	s_waitcnt vmcnt(8)
	s_waitcnt lgkmcnt(0)
	s_barrier
	s_setprio 1
	s_waitcnt lgkmcnt(0)
	v_mfma_f32_16x16x32_bf16 v[126:129], v[146:149], v[186:189], v[126:129]
	v_mfma_f32_16x16x32_bf16 v[122:125], v[162:165], v[186:189], v[122:125]
	v_mfma_f32_16x16x32_bf16 v[110:113], v[146:149], v[194:197], v[110:113]
	v_mfma_f32_16x16x32_bf16 v[106:109], v[162:165], v[194:197], v[106:109]
	v_mfma_f32_16x16x32_bf16 v[94:97], v[146:149], v[202:205], v[94:97]
	v_mfma_f32_16x16x32_bf16 v[90:93], v[162:165], v[202:205], v[90:93]
	v_mfma_f32_16x16x32_bf16 v[78:81], v[146:149], v[210:213], v[78:81]
	v_mfma_f32_16x16x32_bf16 v[74:77], v[162:165], v[210:213], v[74:77]
	v_mfma_f32_16x16x32_bf16 v[126:129], v[158:161], v[190:193], v[126:129]
	v_mfma_f32_16x16x32_bf16 v[122:125], v[166:169], v[190:193], v[122:125]
	v_mfma_f32_16x16x32_bf16 v[110:113], v[158:161], v[198:201], v[110:113]
	v_mfma_f32_16x16x32_bf16 v[106:109], v[166:169], v[198:201], v[106:109]
	v_mfma_f32_16x16x32_bf16 v[94:97], v[158:161], v[206:209], v[94:97]
	v_mfma_f32_16x16x32_bf16 v[90:93], v[166:169], v[206:209], v[90:93]
	v_mfma_f32_16x16x32_bf16 v[78:81], v[158:161], v[214:217], v[78:81]
	v_mfma_f32_16x16x32_bf16 v[74:77], v[166:169], v[214:217], v[74:77]
	s_setprio 0
	s_setprio 1
	v_mfma_f32_16x16x32_bf16 v[118:121], v[170:173], v[186:189], v[118:121]
	v_mfma_f32_16x16x32_bf16 v[114:117], v[178:181], v[186:189], v[114:117]
	v_mfma_f32_16x16x32_bf16 v[102:105], v[170:173], v[194:197], v[102:105]
	v_mfma_f32_16x16x32_bf16 v[98:101], v[178:181], v[194:197], v[98:101]
	v_mfma_f32_16x16x32_bf16 v[86:89], v[170:173], v[202:205], v[86:89]
	v_mfma_f32_16x16x32_bf16 v[82:85], v[178:181], v[202:205], v[82:85]
	v_mfma_f32_16x16x32_bf16 v[70:73], v[170:173], v[210:213], v[70:73]
	v_mfma_f32_16x16x32_bf16 v[66:69], v[178:181], v[210:213], v[66:69]
	v_mfma_f32_16x16x32_bf16 v[118:121], v[174:177], v[190:193], v[118:121]
	v_mfma_f32_16x16x32_bf16 v[114:117], v[182:185], v[190:193], v[114:117]
	v_mfma_f32_16x16x32_bf16 v[102:105], v[174:177], v[198:201], v[102:105]
	v_mfma_f32_16x16x32_bf16 v[98:101], v[182:185], v[198:201], v[98:101]
	v_mfma_f32_16x16x32_bf16 v[86:89], v[174:177], v[206:209], v[86:89]
	v_mfma_f32_16x16x32_bf16 v[82:85], v[182:185], v[206:209], v[82:85]
	v_mfma_f32_16x16x32_bf16 v[70:73], v[174:177], v[214:217], v[70:73]
	v_mfma_f32_16x16x32_bf16 v[66:69], v[182:185], v[214:217], v[66:69]
	s_setprio 0
	s_barrier
; #define PG8_STAGE(bufoff, gbase, voff) do { _Pragma("unroll") for (int _i = 0; _i < 2; ++_i) \
;         __builtin_amdgcn_global_load_lds((const unsigned*)((const char*)(gbase) + (voff)[_i]), (LAS unsigned*)(lds + (bufoff) + ldsw + _i * 8192), 16, 0, 0); } while (0)
; #define PG8_LDA(dst, b, h) do { _Pragma("unroll") for (int m = 0; m < 4; ++m) _Pragma("unroll") for (int k = 0; k < 2; ++k) dst[m][k] = *(const LAS bf16x8*)(lds + PG8_SA(b, h) + aoff + m * 2048 + k * 1024); } while (0)
; #define PG8_MMA(ai, bj, At, Bt) do { __builtin_amdgcn_s_setprio(1); _Pragma("unroll") for (int m = 0; m < 4; ++m) _Pragma("unroll") for (int n = 0; n < 2; ++n) _Pragma("unroll") for (int k = 0; k < 2; ++k) \
;         acc[ai][bj][m][n] = __builtin_amdgcn_mfma_f32_16x16x32_bf16(Bt[n][k], At[m][k], acc[ai][bj][m][n], 0, 0, 0); __builtin_amdgcn_s_setprio(0); } while (0)
; template <class Epi, bool SEG = false>
; __device__ __forceinline__ void gemm_phase(LAS unsigned char* lds, const Gemm g, const StaticOrder& S, const Epi& E, const float* stat2 = nullptr) {
;     ...
;             PG8_LDA(At, 1, 1); PG8_STAGE(PG8_SB(1, 0), b3, voffB); PG8_STAGE(PG8_SB(1, 1), b3 + hstepB, voffB); PG8_STAGE(PG8_SA(1, 0), a3, voffA);
;             PG8_WAIT_V(8); PG8_WAIT_L(0); PG8_BAR; PG8_MMA(1, 0, At, B0); PG8_MMA(1, 1, At, B1); PG8_BAR; PG8_SCHED;
;         }
;         }
;         if (wr == 0) PG8_BAR;
;     __device__ __forceinline__ void operator()(const Acc& acc, const pg8::Unit& u, int wr, int wc, int fr, int fq) const {
;         const int row0 = u.pm * 256 + wr * 64 + fr, col0 = u.pn * 256 + wc * 32 + 8 * fq;
;         const bool st = (u.pn < stat_pn);
; #pragma unroll
;         for (int ai = 0; ai < 2; ++ai)
; #pragma unroll
;             for (int m = 0; m < 4; ++m) {
;                 const int row = row0 + ai * 128 + m * 16; bf16_t* rowp = O + (size_t)row * ldc + col0; float ss = 0.f;
; #pragma unroll
;                 for (int bj = 0; bj < 2; ++bj) { const f32x4 v0 = acc[ai][bj][m][0], v1 = acc[ai][bj][m][1];
;                     ss += (v0[0] * v0[0] + v0[1] * v0[1]) + (v0[2] * v0[2] + v0[3] * v0[3]) + (v1[0] * v1[0] + v1[1] * v1[1]) + (v1[2] * v1[2] + v1[3] * v1[3]);
;                     *(u32x4*)(rowp + bj * 128) = pack8(v0, v1); }
;                 if (st) { ss += __shfl_xor(ss, 16); ss += __shfl_xor(ss, 32); if (fq == 0) stat[(size_t)row * 16 + u.pn * 4 + wc] = ss; }
	s_add_i32 s30, s95, s62
	v_lshl_add_u64 v[218:219], v[218:219], 0, s[16:17]
	s_mov_b32 m0, s30
	ds_read_b128 v[186:189], v155 offset:49152
	ds_read_b128 v[190:193], v155 offset:50176
	ds_read_b128 v[194:197], v155 offset:51200
	ds_read_b128 v[198:201], v155 offset:52224
	ds_read_b128 v[202:205], v155 offset:53248
	ds_read_b128 v[206:209], v155 offset:54272
	ds_read_b128 v[210:213], v155 offset:55296
	ds_read_b128 v[214:217], v155 offset:56320
	global_load_lds_dwordx4 v[218:219], off
	s_add_i32 m0, s30, 0x2000
	s_add_u32 s30, s56, 0x80080
	v_lshl_add_u64 v[218:219], v[220:221], 0, s[16:17]
	s_addc_u32 s31, s57, 0
	s_add_i32 s56, s96, s62
	global_load_lds_dwordx4 v[218:219], off
	v_lshl_add_u64 v[218:219], s[30:31], 0, v[132:133]
	s_mov_b32 m0, s56
	s_nop 0
	global_load_lds_dwordx4 v[218:219], off
	v_lshl_add_u64 v[218:219], s[30:31], 0, v[136:137]
	s_add_i32 m0, s56, 0x2000
	s_nop 0
	global_load_lds_dwordx4 v[218:219], off
	v_lshl_add_u64 v[218:219], v[222:223], 0, s[16:17]
	s_mov_b32 m0, s83
	s_nop 0
	global_load_lds_dwordx4 v[218:219], off
	v_lshl_add_u64 v[218:219], v[224:225], 0, s[16:17]
	s_mov_b32 m0, s84
	s_nop 0
	global_load_lds_dwordx4 v[218:219], off
	s_waitcnt vmcnt(8)
	s_waitcnt lgkmcnt(0)
	s_barrier
	s_setprio 1
	s_waitcnt lgkmcnt(0)
	v_mfma_f32_16x16x32_bf16 v[62:65], v[146:149], v[186:189], v[62:65]
	v_mfma_f32_16x16x32_bf16 v[58:61], v[162:165], v[186:189], v[58:61]
	v_mfma_f32_16x16x32_bf16 v[46:49], v[146:149], v[194:197], v[46:49]
	v_mfma_f32_16x16x32_bf16 v[42:45], v[162:165], v[194:197], v[42:45]
	v_mfma_f32_16x16x32_bf16 v[30:33], v[146:149], v[202:205], v[30:33]
	v_mfma_f32_16x16x32_bf16 v[26:29], v[162:165], v[202:205], v[26:29]
	v_mfma_f32_16x16x32_bf16 v[14:17], v[146:149], v[210:213], v[14:17]
	v_mfma_f32_16x16x32_bf16 v[10:13], v[162:165], v[210:213], v[10:13]
	v_mfma_f32_16x16x32_bf16 v[62:65], v[158:161], v[190:193], v[62:65]
	v_mfma_f32_16x16x32_bf16 v[58:61], v[166:169], v[190:193], v[58:61]
	v_mfma_f32_16x16x32_bf16 v[46:49], v[158:161], v[198:201], v[46:49]
	v_mfma_f32_16x16x32_bf16 v[42:45], v[166:169], v[198:201], v[42:45]
	v_mfma_f32_16x16x32_bf16 v[30:33], v[158:161], v[206:209], v[30:33]
	v_mfma_f32_16x16x32_bf16 v[26:29], v[166:169], v[206:209], v[26:29]
	v_mfma_f32_16x16x32_bf16 v[14:17], v[158:161], v[214:217], v[14:17]
	v_mfma_f32_16x16x32_bf16 v[10:13], v[166:169], v[214:217], v[10:13]
	s_setprio 0
	s_setprio 1
	v_mfma_f32_16x16x32_bf16 v[54:57], v[170:173], v[186:189], v[54:57]
	v_mfma_f32_16x16x32_bf16 v[50:53], v[178:181], v[186:189], v[50:53]
	v_mfma_f32_16x16x32_bf16 v[38:41], v[170:173], v[194:197], v[38:41]
	v_mfma_f32_16x16x32_bf16 v[34:37], v[178:181], v[194:197], v[34:37]
	v_mfma_f32_16x16x32_bf16 v[22:25], v[170:173], v[202:205], v[22:25]
	v_mfma_f32_16x16x32_bf16 v[18:21], v[178:181], v[202:205], v[18:21]
	v_mfma_f32_16x16x32_bf16 v[6:9], v[170:173], v[210:213], v[6:9]
	v_mfma_f32_16x16x32_bf16 v[2:5], v[178:181], v[210:213], v[2:5]
	v_mfma_f32_16x16x32_bf16 v[54:57], v[174:177], v[190:193], v[54:57]
	v_mfma_f32_16x16x32_bf16 v[50:53], v[182:185], v[190:193], v[50:53]
	v_mfma_f32_16x16x32_bf16 v[38:41], v[174:177], v[198:201], v[38:41]
	v_mfma_f32_16x16x32_bf16 v[34:37], v[182:185], v[198:201], v[34:37]
	v_mfma_f32_16x16x32_bf16 v[22:25], v[174:177], v[206:209], v[22:25]
	v_mfma_f32_16x16x32_bf16 v[18:21], v[182:185], v[206:209], v[18:21]
	v_mfma_f32_16x16x32_bf16 v[6:9], v[174:177], v[214:217], v[6:9]
	v_mfma_f32_16x16x32_bf16 v[2:5], v[182:185], v[214:217], v[2:5]
	s_setprio 0
	s_barrier
	s_add_i32 s94, s94, 2
	s_add_u32 s54, s54, 0x100
	s_addc_u32 s55, s55, 0
	s_add_u32 s92, s92, 0x100
	s_addc_u32 s93, s93, 0
	s_cmp_gt_u32 s94, 29
	s_cbranch_scc0 .LBB0_479
	s_and_b64 vcc, exec, s[18:19]
	s_cbranch_vccz .LBB0_482
	s_barrier
.LBB0_482:
	s_mov_b32 s32, 1
	s_cmp_lt_i32 s4, 4
	s_cselect_b64 s[56:57], -1, 0
	s_lshl_b32 s54, s4, 2
	v_lshl_add_u32 v148, s8, 8, v1
	v_lshl_or_b32 v146, s4, 8, v152
	s_ashr_i32 s55, s54, 31
	v_mov_b64_e32 v[158:159], s[12:13]
	s_cmp_gt_i32 s4, 3
	v_ashrrev_i32_e32 v147, 31, v146
	v_mad_i64_i32 v[158:159], s[4:5], v148, s89, v[158:159]
	v_lshl_add_u64 v[162:163], v[146:147], 1, v[158:159]
	v_cvt_pk_bf16_f32 v158, v126, v127
	v_cvt_pk_bf16_f32 v159, v128, v129
	v_cvt_pk_bf16_f32 v160, v122, v123
	v_cvt_pk_bf16_f32 v161, v124, v125
	v_ashrrev_i32_e32 v149, 31, v148
	global_store_dwordx4 v[162:163], v[158:161], off
	s_nop 1
	v_cvt_pk_bf16_f32 v158, v118, v119
	v_cvt_pk_bf16_f32 v159, v120, v121
	v_cvt_pk_bf16_f32 v160, v114, v115
	v_cvt_pk_bf16_f32 v161, v116, v117
	global_store_dwordx4 v[162:163], v[158:161], off offset:256
	s_cbranch_scc1 .LBB0_486
	v_mul_f32_e32 v117, v117, v117
	v_fmac_f32_e32 v117, v116, v116
	v_mul_f32_e32 v116, v119, v119
	v_mul_f32_e32 v125, v125, v125
	v_fmac_f32_e32 v116, v118, v118
	v_mul_f32_e32 v118, v121, v121
	v_fmac_f32_e32 v125, v124, v124
	v_mul_f32_e32 v124, v127, v127
	v_fmac_f32_e32 v118, v120, v120
	v_mul_f32_e32 v115, v115, v115
	v_fmac_f32_e32 v124, v126, v126
	v_mul_f32_e32 v126, v129, v129
	v_add_f32_e32 v116, v116, v118
	v_fmac_f32_e32 v115, v114, v114
	v_fmac_f32_e32 v126, v128, v128
	v_mul_f32_e32 v123, v123, v123
	v_add_f32_e32 v114, v116, v115
	v_and_b32_e32 v116, 64, v156
	v_add_f32_e32 v124, v124, v126
	v_fmac_f32_e32 v123, v122, v122
	v_xor_b32_e32 v115, 16, v156
	v_add_u32_e32 v116, 64, v116
	v_add_f32_e32 v122, v124, v123
	v_cmp_lt_i32_e32 vcc, v115, v116
	v_add_f32_e32 v122, v125, v122
	v_add_f32_e32 v114, v117, v114
	v_cndmask_b32_e32 v115, v156, v115, vcc
	v_add_f32_e32 v114, v122, v114
	v_lshlrev_b32_e32 v115, 2, v115
	ds_bpermute_b32 v115, v115, v114
	s_waitcnt lgkmcnt(0)
	v_add_f32_e32 v114, v114, v115
	v_xor_b32_e32 v115, 32, v156
	v_cmp_lt_i32_e32 vcc, v115, v116
	s_nop 1
	v_cndmask_b32_e32 v115, v156, v115, vcc
	v_lshlrev_b32_e32 v115, 2, v115
	ds_bpermute_b32 v115, v115, v114
	s_and_saveexec_b64 s[4:5], s[0:1]
	s_cbranch_execz .LBB0_485
	v_lshlrev_b64 v[116:117], 6, v[148:149]
	v_lshl_add_u64 v[116:117], s[14:15], 0, v[116:117]
	v_lshl_add_u64 v[116:117], s[54:55], 2, v[116:117]
	s_lshl_b32 s8, s82, 2
	v_lshl_add_u64 v[116:117], v[116:117], 0, s[8:9]
	s_waitcnt lgkmcnt(0)
	v_add_f32_e32 v114, v114, v115
	global_store_dword v[116:117], v114, off

; #define PG8_STAGE(bufoff, gbase, voff) do { _Pragma("unroll") for (int _i = 0; _i < 2; ++_i) \
;         __builtin_amdgcn_global_load_lds((const unsigned*)((const char*)(gbase) + (voff)[_i]), (LAS unsigned*)(lds + (bufoff) + ldsw + _i * 8192), 16, 0, 0); } while (0)
; #define PG8_LDA(dst, b, h) do { _Pragma("unroll") for (int m = 0; m < 4; ++m) _Pragma("unroll") for (int k = 0; k < 2; ++k) dst[m][k] = *(const LAS bf16x8*)(lds + PG8_SA(b, h) + aoff + m * 2048 + k * 1024); } while (0)
; #define PG8_LDB(dst, b, h) do { _Pragma("unroll") for (int n = 0; n < 2; ++n) _Pragma("unroll") for (int k = 0; k < 2; ++k) dst[n][k] = *(const LAS bf16x8*)(lds + PG8_SB(b, h) + boff + n * 2048 + k * 1024); } while (0)
; #define PG8_MMA(ai, bj, At, Bt) do { __builtin_amdgcn_s_setprio(1); _Pragma("unroll") for (int m = 0; m < 4; ++m) _Pragma("unroll") for (int n = 0; n < 2; ++n) _Pragma("unroll") for (int k = 0; k < 2; ++k) \
;         acc[ai][bj][m][n] = __builtin_amdgcn_mfma_f32_16x16x32_bf16(Bt[n][k], At[m][k], acc[ai][bj][m][n], 0, 0, 0); __builtin_amdgcn_s_setprio(0); } while (0)
; #define PG8_WAIT_V(n) asm volatile("s_waitcnt vmcnt(" #n ")" ::: "memory")
; #define PG8_WAIT_L(n) asm volatile("s_waitcnt lgkmcnt(" #n ")" ::: "memory")
; #define PG8_BAR __builtin_amdgcn_s_barrier()
; #define PG8_SCHED __builtin_amdgcn_sched_barrier(0)
; template <class Epi, bool SEG = false>
; __device__ __forceinline__ void gemm_phase(LAS unsigned char* lds, const Gemm g, const StaticOrder& S, const Epi& E, const float* stat2 = nullptr) {
;     ...
;             const char* a2 = last ? nA : cA + (size_t)(t + 2) * kstep; const char* b2 = last ? nB : cB + (size_t)(t + 2) * kstep;
;             const char* a3 = a2 + kstep; const char* b3 = b2 + kstep;
;             PG8_LDB(B0, 0, 0); PG8_LDB(B1, 0, 1); PG8_SCHED; PG8_LDA(At, 0, 0); PG8_STAGE(PG8_SA(1, 1), a1 + hstepA, voffA);
;             PG8_WAIT_V(8); PG8_WAIT_L(0); PG8_BAR; PG8_MMA(0, 0, At, B0); PG8_MMA(0, 1, At, B1); PG8_BAR; PG8_SCHED;
;             PG8_LDA(At, 0, 1); PG8_STAGE(PG8_SB(0, 0), b2, voffB); PG8_STAGE(PG8_SB(0, 1), b2 + hstepB, voffB); PG8_STAGE(PG8_SA(0, 0), a2, voffA);
.LBB0_665:
	ds_read_b128 v[170:173], v141
	ds_read_b128 v[174:177], v141 offset:1024
	ds_read_b128 v[178:181], v141 offset:2048
	ds_read_b128 v[182:185], v141 offset:3072
	ds_read_b128 v[186:189], v165
	ds_read_b128 v[190:193], v165 offset:1024
	ds_read_b128 v[194:197], v165 offset:2048
	ds_read_b128 v[198:201], v165 offset:3072
	s_add_u32 s24, s2, 0xfff10080
	s_addc_u32 s25, s3, -1
	s_cmp_eq_u32 s83, 4
	s_cselect_b32 s27, s21, s25
	s_cselect_b32 s26, s20, s24
	s_cselect_b32 s25, s5, s43
	s_cselect_b32 s24, s19, s42
	v_lshl_add_u64 v[156:157], s[2:3], 0, v[148:149]
	s_add_i32 m0, s47, 0xc000
	ds_read_b128 v[202:205], v166
	ds_read_b128 v[206:209], v166 offset:1024
	ds_read_b128 v[210:213], v166 offset:2048
	ds_read_b128 v[214:217], v166 offset:3072
	ds_read_b128 v[218:221], v166 offset:4096
	ds_read_b128 v[222:225], v166 offset:5120
	ds_read_b128 v[226:229], v166 offset:6144
	ds_read_b128 v[230:233], v166 offset:7168
	global_load_lds_dwordx4 v[156:157], off
	v_lshl_add_u64 v[156:157], s[2:3], 0, v[150:151]
	s_add_i32 m0, s47, 0xe000
	s_nop 0
	global_load_lds_dwordx4 v[156:157], off
	s_cmp_eq_u32 s32, 0
	s_cbranch_scc0 .Lt1_rx1_0
	s_waitcnt vmcnt(8)
.Lt1_j1_0:
	s_waitcnt lgkmcnt(0)
	s_barrier
	s_setprio 1
	s_waitcnt lgkmcnt(0)
	v_mfma_f32_16x16x32_bf16 v[126:129], v[170:173], v[202:205], v[126:129]
	v_mfma_f32_16x16x32_bf16 v[122:125], v[178:181], v[202:205], v[122:125]
	v_mfma_f32_16x16x32_bf16 v[110:113], v[170:173], v[210:213], v[110:113]
	v_mfma_f32_16x16x32_bf16 v[106:109], v[178:181], v[210:213], v[106:109]
	v_mfma_f32_16x16x32_bf16 v[94:97], v[170:173], v[218:221], v[94:97]
	v_mfma_f32_16x16x32_bf16 v[90:93], v[178:181], v[218:221], v[90:93]
	v_mfma_f32_16x16x32_bf16 v[78:81], v[170:173], v[226:229], v[78:81]
	v_mfma_f32_16x16x32_bf16 v[74:77], v[178:181], v[226:229], v[74:77]
	v_mfma_f32_16x16x32_bf16 v[126:129], v[174:177], v[206:209], v[126:129]
	v_mfma_f32_16x16x32_bf16 v[122:125], v[182:185], v[206:209], v[122:125]
	v_mfma_f32_16x16x32_bf16 v[110:113], v[174:177], v[214:217], v[110:113]
	v_mfma_f32_16x16x32_bf16 v[106:109], v[182:185], v[214:217], v[106:109]
	v_mfma_f32_16x16x32_bf16 v[94:97], v[174:177], v[222:225], v[94:97]
	v_mfma_f32_16x16x32_bf16 v[90:93], v[182:185], v[222:225], v[90:93]
	v_mfma_f32_16x16x32_bf16 v[78:81], v[174:177], v[230:233], v[78:81]
	v_mfma_f32_16x16x32_bf16 v[74:77], v[182:185], v[230:233], v[74:77]
	s_setprio 0
	s_setprio 1
	v_mfma_f32_16x16x32_bf16 v[118:121], v[186:189], v[202:205], v[118:121]
	v_mfma_f32_16x16x32_bf16 v[114:117], v[194:197], v[202:205], v[114:117]
	v_mfma_f32_16x16x32_bf16 v[102:105], v[186:189], v[210:213], v[102:105]
	v_mfma_f32_16x16x32_bf16 v[98:101], v[194:197], v[210:213], v[98:101]
	v_mfma_f32_16x16x32_bf16 v[86:89], v[186:189], v[218:221], v[86:89]
	v_mfma_f32_16x16x32_bf16 v[82:85], v[194:197], v[218:221], v[82:85]
	v_mfma_f32_16x16x32_bf16 v[70:73], v[186:189], v[226:229], v[70:73]
	v_mfma_f32_16x16x32_bf16 v[66:69], v[194:197], v[226:229], v[66:69]
	v_mfma_f32_16x16x32_bf16 v[118:121], v[190:193], v[206:209], v[118:121]
	v_mfma_f32_16x16x32_bf16 v[114:117], v[198:201], v[206:209], v[114:117]
	v_mfma_f32_16x16x32_bf16 v[102:105], v[190:193], v[214:217], v[102:105]
	v_mfma_f32_16x16x32_bf16 v[98:101], v[198:201], v[214:217], v[98:101]
	v_mfma_f32_16x16x32_bf16 v[86:89], v[190:193], v[222:225], v[86:89]
	v_mfma_f32_16x16x32_bf16 v[82:85], v[198:201], v[222:225], v[82:85]
	v_mfma_f32_16x16x32_bf16 v[70:73], v[190:193], v[230:233], v[70:73]
	v_mfma_f32_16x16x32_bf16 v[66:69], v[198:201], v[230:233], v[66:69]
	s_setprio 0
	s_barrier
	s_add_i32 s30, s65, s46
	v_lshl_add_u64 v[156:157], s[24:25], 0, v[132:133]
	s_mov_b32 m0, s30
	ds_read_b128 v[202:205], v166 offset:16384
	ds_read_b128 v[206:209], v166 offset:17408
	ds_read_b128 v[210:213], v166 offset:18432
	ds_read_b128 v[214:217], v166 offset:19456
	ds_read_b128 v[218:221], v166 offset:20480
	ds_read_b128 v[222:225], v166 offset:21504
	ds_read_b128 v[226:229], v166 offset:22528
	ds_read_b128 v[230:233], v166 offset:23552
	global_load_lds_dwordx4 v[156:157], off
	s_add_i32 m0, s30, 0x2000
	s_add_u32 s30, s24, 0x20000
	v_lshl_add_u64 v[234:235], s[24:25], 0, v[136:137]
	s_addc_u32 s31, s25, 0
	s_add_i32 s84, s76, s46
	global_load_lds_dwordx4 v[234:235], off
	v_lshl_add_u64 v[236:237], s[30:31], 0, v[132:133]
	s_mov_b32 m0, s84
	v_lshl_add_u64 v[238:239], s[26:27], 0, v[134:135]
	global_load_lds_dwordx4 v[236:237], off
	v_lshl_add_u64 v[236:237], s[30:31], 0, v[136:137]
	s_add_i32 m0, s84, 0x2000
	s_nop 0
	global_load_lds_dwordx4 v[236:237], off
	v_lshl_add_u64 v[236:237], s[26:27], 0, v[130:131]
	s_mov_b32 m0, s47
	s_nop 0
	global_load_lds_dwordx4 v[236:237], off
	s_mov_b32 m0, s54
	s_nop 0
	global_load_lds_dwordx4 v[238:239], off
	s_cmp_eq_u32 s32, 0
	s_cbranch_scc0 .Lt1_rx1_1
	s_waitcnt vmcnt(8)
; #define PG8_STAGE(bufoff, gbase, voff) do { _Pragma("unroll") for (int _i = 0; _i < 2; ++_i) \
;         __builtin_amdgcn_global_load_lds((const unsigned*)((const char*)(gbase) + (voff)[_i]), (LAS unsigned*)(lds + (bufoff) + ldsw + _i * 8192), 16, 0, 0); } while (0)
; #define PG8_LDA(dst, b, h) do { _Pragma("unroll") for (int m = 0; m < 4; ++m) _Pragma("unroll") for (int k = 0; k < 2; ++k) dst[m][k] = *(const LAS bf16x8*)(lds + PG8_SA(b, h) + aoff + m * 2048 + k * 1024); } while (0)
; #define PG8_LDB(dst, b, h) do { _Pragma("unroll") for (int n = 0; n < 2; ++n) _Pragma("unroll") for (int k = 0; k < 2; ++k) dst[n][k] = *(const LAS bf16x8*)(lds + PG8_SB(b, h) + boff + n * 2048 + k * 1024); } while (0)
; #define PG8_MMA(ai, bj, At, Bt) do { __builtin_amdgcn_s_setprio(1); _Pragma("unroll") for (int m = 0; m < 4; ++m) _Pragma("unroll") for (int n = 0; n < 2; ++n) _Pragma("unroll") for (int k = 0; k < 2; ++k) \
;         acc[ai][bj][m][n] = __builtin_amdgcn_mfma_f32_16x16x32_bf16(Bt[n][k], At[m][k], acc[ai][bj][m][n], 0, 0, 0); __builtin_amdgcn_s_setprio(0); } while (0)
; #define PG8_WAIT_V(n) asm volatile("s_waitcnt vmcnt(" #n ")" ::: "memory")
; #define PG8_WAIT_L(n) asm volatile("s_waitcnt lgkmcnt(" #n ")" ::: "memory")
; #define PG8_BAR __builtin_amdgcn_s_barrier()
; #define PG8_SCHED __builtin_amdgcn_sched_barrier(0)
; template <class Epi, bool SEG = false>
; __device__ __forceinline__ void gemm_phase(LAS unsigned char* lds, const Gemm g, const StaticOrder& S, const Epi& E, const float* stat2 = nullptr) {
;     ...
;             PG8_WAIT_V(8); PG8_WAIT_L(0); PG8_BAR; PG8_MMA(1, 0, At, B0); PG8_MMA(1, 1, At, B1); PG8_BAR; PG8_SCHED;
;             PG8_LDB(B0, 1, 0); PG8_LDB(B1, 1, 1); PG8_SCHED; PG8_LDA(At, 1, 0); PG8_STAGE(PG8_SA(0, 1), a2 + hstepA, voffA);
;             PG8_WAIT_V(8); PG8_WAIT_L(0); PG8_BAR; PG8_MMA(0, 0, At, B0); PG8_MMA(0, 1, At, B1); PG8_BAR; PG8_SCHED;
.Lt1_j1_1:
	s_waitcnt lgkmcnt(0)
	s_barrier
	s_setprio 1
	s_waitcnt lgkmcnt(0)
	v_mfma_f32_16x16x32_bf16 v[62:65], v[170:173], v[202:205], v[62:65]
	v_mfma_f32_16x16x32_bf16 v[58:61], v[178:181], v[202:205], v[58:61]
	v_mfma_f32_16x16x32_bf16 v[46:49], v[170:173], v[210:213], v[46:49]
	v_mfma_f32_16x16x32_bf16 v[42:45], v[178:181], v[210:213], v[42:45]
	v_mfma_f32_16x16x32_bf16 v[30:33], v[170:173], v[218:221], v[30:33]
	v_mfma_f32_16x16x32_bf16 v[26:29], v[178:181], v[218:221], v[26:29]
	v_mfma_f32_16x16x32_bf16 v[14:17], v[170:173], v[226:229], v[14:17]
	v_mfma_f32_16x16x32_bf16 v[10:13], v[178:181], v[226:229], v[10:13]
	v_mfma_f32_16x16x32_bf16 v[62:65], v[174:177], v[206:209], v[62:65]
	v_mfma_f32_16x16x32_bf16 v[58:61], v[182:185], v[206:209], v[58:61]
	v_mfma_f32_16x16x32_bf16 v[46:49], v[174:177], v[214:217], v[46:49]
	v_mfma_f32_16x16x32_bf16 v[42:45], v[182:185], v[214:217], v[42:45]
	v_mfma_f32_16x16x32_bf16 v[30:33], v[174:177], v[222:225], v[30:33]
	v_mfma_f32_16x16x32_bf16 v[26:29], v[182:185], v[222:225], v[26:29]
	v_mfma_f32_16x16x32_bf16 v[14:17], v[174:177], v[230:233], v[14:17]
	v_mfma_f32_16x16x32_bf16 v[10:13], v[182:185], v[230:233], v[10:13]
	s_setprio 0
	s_setprio 1
	v_mfma_f32_16x16x32_bf16 v[54:57], v[186:189], v[202:205], v[54:57]
	v_mfma_f32_16x16x32_bf16 v[50:53], v[194:197], v[202:205], v[50:53]
	v_mfma_f32_16x16x32_bf16 v[38:41], v[186:189], v[210:213], v[38:41]
	v_mfma_f32_16x16x32_bf16 v[34:37], v[194:197], v[210:213], v[34:37]
	v_mfma_f32_16x16x32_bf16 v[22:25], v[186:189], v[218:221], v[22:25]
	v_mfma_f32_16x16x32_bf16 v[18:21], v[194:197], v[218:221], v[18:21]
	v_mfma_f32_16x16x32_bf16 v[6:9], v[186:189], v[226:229], v[6:9]
	v_mfma_f32_16x16x32_bf16 v[2:5], v[194:197], v[226:229], v[2:5]
	v_mfma_f32_16x16x32_bf16 v[54:57], v[190:193], v[206:209], v[54:57]
	v_mfma_f32_16x16x32_bf16 v[50:53], v[198:201], v[206:209], v[50:53]
	v_mfma_f32_16x16x32_bf16 v[38:41], v[190:193], v[214:217], v[38:41]
	v_mfma_f32_16x16x32_bf16 v[34:37], v[198:201], v[214:217], v[34:37]
	v_mfma_f32_16x16x32_bf16 v[22:25], v[190:193], v[222:225], v[22:25]
	v_mfma_f32_16x16x32_bf16 v[18:21], v[198:201], v[222:225], v[18:21]
	v_mfma_f32_16x16x32_bf16 v[6:9], v[190:193], v[230:233], v[6:9]
	v_mfma_f32_16x16x32_bf16 v[2:5], v[198:201], v[230:233], v[2:5]
	s_setprio 0
	s_barrier
	s_add_i32 s30, 0, 0x18000
	v_add_u32_e32 v158, s30, v139
	s_add_i32 s31, 0, 0x1c000
	ds_read_b128 v[170:173], v158
	ds_read_b128 v[174:177], v158 offset:1024
	ds_read_b128 v[178:181], v158 offset:2048
	ds_read_b128 v[182:185], v158 offset:3072
	v_add_u32_e32 v158, s31, v139
	ds_read_b128 v[186:189], v158
	ds_read_b128 v[190:193], v158 offset:1024
	ds_read_b128 v[194:197], v158 offset:2048
	ds_read_b128 v[198:201], v158 offset:3072
	s_add_u32 s26, s26, 0xf0000
	s_addc_u32 s27, s27, 0
	s_mov_b32 m0, s55
	v_lshl_add_u64 v[240:241], s[26:27], 0, v[130:131]
	ds_read_b128 v[202:205], v166 offset:32768
	ds_read_b128 v[206:209], v166 offset:33792
	ds_read_b128 v[210:213], v166 offset:34816
	ds_read_b128 v[214:217], v166 offset:35840
	ds_read_b128 v[218:221], v166 offset:36864
	ds_read_b128 v[222:225], v166 offset:37888
	ds_read_b128 v[226:229], v166 offset:38912
	ds_read_b128 v[230:233], v166 offset:39936
	global_load_lds_dwordx4 v[240:241], off
	v_lshl_add_u64 v[240:241], s[26:27], 0, v[134:135]
	s_mov_b32 m0, s56
	s_nop 0
	global_load_lds_dwordx4 v[240:241], off
	s_waitcnt vmcnt(8)
	s_waitcnt lgkmcnt(0)
	s_barrier
	s_setprio 1
	s_waitcnt lgkmcnt(0)
	v_mfma_f32_16x16x32_bf16 v[126:129], v[170:173], v[202:205], v[126:129]
	v_mfma_f32_16x16x32_bf16 v[122:125], v[178:181], v[202:205], v[122:125]
	v_mfma_f32_16x16x32_bf16 v[110:113], v[170:173], v[210:213], v[110:113]
	v_mfma_f32_16x16x32_bf16 v[106:109], v[178:181], v[210:213], v[106:109]
	v_mfma_f32_16x16x32_bf16 v[94:97], v[170:173], v[218:221], v[94:97]
	v_mfma_f32_16x16x32_bf16 v[90:93], v[178:181], v[218:221], v[90:93]
	v_mfma_f32_16x16x32_bf16 v[78:81], v[170:173], v[226:229], v[78:81]
	v_mfma_f32_16x16x32_bf16 v[74:77], v[178:181], v[226:229], v[74:77]
	v_mfma_f32_16x16x32_bf16 v[126:129], v[174:177], v[206:209], v[126:129]
	v_mfma_f32_16x16x32_bf16 v[122:125], v[182:185], v[206:209], v[122:125]
	v_mfma_f32_16x16x32_bf16 v[110:113], v[174:177], v[214:217], v[110:113]
	v_mfma_f32_16x16x32_bf16 v[106:109], v[182:185], v[214:217], v[106:109]
	v_mfma_f32_16x16x32_bf16 v[94:97], v[174:177], v[222:225], v[94:97]
	v_mfma_f32_16x16x32_bf16 v[90:93], v[182:185], v[222:225], v[90:93]
	v_mfma_f32_16x16x32_bf16 v[78:81], v[174:177], v[230:233], v[78:81]
	v_mfma_f32_16x16x32_bf16 v[74:77], v[182:185], v[230:233], v[74:77]
	s_setprio 0
	s_setprio 1
	v_mfma_f32_16x16x32_bf16 v[118:121], v[186:189], v[202:205], v[118:121]
	v_mfma_f32_16x16x32_bf16 v[114:117], v[194:197], v[202:205], v[114:117]
	v_mfma_f32_16x16x32_bf16 v[102:105], v[186:189], v[210:213], v[102:105]
	v_mfma_f32_16x16x32_bf16 v[98:101], v[194:197], v[210:213], v[98:101]
	v_mfma_f32_16x16x32_bf16 v[86:89], v[186:189], v[218:221], v[86:89]
	v_mfma_f32_16x16x32_bf16 v[82:85], v[194:197], v[218:221], v[82:85]
	v_mfma_f32_16x16x32_bf16 v[70:73], v[186:189], v[226:229], v[70:73]
	v_mfma_f32_16x16x32_bf16 v[66:69], v[194:197], v[226:229], v[66:69]
	v_mfma_f32_16x16x32_bf16 v[118:121], v[190:193], v[206:209], v[118:121]
	v_mfma_f32_16x16x32_bf16 v[114:117], v[198:201], v[206:209], v[114:117]
	v_mfma_f32_16x16x32_bf16 v[102:105], v[190:193], v[214:217], v[102:105]
	v_mfma_f32_16x16x32_bf16 v[98:101], v[198:201], v[214:217], v[98:101]
	v_mfma_f32_16x16x32_bf16 v[86:89], v[190:193], v[222:225], v[86:89]
	v_mfma_f32_16x16x32_bf16 v[82:85], v[198:201], v[222:225], v[82:85]
	v_mfma_f32_16x16x32_bf16 v[70:73], v[190:193], v[230:233], v[70:73]
	v_mfma_f32_16x16x32_bf16 v[66:69], v[198:201], v[230:233], v[66:69]
	s_setprio 0
	s_barrier
; #define PG8_STAGE(bufoff, gbase, voff) do { _Pragma("unroll") for (int _i = 0; _i < 2; ++_i) \
;         __builtin_amdgcn_global_load_lds((const unsigned*)((const char*)(gbase) + (voff)[_i]), (LAS unsigned*)(lds + (bufoff) + ldsw + _i * 8192), 16, 0, 0); } while (0)
; #define PG8_LDA(dst, b, h) do { _Pragma("unroll") for (int m = 0; m < 4; ++m) _Pragma("unroll") for (int k = 0; k < 2; ++k) dst[m][k] = *(const LAS bf16x8*)(lds + PG8_SA(b, h) + aoff + m * 2048 + k * 1024); } while (0)
; #define PG8_MMA(ai, bj, At, Bt) do { __builtin_amdgcn_s_setprio(1); _Pragma("unroll") for (int m = 0; m < 4; ++m) _Pragma("unroll") for (int n = 0; n < 2; ++n) _Pragma("unroll") for (int k = 0; k < 2; ++k) \
;         acc[ai][bj][m][n] = __builtin_amdgcn_mfma_f32_16x16x32_bf16(Bt[n][k], At[m][k], acc[ai][bj][m][n], 0, 0, 0); __builtin_amdgcn_s_setprio(0); } while (0)
; #define PG8_WAIT_V(n) asm volatile("s_waitcnt vmcnt(" #n ")" ::: "memory")
; #define PG8_WAIT_L(n) asm volatile("s_waitcnt lgkmcnt(" #n ")" ::: "memory")
; #define PG8_BAR __builtin_amdgcn_s_barrier()
; #define PG8_SCHED __builtin_amdgcn_sched_barrier(0)
; template <class Epi, bool SEG = false>
; __device__ __forceinline__ void gemm_phase(LAS unsigned char* lds, const Gemm g, const StaticOrder& S, const Epi& E, const float* stat2 = nullptr) {
;     ...
;             PG8_LDA(At, 1, 1); PG8_STAGE(PG8_SB(1, 0), b3, voffB); PG8_STAGE(PG8_SB(1, 1), b3 + hstepB, voffB); PG8_STAGE(PG8_SA(1, 0), a3, voffA);
;             PG8_WAIT_V(8); PG8_WAIT_L(0); PG8_BAR; PG8_MMA(1, 0, At, B0); PG8_MMA(1, 1, At, B1); PG8_BAR; PG8_SCHED;
;         }
;         }
;         if (wr == 0) PG8_BAR;
	s_add_i32 s26, s30, s46
	v_lshl_add_u64 v[156:157], v[156:157], 0, s[14:15]
	s_mov_b32 m0, s26
	ds_read_b128 v[202:205], v166 offset:49152
	ds_read_b128 v[206:209], v166 offset:50176
	ds_read_b128 v[210:213], v166 offset:51200
	ds_read_b128 v[214:217], v166 offset:52224
	ds_read_b128 v[218:221], v166 offset:53248
	ds_read_b128 v[222:225], v166 offset:54272
	ds_read_b128 v[226:229], v166 offset:55296
	ds_read_b128 v[230:233], v166 offset:56320
	global_load_lds_dwordx4 v[156:157], off
	s_add_i32 m0, s26, 0x2000
	s_add_u32 s24, s24, 0x20080
	v_lshl_add_u64 v[156:157], v[234:235], 0, s[14:15]
	s_addc_u32 s25, s25, 0
	s_add_i32 s26, s31, s46
	global_load_lds_dwordx4 v[156:157], off
	v_lshl_add_u64 v[156:157], s[24:25], 0, v[132:133]
	s_mov_b32 m0, s26
	s_nop 0
	global_load_lds_dwordx4 v[156:157], off
	v_lshl_add_u64 v[156:157], s[24:25], 0, v[136:137]
	s_add_i32 m0, s26, 0x2000
	s_nop 0
	global_load_lds_dwordx4 v[156:157], off
	v_lshl_add_u64 v[156:157], v[236:237], 0, s[14:15]
	s_mov_b32 m0, s59
	s_nop 0
	global_load_lds_dwordx4 v[156:157], off
	v_lshl_add_u64 v[156:157], v[238:239], 0, s[14:15]
	s_mov_b32 m0, s60
	s_nop 0
	global_load_lds_dwordx4 v[156:157], off
	s_waitcnt vmcnt(8)
	s_waitcnt lgkmcnt(0)
	s_barrier
	s_setprio 1
	s_waitcnt lgkmcnt(0)
	v_mfma_f32_16x16x32_bf16 v[62:65], v[170:173], v[202:205], v[62:65]
	v_mfma_f32_16x16x32_bf16 v[58:61], v[178:181], v[202:205], v[58:61]
	v_mfma_f32_16x16x32_bf16 v[46:49], v[170:173], v[210:213], v[46:49]
	v_mfma_f32_16x16x32_bf16 v[42:45], v[178:181], v[210:213], v[42:45]
	v_mfma_f32_16x16x32_bf16 v[30:33], v[170:173], v[218:221], v[30:33]
	v_mfma_f32_16x16x32_bf16 v[26:29], v[178:181], v[218:221], v[26:29]
	v_mfma_f32_16x16x32_bf16 v[14:17], v[170:173], v[226:229], v[14:17]
	v_mfma_f32_16x16x32_bf16 v[10:13], v[178:181], v[226:229], v[10:13]
	v_mfma_f32_16x16x32_bf16 v[62:65], v[174:177], v[206:209], v[62:65]
	v_mfma_f32_16x16x32_bf16 v[58:61], v[182:185], v[206:209], v[58:61]
	v_mfma_f32_16x16x32_bf16 v[46:49], v[174:177], v[214:217], v[46:49]
	v_mfma_f32_16x16x32_bf16 v[42:45], v[182:185], v[214:217], v[42:45]
	v_mfma_f32_16x16x32_bf16 v[30:33], v[174:177], v[222:225], v[30:33]
	v_mfma_f32_16x16x32_bf16 v[26:29], v[182:185], v[222:225], v[26:29]
	v_mfma_f32_16x16x32_bf16 v[14:17], v[174:177], v[230:233], v[14:17]
	v_mfma_f32_16x16x32_bf16 v[10:13], v[182:185], v[230:233], v[10:13]
	s_setprio 0
	s_setprio 1
	v_mfma_f32_16x16x32_bf16 v[54:57], v[186:189], v[202:205], v[54:57]
	v_mfma_f32_16x16x32_bf16 v[50:53], v[194:197], v[202:205], v[50:53]
	v_mfma_f32_16x16x32_bf16 v[38:41], v[186:189], v[210:213], v[38:41]
	v_mfma_f32_16x16x32_bf16 v[34:37], v[194:197], v[210:213], v[34:37]
	v_mfma_f32_16x16x32_bf16 v[22:25], v[186:189], v[218:221], v[22:25]
	v_mfma_f32_16x16x32_bf16 v[18:21], v[194:197], v[218:221], v[18:21]
	v_mfma_f32_16x16x32_bf16 v[6:9], v[186:189], v[226:229], v[6:9]
	v_mfma_f32_16x16x32_bf16 v[2:5], v[194:197], v[226:229], v[2:5]
	v_mfma_f32_16x16x32_bf16 v[54:57], v[190:193], v[206:209], v[54:57]
	v_mfma_f32_16x16x32_bf16 v[50:53], v[198:201], v[206:209], v[50:53]
	v_mfma_f32_16x16x32_bf16 v[38:41], v[190:193], v[214:217], v[38:41]
	v_mfma_f32_16x16x32_bf16 v[34:37], v[198:201], v[214:217], v[34:37]
	v_mfma_f32_16x16x32_bf16 v[22:25], v[190:193], v[222:225], v[22:25]
	v_mfma_f32_16x16x32_bf16 v[18:21], v[198:201], v[222:225], v[18:21]
	v_mfma_f32_16x16x32_bf16 v[6:9], v[190:193], v[230:233], v[6:9]
	v_mfma_f32_16x16x32_bf16 v[2:5], v[198:201], v[230:233], v[2:5]
	s_setprio 0
	s_barrier
	s_add_i32 s83, s83, 2
	s_add_u32 s2, s2, 0x100
	s_addc_u32 s3, s3, 0
	s_add_u32 s42, s42, 0x100
	s_addc_u32 s43, s43, 0
	s_cmp_gt_u32 s83, 5
	s_cbranch_scc0 .LBB0_665
	s_and_b64 vcc, exec, s[16:17]
	s_cbranch_vccz .LBB0_668
	s_barrier
;     __device__ __forceinline__ void operator()(const Acc& acc, const pg8::Unit& u, int wr, int wc, int fr, int fq) const {
;         const int row0 = u.pm * 256 + wr * 64 + fr;
; #pragma unroll
;         for (int ai = 0; ai < 2; ++ai)
; #pragma unroll
;             for (int m = 0; m < 4; ++m) {
;                 const int row = row0 + ai * 128 + m * 16, b = row >> 12, s = row & 4095;
;                 const f32x4 s0 = *(const f32x4*)(stat + (size_t)row * 16), s1 = *(const f32x4*)(stat + (size_t)row * 16 + 4);
;                 const float rs = rsqrtf(((s0[0] + s0[1]) + (s0[2] + s0[3]) + (s1[0] + s1[1]) + (s1[2] + s1[3])) * (1.0f / 512.0f) + EPS);
;                 if (u.pn < 4) {
; #pragma unroll
;                     for (int bj = 0; bj < 2; ++bj) { const int h = 2 * u.pn + bj;
;                         bf16_t* dst = Q + ((size_t)(b * 8 + h) * 4096 + s) * 192 + wc * 32 + 8 * fq;
;                         *(u32x4*)dst = pack8(acc[ai][bj][m][0] * rs, acc[ai][bj][m][1] * rs); }
;                 } else {
;                     const int h = 4 * (u.pn - 4) + wc;
;                     const f32x2* cp = cs + (size_t)row * 32 + 8 * fq;
;                     f32x4 o1[2], o2[2];
; #pragma unroll
;                     for (int n = 0; n < 2; ++n)
; #pragma unroll
;                         for (int i = 0; i < 4; ++i) { const f32x2 c = cp[4 * n + i]; const float x1 = acc[ai][0][m][n][i], x2 = acc[ai][1][m][n][i];
;                             o1[n][i] = (x1 * c.x - x2 * c.y) * rs; o2[n][i] = (x2 * c.x + x1 * c.y) * rs; }
;                     bf16_t* dst = Q + ((size_t)(b * 8 + h) * 4096 + s) * 192 + 128 + 8 * fq;
;                     *(u32x4*)dst = pack8(o1[0], o1[1]); *(u32x4*)(dst + 32) = pack8(o2[0], o2[1]);
.LBB0_668:
	s_mov_b32 s32, 1
	s_lshl_b32 s2, s33, 8
	s_add_i32 s2, s2, s58
	v_or_b32_e32 v156, s2, v159
	v_ashrrev_i32_e32 v157, 31, v156
	v_lshlrev_b64 v[170:171], 6, v[156:157]
	v_lshl_add_u64 v[170:171], s[10:11], 0, v[170:171]
	global_load_dwordx4 v[172:175], v[170:171], off
	global_load_dwordx4 v[176:179], v[170:171], off offset:16
	global_load_dwordx4 v[206:209], v[170:171], off offset:1024
	global_load_dwordx4 v[210:213], v[170:171], off offset:1040
	global_load_dwordx4 v[214:217], v[170:171], off offset:2048
	global_load_dwordx4 v[218:221], v[170:171], off offset:2064
	global_load_dwordx4 v[222:225], v[170:171], off offset:3072
	global_load_dwordx4 v[226:229], v[170:171], off offset:3088
	v_add_co_u32_e32 v250, vcc, 0x2000, v170
	s_nop 1
	v_addc_co_u32_e32 v251, vcc, 0, v171, vcc
	global_load_dwordx4 v[230:233], v[250:251], off
	global_load_dwordx4 v[234:237], v[250:251], off offset:16
	global_load_dwordx4 v[238:241], v[250:251], off offset:1024
	global_load_dwordx4 v[242:245], v[250:251], off offset:1040
	s_cmp_gt_i32 s4, 3
	v_bitop3_b32 v170, s2, v168, v159 bitop3:0xc8
	s_cselect_b64 s[42:43], -1, 0
	s_ashr_i32 s2, s2, 9
	s_and_b32 s5, s2, -8
	s_lshl_b32 s19, s4, 2
	s_add_i32 s19, s19, s61
	s_add_i32 s24, s5, s19
	s_ashr_i32 s25, s24, 31
	s_mov_b64 s[26:27], -1
	s_and_b64 vcc, exec, s[42:43]
	s_lshl_b64 s[24:25], s[24:25], 12
	s_waitcnt vmcnt(0)
	v_mov_b32_e32 v180, v173
	v_mov_b32_e32 v181, v174
	v_mov_b32_e32 v173, v175
	v_mov_b32_e32 v174, v178
	v_mov_b32_e32 v175, v176
	v_mov_b32_e32 v176, v179
	v_pk_add_f32 v[172:173], v[180:181], v[172:173]
	v_pk_add_f32 v[174:175], v[174:175], v[176:177]
	v_add_f32_e32 v158, v172, v173
	v_add_f32_e32 v158, v158, v175
	v_add_f32_e32 v158, v174, v158
	v_fmamk_f32 v158, v158, 0x3b000000, v167
	v_mul_f32_e32 v171, 0x4b800000, v158
	v_cmp_gt_f32_e64 s[2:3], s77, v158
	s_nop 1
	v_cndmask_b32_e64 v158, v158, v171, s[2:3]
	v_rsq_f32_e32 v158, v158
	s_nop 0
	v_mul_f32_e32 v171, 0x45800000, v158
	v_cndmask_b32_e64 v158, v158, v171, s[2:3]
	s_cbranch_vccz .LBB0_670
	v_lshlrev_b64 v[172:173], 8, v[156:157]
	v_lshl_add_u64 v[184:185], v[142:143], 0, v[172:173]
	global_load_dwordx4 v[172:175], v[184:185], off
	global_load_dwordx4 v[176:179], v[184:185], off offset:16
	global_load_dwordx4 v[180:183], v[184:185], off offset:32
	s_nop 0
	global_load_dwordx4 v[184:187], v[184:185], off offset:48
	v_or_b32_e32 v157, s24, v170
	v_mad_u64_u32 v[188:189], s[2:3], v157, s78, v[146:147]
	v_mad_i32_i24 v189, s25, v169, v189
	s_mov_b64 s[26:27], 0
	s_waitcnt vmcnt(3)
	v_mov_b32_e32 v190, v172
	v_mov_b32_e32 v191, v174
	v_mov_b32_e32 v174, v173
	s_waitcnt vmcnt(2)
	v_mov_b32_e32 v173, v178
	v_mov_b32_e32 v178, v177
	s_waitcnt vmcnt(1)
	v_mov_b32_e32 v177, v182
	v_mov_b32_e32 v182, v181
	s_waitcnt vmcnt(0)
	v_mov_b32_e32 v181, v186
	v_mov_b32_e32 v186, v185
	v_mov_b32_e32 v172, v176
	v_mov_b32_e32 v176, v180
	v_mov_b32_e32 v180, v184
	v_pk_mul_f32 v[184:185], v[118:119], v[174:175]
	v_pk_mul_f32 v[192:193], v[118:119], v[190:191]
	v_pk_mul_f32 v[194:195], v[120:121], v[178:179]
	v_pk_mul_f32 v[198:199], v[114:115], v[182:183]
	v_pk_mul_f32 v[202:203], v[116:117], v[186:187]
	v_pk_mul_f32 v[196:197], v[120:121], v[172:173]
	v_pk_mul_f32 v[200:201], v[114:115], v[176:177]
	v_pk_mul_f32 v[204:205], v[116:117], v[180:181]
	v_pk_fma_f32 v[184:185], v[126:127], v[190:191], v[184:185] neg_lo:[0,0,1] neg_hi:[0,0,1]
	v_pk_fma_f32 v[174:175], v[126:127], v[174:175], v[192:193]
	v_pk_fma_f32 v[172:173], v[128:129], v[172:173], v[194:195] neg_lo:[0,0,1] neg_hi:[0,0,1]
	v_pk_fma_f32 v[176:177], v[122:123], v[176:177], v[198:199] neg_lo:[0,0,1] neg_hi:[0,0,1]
	v_pk_fma_f32 v[180:181], v[124:125], v[180:181], v[202:203] neg_lo:[0,0,1] neg_hi:[0,0,1]
	v_pk_fma_f32 v[178:179], v[128:129], v[178:179], v[196:197]
	v_pk_fma_f32 v[182:183], v[122:123], v[182:183], v[200:201]
	v_pk_fma_f32 v[186:187], v[124:125], v[186:187], v[204:205]
	v_pk_mul_f32 v[184:185], v[158:159], v[184:185] op_sel_hi:[0,1]
	v_pk_mul_f32 v[190:191], v[158:159], v[174:175] op_sel_hi:[0,1]
	v_pk_mul_f32 v[174:175], v[158:159], v[172:173] op_sel_hi:[0,1]
	v_pk_mul_f32 v[176:177], v[158:159], v[176:177] op_sel_hi:[0,1]
	v_pk_mul_f32 v[180:181], v[158:159], v[180:181] op_sel_hi:[0,1]
	v_pk_mul_f32 v[178:179], v[158:159], v[178:179] op_sel_hi:[0,1]
	v_pk_mul_f32 v[182:183], v[158:159], v[182:183] op_sel_hi:[0,1]
	v_pk_mul_f32 v[186:187], v[158:159], v[186:187] op_sel_hi:[0,1]
	v_cvt_pk_bf16_f32 v172, v184, v185
	v_cvt_pk_bf16_f32 v173, v174, v175
	v_cvt_pk_bf16_f32 v174, v176, v177
	v_cvt_pk_bf16_f32 v175, v180, v181
	v_cvt_pk_bf16_f32 v176, v190, v191
	v_cvt_pk_bf16_f32 v177, v178, v179
	v_cvt_pk_bf16_f32 v178, v182, v183
	v_cvt_pk_bf16_f32 v179, v186, v187
	global_store_dwordx4 v[188:189], v[172:175], off offset:256
	global_store_dwordx4 v[188:189], v[176:179], off offset:320

;     __device__ __forceinline__ void operator()(const Acc& acc, const pg8::Unit& u, int wr, int wc, int fr, int fq) const {
;     ...
;                 const int row = row0 + ai * 128 + m * 16, b = row >> 12, s = row & 4095;
;                 const f32x4 s0 = *(const f32x4*)(stat + (size_t)row * 16), s1 = *(const f32x4*)(stat + (size_t)row * 16 + 4);
;                 const float rs = rsqrtf(((s0[0] + s0[1]) + (s0[2] + s0[3]) + (s1[0] + s1[1]) + (s1[2] + s1[3])) * (1.0f / 512.0f) + EPS);
;                 if (u.pn < 4) {
; #pragma unroll
;                     for (int bj = 0; bj < 2; ++bj) { const int h = 2 * u.pn + bj;
;                         bf16_t* dst = Q + ((size_t)(b * 8 + h) * 4096 + s) * 192 + wc * 32 + 8 * fq;
;                         *(u32x4*)dst = pack8(acc[ai][bj][m][0] * rs, acc[ai][bj][m][1] * rs); }
;                 } else {
;                     const int h = 4 * (u.pn - 4) + wc;
;                     const f32x2* cp = cs + (size_t)row * 32 + 8 * fq;
;                     f32x4 o1[2], o2[2];
; #pragma unroll
;                     for (int n = 0; n < 2; ++n)
; #pragma unroll
;                         for (int i = 0; i < 4; ++i) { const f32x2 c = cp[4 * n + i]; const float x1 = acc[ai][0][m][n][i], x2 = acc[ai][1][m][n][i];
;                             o1[n][i] = (x1 * c.x - x2 * c.y) * rs; o2[n][i] = (x2 * c.x + x1 * c.y) * rs; }
;                     bf16_t* dst = Q + ((size_t)(b * 8 + h) * 4096 + s) * 192 + 128 + 8 * fq;
;                     *(u32x4*)dst = pack8(o1[0], o1[1]); *(u32x4*)(dst + 32) = pack8(o2[0], o2[1]);
.LBB0_672:
	s_nop 1
	v_or_b32_e32 v116, 16, v156
	v_ashrrev_i32_e32 v117, 31, v116
	v_lshlrev_b64 v[114:115], 6, v[116:117]
	v_lshl_add_u64 v[114:115], s[10:11], 0, v[114:115]
	v_bitop3_b32 v115, v156, s79, 16 bitop3:0xc8
	s_andn2_b64 vcc, exec, s[42:43]
	v_mov_b32_e32 v118, v206
	v_mov_b32_e32 v119, v207
	v_mov_b32_e32 v120, v208
	v_mov_b32_e32 v121, v209
	v_mov_b32_e32 v126, v119
	v_mov_b32_e32 v127, v120
	v_mov_b32_e32 v119, v121
	v_mov_b32_e32 v122, v210
	v_mov_b32_e32 v123, v211
	v_mov_b32_e32 v124, v212
	v_mov_b32_e32 v125, v213
	v_mov_b32_e32 v120, v124
	v_mov_b32_e32 v121, v122
	v_mov_b32_e32 v122, v125
	v_pk_add_f32 v[118:119], v[126:127], v[118:119]
	v_pk_add_f32 v[120:121], v[120:121], v[122:123]
	v_add_f32_e32 v114, v118, v119
	v_add_f32_e32 v114, v114, v121
	v_add_f32_e32 v114, v120, v114
	v_fmamk_f32 v114, v114, 0x3b000000, v167
	v_mul_f32_e32 v118, 0x4b800000, v114
	v_cmp_gt_f32_e64 s[4:5], s77, v114
	s_nop 1
	v_cndmask_b32_e64 v114, v114, v118, s[4:5]
	v_rsq_f32_e32 v114, v114
	v_cndmask_b32_e64 v118, 0, 1, s[42:43]
	v_cmp_ne_u32_e64 s[2:3], 1, v118
	v_mul_f32_e32 v118, 0x45800000, v114
	v_cndmask_b32_e64 v114, v114, v118, s[4:5]
	s_mov_b64 s[4:5], -1
	s_cbranch_vccnz .LBB0_674
	v_lshlrev_b64 v[116:117], 8, v[116:117]
	v_lshl_add_u64 v[128:129], v[142:143], 0, v[116:117]
	global_load_dwordx4 v[116:119], v[128:129], off
	global_load_dwordx4 v[120:123], v[128:129], off offset:16
	global_load_dwordx4 v[124:127], v[128:129], off offset:32
	global_load_dwordx4 v[170:173], v[128:129], off offset:48
	v_or_b32_e32 v128, s24, v115
	v_mad_u64_u32 v[128:129], s[4:5], v128, s78, v[146:147]
	v_mad_i32_i24 v129, s25, v169, v129
	s_mov_b64 s[4:5], 0
	s_waitcnt vmcnt(3)
	v_mov_b32_e32 v174, v116
	v_mov_b32_e32 v175, v118
	v_mov_b32_e32 v118, v117
	s_waitcnt vmcnt(2)
	v_mov_b32_e32 v117, v122
	v_mov_b32_e32 v122, v121
	s_waitcnt vmcnt(1)
	v_mov_b32_e32 v121, v126
	v_mov_b32_e32 v126, v125
	s_waitcnt vmcnt(0)
	v_mov_b32_e32 v125, v172
	v_mov_b32_e32 v172, v171
	v_mov_b32_e32 v116, v120
	v_mov_b32_e32 v120, v124
	v_mov_b32_e32 v124, v170
	v_pk_mul_f32 v[170:171], v[102:103], v[118:119]
	v_pk_mul_f32 v[176:177], v[102:103], v[174:175]
	v_pk_mul_f32 v[178:179], v[104:105], v[122:123]
	v_pk_mul_f32 v[182:183], v[98:99], v[126:127]
	v_pk_mul_f32 v[186:187], v[100:101], v[172:173]
	v_pk_mul_f32 v[180:181], v[104:105], v[116:117]
	v_pk_mul_f32 v[184:185], v[98:99], v[120:121]
	v_pk_mul_f32 v[188:189], v[100:101], v[124:125]
	v_pk_fma_f32 v[170:171], v[110:111], v[174:175], v[170:171] neg_lo:[0,0,1] neg_hi:[0,0,1]
	v_pk_fma_f32 v[118:119], v[110:111], v[118:119], v[176:177]
	v_pk_fma_f32 v[116:117], v[112:113], v[116:117], v[178:179] neg_lo:[0,0,1] neg_hi:[0,0,1]
	v_pk_fma_f32 v[120:121], v[106:107], v[120:121], v[182:183] neg_lo:[0,0,1] neg_hi:[0,0,1]
	v_pk_fma_f32 v[124:125], v[108:109], v[124:125], v[186:187] neg_lo:[0,0,1] neg_hi:[0,0,1]
	v_pk_fma_f32 v[122:123], v[112:113], v[122:123], v[180:181]
	v_pk_fma_f32 v[126:127], v[106:107], v[126:127], v[184:185]
	v_pk_fma_f32 v[172:173], v[108:109], v[172:173], v[188:189]
	v_pk_mul_f32 v[170:171], v[114:115], v[170:171] op_sel_hi:[0,1]
	v_pk_mul_f32 v[174:175], v[114:115], v[118:119] op_sel_hi:[0,1]
	v_pk_mul_f32 v[118:119], v[114:115], v[116:117] op_sel_hi:[0,1]
	v_pk_mul_f32 v[120:121], v[114:115], v[120:121] op_sel_hi:[0,1]
	v_pk_mul_f32 v[124:125], v[114:115], v[124:125] op_sel_hi:[0,1]
	v_pk_mul_f32 v[122:123], v[114:115], v[122:123] op_sel_hi:[0,1]
	v_pk_mul_f32 v[126:127], v[114:115], v[126:127] op_sel_hi:[0,1]
	v_pk_mul_f32 v[172:173], v[114:115], v[172:173] op_sel_hi:[0,1]
	v_cvt_pk_bf16_f32 v116, v170, v171
	v_cvt_pk_bf16_f32 v117, v118, v119
	v_cvt_pk_bf16_f32 v118, v120, v121
	v_cvt_pk_bf16_f32 v119, v124, v125
	v_cvt_pk_bf16_f32 v120, v174, v175
	v_cvt_pk_bf16_f32 v121, v122, v123
	v_cvt_pk_bf16_f32 v122, v126, v127
	v_cvt_pk_bf16_f32 v123, v172, v173
	global_store_dwordx4 v[128:129], v[116:119], off offset:256
	global_store_dwordx4 v[128:129], v[120:123], off offset:320

;     __device__ __forceinline__ void operator()(const Acc& acc, const pg8::Unit& u, int wr, int wc, int fr, int fq) const {
;     ...
;                 const int row = row0 + ai * 128 + m * 16, b = row >> 12, s = row & 4095;
;                 const f32x4 s0 = *(const f32x4*)(stat + (size_t)row * 16), s1 = *(const f32x4*)(stat + (size_t)row * 16 + 4);
;                 const float rs = rsqrtf(((s0[0] + s0[1]) + (s0[2] + s0[3]) + (s1[0] + s1[1]) + (s1[2] + s1[3])) * (1.0f / 512.0f) + EPS);
;                 if (u.pn < 4) {
; #pragma unroll
;                     for (int bj = 0; bj < 2; ++bj) { const int h = 2 * u.pn + bj;
;                         bf16_t* dst = Q + ((size_t)(b * 8 + h) * 4096 + s) * 192 + wc * 32 + 8 * fq;
;                         *(u32x4*)dst = pack8(acc[ai][bj][m][0] * rs, acc[ai][bj][m][1] * rs); }
;                 } else {
;                     const int h = 4 * (u.pn - 4) + wc;
;                     const f32x2* cp = cs + (size_t)row * 32 + 8 * fq;
;                     f32x4 o1[2], o2[2];
; #pragma unroll
;                     for (int n = 0; n < 2; ++n)
; #pragma unroll
;                         for (int i = 0; i < 4; ++i) { const f32x2 c = cp[4 * n + i]; const float x1 = acc[ai][0][m][n][i], x2 = acc[ai][1][m][n][i];
;                             o1[n][i] = (x1 * c.x - x2 * c.y) * rs; o2[n][i] = (x2 * c.x + x1 * c.y) * rs; }
;                     bf16_t* dst = Q + ((size_t)(b * 8 + h) * 4096 + s) * 192 + 128 + 8 * fq;
;                     *(u32x4*)dst = pack8(o1[0], o1[1]); *(u32x4*)(dst + 32) = pack8(o2[0], o2[1]);
.LBB0_676:
	s_nop 1
	v_or_b32_e32 v100, 32, v156
	v_ashrrev_i32_e32 v101, 31, v100
	v_lshlrev_b64 v[98:99], 6, v[100:101]
	v_lshl_add_u64 v[98:99], s[10:11], 0, v[98:99]
	s_and_b64 vcc, exec, s[2:3]
	v_mov_b32_e32 v102, v214
	v_mov_b32_e32 v103, v215
	v_mov_b32_e32 v104, v216
	v_mov_b32_e32 v105, v217
	v_mov_b32_e32 v98, v103
	v_mov_b32_e32 v99, v104
	v_mov_b32_e32 v103, v105
	v_mov_b32_e32 v106, v218
	v_mov_b32_e32 v107, v219
	v_mov_b32_e32 v108, v220
	v_mov_b32_e32 v109, v221
	v_mov_b32_e32 v104, v108
	v_mov_b32_e32 v105, v106
	v_mov_b32_e32 v106, v109
	v_pk_add_f32 v[98:99], v[98:99], v[102:103]
	v_pk_add_f32 v[102:103], v[104:105], v[106:107]
	v_add_f32_e32 v98, v98, v99
	v_add_f32_e32 v98, v98, v103
	v_add_f32_e32 v98, v102, v98
	v_fmamk_f32 v98, v98, 0x3b000000, v167
	v_mul_f32_e32 v99, 0x4b800000, v98
	v_cmp_gt_f32_e64 s[4:5], s77, v98
	s_nop 1
	v_cndmask_b32_e64 v98, v98, v99, s[4:5]
	v_rsq_f32_e32 v98, v98
	v_bitop3_b32 v99, v156, s80, 32 bitop3:0xc8
	v_mul_f32_e32 v102, 0x45800000, v98
	v_cndmask_b32_e64 v98, v98, v102, s[4:5]
	s_mov_b64 s[4:5], -1
	s_cbranch_vccnz .LBB0_678
	v_lshlrev_b64 v[100:101], 8, v[100:101]
	v_lshl_add_u64 v[112:113], v[142:143], 0, v[100:101]
	global_load_dwordx4 v[100:103], v[112:113], off
	global_load_dwordx4 v[104:107], v[112:113], off offset:16
	global_load_dwordx4 v[108:111], v[112:113], off offset:32
	s_nop 0
	global_load_dwordx4 v[112:115], v[112:113], off offset:48
	v_or_b32_e32 v116, s24, v99
	v_mad_u64_u32 v[116:117], s[4:5], v116, s78, v[146:147]
	v_mad_i32_i24 v117, s25, v169, v117
	s_mov_b64 s[4:5], 0
	s_waitcnt vmcnt(3)
	v_mov_b32_e32 v118, v100
	v_mov_b32_e32 v119, v102
	v_mov_b32_e32 v102, v101
	s_waitcnt vmcnt(2)
	v_mov_b32_e32 v101, v106
	v_mov_b32_e32 v106, v105
	s_waitcnt vmcnt(1)
	v_mov_b32_e32 v105, v110
	v_mov_b32_e32 v110, v109
	s_waitcnt vmcnt(0)
	v_mov_b32_e32 v109, v114
	v_mov_b32_e32 v114, v113
	v_mov_b32_e32 v100, v104
	v_mov_b32_e32 v104, v108
	v_mov_b32_e32 v108, v112
	v_pk_mul_f32 v[112:113], v[86:87], v[102:103]
	v_pk_mul_f32 v[120:121], v[86:87], v[118:119]
	v_pk_mul_f32 v[122:123], v[88:89], v[106:107]
	v_pk_mul_f32 v[126:127], v[82:83], v[110:111]
	v_pk_mul_f32 v[170:171], v[84:85], v[114:115]
	v_pk_mul_f32 v[124:125], v[88:89], v[100:101]
	v_pk_mul_f32 v[128:129], v[82:83], v[104:105]
	v_pk_mul_f32 v[172:173], v[84:85], v[108:109]
	v_pk_fma_f32 v[112:113], v[94:95], v[118:119], v[112:113] neg_lo:[0,0,1] neg_hi:[0,0,1]
	v_pk_fma_f32 v[102:103], v[94:95], v[102:103], v[120:121]
	v_pk_fma_f32 v[100:101], v[96:97], v[100:101], v[122:123] neg_lo:[0,0,1] neg_hi:[0,0,1]
	v_pk_fma_f32 v[104:105], v[90:91], v[104:105], v[126:127] neg_lo:[0,0,1] neg_hi:[0,0,1]
	v_pk_fma_f32 v[108:109], v[92:93], v[108:109], v[170:171] neg_lo:[0,0,1] neg_hi:[0,0,1]
	v_pk_fma_f32 v[106:107], v[96:97], v[106:107], v[124:125]
	v_pk_fma_f32 v[110:111], v[90:91], v[110:111], v[128:129]
	v_pk_fma_f32 v[114:115], v[92:93], v[114:115], v[172:173]
	v_pk_mul_f32 v[112:113], v[98:99], v[112:113] op_sel_hi:[0,1]
	v_pk_mul_f32 v[118:119], v[98:99], v[102:103] op_sel_hi:[0,1]
	v_pk_mul_f32 v[102:103], v[98:99], v[100:101] op_sel_hi:[0,1]
	v_pk_mul_f32 v[104:105], v[98:99], v[104:105] op_sel_hi:[0,1]
	v_pk_mul_f32 v[108:109], v[98:99], v[108:109] op_sel_hi:[0,1]
	v_pk_mul_f32 v[106:107], v[98:99], v[106:107] op_sel_hi:[0,1]
	v_pk_mul_f32 v[110:111], v[98:99], v[110:111] op_sel_hi:[0,1]
	v_pk_mul_f32 v[114:115], v[98:99], v[114:115] op_sel_hi:[0,1]
	v_cvt_pk_bf16_f32 v100, v112, v113
	v_cvt_pk_bf16_f32 v101, v102, v103
	v_cvt_pk_bf16_f32 v102, v104, v105
	v_cvt_pk_bf16_f32 v103, v108, v109
	v_cvt_pk_bf16_f32 v104, v118, v119
	v_cvt_pk_bf16_f32 v105, v106, v107
	v_cvt_pk_bf16_f32 v106, v110, v111
	v_cvt_pk_bf16_f32 v107, v114, v115
	global_store_dwordx4 v[116:117], v[100:103], off offset:256
	global_store_dwordx4 v[116:117], v[104:107], off offset:320

;     __device__ __forceinline__ void operator()(const Acc& acc, const pg8::Unit& u, int wr, int wc, int fr, int fq) const {
;     ...
;                 const int row = row0 + ai * 128 + m * 16, b = row >> 12, s = row & 4095;
;                 const f32x4 s0 = *(const f32x4*)(stat + (size_t)row * 16), s1 = *(const f32x4*)(stat + (size_t)row * 16 + 4);
;                 const float rs = rsqrtf(((s0[0] + s0[1]) + (s0[2] + s0[3]) + (s1[0] + s1[1]) + (s1[2] + s1[3])) * (1.0f / 512.0f) + EPS);
;                 if (u.pn < 4) {
; #pragma unroll
;                     for (int bj = 0; bj < 2; ++bj) { const int h = 2 * u.pn + bj;
;                         bf16_t* dst = Q + ((size_t)(b * 8 + h) * 4096 + s) * 192 + wc * 32 + 8 * fq;
;                         *(u32x4*)dst = pack8(acc[ai][bj][m][0] * rs, acc[ai][bj][m][1] * rs); }
;                 } else {
;                     const int h = 4 * (u.pn - 4) + wc;
;                     const f32x2* cp = cs + (size_t)row * 32 + 8 * fq;
;                     f32x4 o1[2], o2[2];
; #pragma unroll
;                     for (int n = 0; n < 2; ++n)
; #pragma unroll
;                         for (int i = 0; i < 4; ++i) { const f32x2 c = cp[4 * n + i]; const float x1 = acc[ai][0][m][n][i], x2 = acc[ai][1][m][n][i];
;                             o1[n][i] = (x1 * c.x - x2 * c.y) * rs; o2[n][i] = (x2 * c.x + x1 * c.y) * rs; }
;                     bf16_t* dst = Q + ((size_t)(b * 8 + h) * 4096 + s) * 192 + 128 + 8 * fq;
;                     *(u32x4*)dst = pack8(o1[0], o1[1]); *(u32x4*)(dst + 32) = pack8(o2[0], o2[1]);
.LBB0_680:
	s_nop 1
	v_or_b32_e32 v84, 48, v156
	v_ashrrev_i32_e32 v85, 31, v84
	v_lshlrev_b64 v[82:83], 6, v[84:85]
	v_lshl_add_u64 v[82:83], s[10:11], 0, v[82:83]
	s_and_b64 vcc, exec, s[2:3]
	v_mov_b32_e32 v86, v222
	v_mov_b32_e32 v87, v223
	v_mov_b32_e32 v88, v224
	v_mov_b32_e32 v89, v225
	v_mov_b32_e32 v82, v87
	v_mov_b32_e32 v83, v88
	v_mov_b32_e32 v87, v89
	v_mov_b32_e32 v90, v226
	v_mov_b32_e32 v91, v227
	v_mov_b32_e32 v92, v228
	v_mov_b32_e32 v93, v229
	v_mov_b32_e32 v88, v92
	v_mov_b32_e32 v89, v90
	v_mov_b32_e32 v90, v93
	v_pk_add_f32 v[82:83], v[82:83], v[86:87]
	v_pk_add_f32 v[86:87], v[88:89], v[90:91]
	v_add_f32_e32 v82, v82, v83
	v_add_f32_e32 v82, v82, v87
	v_add_f32_e32 v82, v86, v82
	v_fmamk_f32 v82, v82, 0x3b000000, v167
	v_mul_f32_e32 v83, 0x4b800000, v82
	v_cmp_gt_f32_e64 s[4:5], s77, v82
	s_nop 1
	v_cndmask_b32_e64 v82, v82, v83, s[4:5]
	v_rsq_f32_e32 v82, v82
	v_bitop3_b32 v83, v156, s81, 48 bitop3:0xc8
	v_mul_f32_e32 v86, 0x45800000, v82
	v_cndmask_b32_e64 v82, v82, v86, s[4:5]
	s_mov_b64 s[4:5], -1
	s_cbranch_vccnz .LBB0_682
	v_lshlrev_b64 v[84:85], 8, v[84:85]
	v_lshl_add_u64 v[96:97], v[142:143], 0, v[84:85]
	global_load_dwordx4 v[84:87], v[96:97], off
	global_load_dwordx4 v[88:91], v[96:97], off offset:16
	global_load_dwordx4 v[92:95], v[96:97], off offset:32
	s_nop 0
	global_load_dwordx4 v[96:99], v[96:97], off offset:48
	v_or_b32_e32 v100, s24, v83
	v_mad_u64_u32 v[100:101], s[4:5], v100, s78, v[146:147]
	v_mad_i32_i24 v101, s25, v169, v101
	s_mov_b64 s[4:5], 0
	s_waitcnt vmcnt(3)
	v_mov_b32_e32 v102, v84
	v_mov_b32_e32 v103, v86
	v_mov_b32_e32 v86, v85
	s_waitcnt vmcnt(2)
	v_mov_b32_e32 v85, v90
	v_mov_b32_e32 v90, v89
	s_waitcnt vmcnt(1)
	v_mov_b32_e32 v89, v94
	v_mov_b32_e32 v94, v93
	s_waitcnt vmcnt(0)
	v_mov_b32_e32 v93, v98
	v_mov_b32_e32 v98, v97
	v_mov_b32_e32 v84, v88
	v_mov_b32_e32 v88, v92
	v_mov_b32_e32 v92, v96
	v_pk_mul_f32 v[96:97], v[70:71], v[86:87]
	v_pk_mul_f32 v[104:105], v[70:71], v[102:103]
	v_pk_mul_f32 v[106:107], v[72:73], v[90:91]
	v_pk_mul_f32 v[110:111], v[66:67], v[94:95]
	v_pk_mul_f32 v[114:115], v[68:69], v[98:99]
	v_pk_mul_f32 v[108:109], v[72:73], v[84:85]
	v_pk_mul_f32 v[112:113], v[66:67], v[88:89]
	v_pk_mul_f32 v[116:117], v[68:69], v[92:93]
	v_pk_fma_f32 v[96:97], v[78:79], v[102:103], v[96:97] neg_lo:[0,0,1] neg_hi:[0,0,1]
	v_pk_fma_f32 v[86:87], v[78:79], v[86:87], v[104:105]
	v_pk_fma_f32 v[84:85], v[80:81], v[84:85], v[106:107] neg_lo:[0,0,1] neg_hi:[0,0,1]
	v_pk_fma_f32 v[88:89], v[74:75], v[88:89], v[110:111] neg_lo:[0,0,1] neg_hi:[0,0,1]
	v_pk_fma_f32 v[92:93], v[76:77], v[92:93], v[114:115] neg_lo:[0,0,1] neg_hi:[0,0,1]
	v_pk_fma_f32 v[90:91], v[80:81], v[90:91], v[108:109]
	v_pk_fma_f32 v[94:95], v[74:75], v[94:95], v[112:113]
	v_pk_fma_f32 v[98:99], v[76:77], v[98:99], v[116:117]
	v_pk_mul_f32 v[96:97], v[82:83], v[96:97] op_sel_hi:[0,1]
	v_pk_mul_f32 v[102:103], v[82:83], v[86:87] op_sel_hi:[0,1]
	v_pk_mul_f32 v[86:87], v[82:83], v[84:85] op_sel_hi:[0,1]
	v_pk_mul_f32 v[88:89], v[82:83], v[88:89] op_sel_hi:[0,1]
	v_pk_mul_f32 v[92:93], v[82:83], v[92:93] op_sel_hi:[0,1]
	v_pk_mul_f32 v[90:91], v[82:83], v[90:91] op_sel_hi:[0,1]
	v_pk_mul_f32 v[94:95], v[82:83], v[94:95] op_sel_hi:[0,1]
	v_pk_mul_f32 v[98:99], v[82:83], v[98:99] op_sel_hi:[0,1]
	v_cvt_pk_bf16_f32 v84, v96, v97
	v_cvt_pk_bf16_f32 v85, v86, v87
	v_cvt_pk_bf16_f32 v86, v88, v89
	v_cvt_pk_bf16_f32 v87, v92, v93
	v_cvt_pk_bf16_f32 v88, v102, v103
	v_cvt_pk_bf16_f32 v89, v90, v91
	v_cvt_pk_bf16_f32 v90, v94, v95
	v_cvt_pk_bf16_f32 v91, v98, v99
	global_store_dwordx4 v[100:101], v[84:87], off offset:256
	global_store_dwordx4 v[100:101], v[88:91], off offset:320

;     __device__ __forceinline__ void operator()(const Acc& acc, const pg8::Unit& u, int wr, int wc, int fr, int fq) const {
;     ...
;                 const int row = row0 + ai * 128 + m * 16, b = row >> 12, s = row & 4095;
;                 const f32x4 s0 = *(const f32x4*)(stat + (size_t)row * 16), s1 = *(const f32x4*)(stat + (size_t)row * 16 + 4);
;                 const float rs = rsqrtf(((s0[0] + s0[1]) + (s0[2] + s0[3]) + (s1[0] + s1[1]) + (s1[2] + s1[3])) * (1.0f / 512.0f) + EPS);
;                 if (u.pn < 4) {
; #pragma unroll
;                     for (int bj = 0; bj < 2; ++bj) { const int h = 2 * u.pn + bj;
;                         bf16_t* dst = Q + ((size_t)(b * 8 + h) * 4096 + s) * 192 + wc * 32 + 8 * fq;
;                         *(u32x4*)dst = pack8(acc[ai][bj][m][0] * rs, acc[ai][bj][m][1] * rs); }
;                 } else {
;                     const int h = 4 * (u.pn - 4) + wc;
;                     const f32x2* cp = cs + (size_t)row * 32 + 8 * fq;
;                     f32x4 o1[2], o2[2];
; #pragma unroll
;                     for (int n = 0; n < 2; ++n)
; #pragma unroll
;                         for (int i = 0; i < 4; ++i) { const f32x2 c = cp[4 * n + i]; const float x1 = acc[ai][0][m][n][i], x2 = acc[ai][1][m][n][i];
;                             o1[n][i] = (x1 * c.x - x2 * c.y) * rs; o2[n][i] = (x2 * c.x + x1 * c.y) * rs; }
;                     bf16_t* dst = Q + ((size_t)(b * 8 + h) * 4096 + s) * 192 + 128 + 8 * fq;
;                     *(u32x4*)dst = pack8(o1[0], o1[1]); *(u32x4*)(dst + 32) = pack8(o2[0], o2[1]);
.LBB0_684:
	s_nop 1
	v_add_u32_e32 v68, 0x80, v156
	v_ashrrev_i32_e32 v69, 31, v68
	v_lshlrev_b64 v[66:67], 6, v[68:69]
	v_lshl_add_u64 v[66:67], s[10:11], 0, v[66:67]
	v_ashrrev_i32_e32 v66, 9, v68
	v_and_b32_e32 v70, -8, v66
	s_and_b64 vcc, exec, s[2:3]
	v_and_b32_e32 v73, 0xfcf, v68
	v_mov_b32_e32 v74, v230
	v_mov_b32_e32 v75, v231
	v_mov_b32_e32 v76, v232
	v_mov_b32_e32 v77, v233
	v_mov_b32_e32 v66, v75
	v_mov_b32_e32 v67, v76
	v_mov_b32_e32 v75, v77
	v_mov_b32_e32 v78, v234
	v_mov_b32_e32 v79, v235
	v_mov_b32_e32 v80, v236
	v_mov_b32_e32 v81, v237
	v_mov_b32_e32 v76, v80
	v_mov_b32_e32 v77, v78
	v_mov_b32_e32 v78, v81
	v_pk_add_f32 v[66:67], v[66:67], v[74:75]
	v_pk_add_f32 v[74:75], v[76:77], v[78:79]
	v_add_f32_e32 v66, v66, v67
	v_add_f32_e32 v66, v66, v75
	v_add_f32_e32 v66, v74, v66
	v_fmamk_f32 v66, v66, 0x3b000000, v167
	v_mul_f32_e32 v67, 0x4b800000, v66
	v_cmp_gt_f32_e64 s[4:5], s77, v66
	s_nop 1
	v_cndmask_b32_e64 v66, v66, v67, s[4:5]
	v_rsq_f32_e32 v71, v66
	v_add_u32_e32 v66, s19, v70
	v_ashrrev_i32_e32 v67, 31, v66
	v_lshlrev_b64 v[66:67], 12, v[66:67]
	v_mul_f32_e32 v72, 0x45800000, v71
	v_cndmask_b32_e64 v72, v71, v72, s[4:5]
	s_mov_b64 s[4:5], -1
	s_cbranch_vccnz .LBB0_686
	v_lshlrev_b64 v[68:69], 8, v[68:69]
	v_lshl_add_u64 v[68:69], v[142:143], 0, v[68:69]
	global_load_dwordx4 v[74:77], v[68:69], off
	global_load_dwordx4 v[78:81], v[68:69], off offset:16
	global_load_dwordx4 v[82:85], v[68:69], off offset:32
	global_load_dwordx4 v[86:89], v[68:69], off offset:48
	v_or_b32_e32 v68, v66, v73
	v_mad_u64_u32 v[68:69], s[4:5], v68, s78, v[146:147]
	v_mad_i32_i24 v69, v67, s78, v69
	s_mov_b64 s[4:5], 0
	s_waitcnt vmcnt(3)
	v_mov_b32_e32 v90, v74
	v_mov_b32_e32 v91, v76
	v_mov_b32_e32 v76, v75
	s_waitcnt vmcnt(2)
	v_mov_b32_e32 v75, v80
	v_mov_b32_e32 v80, v79
	s_waitcnt vmcnt(1)
	v_mov_b32_e32 v79, v84
	v_mov_b32_e32 v84, v83
	s_waitcnt vmcnt(0)
	v_mov_b32_e32 v83, v88
	v_mov_b32_e32 v88, v87
	v_mov_b32_e32 v74, v78
	v_mov_b32_e32 v78, v82
	v_mov_b32_e32 v82, v86
	v_pk_mul_f32 v[86:87], v[54:55], v[76:77]
	v_pk_mul_f32 v[92:93], v[54:55], v[90:91]
	v_pk_mul_f32 v[94:95], v[56:57], v[80:81]
	v_pk_mul_f32 v[98:99], v[50:51], v[84:85]
	v_pk_mul_f32 v[102:103], v[52:53], v[88:89]
	v_pk_mul_f32 v[96:97], v[56:57], v[74:75]
	v_pk_mul_f32 v[100:101], v[50:51], v[78:79]
	v_pk_mul_f32 v[104:105], v[52:53], v[82:83]
	v_pk_fma_f32 v[86:87], v[62:63], v[90:91], v[86:87] neg_lo:[0,0,1] neg_hi:[0,0,1]
	v_pk_fma_f32 v[76:77], v[62:63], v[76:77], v[92:93]
	v_pk_fma_f32 v[74:75], v[64:65], v[74:75], v[94:95] neg_lo:[0,0,1] neg_hi:[0,0,1]
	v_pk_fma_f32 v[78:79], v[58:59], v[78:79], v[98:99] neg_lo:[0,0,1] neg_hi:[0,0,1]
	v_pk_fma_f32 v[82:83], v[60:61], v[82:83], v[102:103] neg_lo:[0,0,1] neg_hi:[0,0,1]
	v_pk_fma_f32 v[80:81], v[64:65], v[80:81], v[96:97]
	v_pk_fma_f32 v[84:85], v[58:59], v[84:85], v[100:101]
	v_pk_fma_f32 v[88:89], v[60:61], v[88:89], v[104:105]
	v_pk_mul_f32 v[86:87], v[72:73], v[86:87] op_sel_hi:[0,1]
	v_pk_mul_f32 v[90:91], v[72:73], v[76:77] op_sel_hi:[0,1]
	v_pk_mul_f32 v[76:77], v[72:73], v[74:75] op_sel_hi:[0,1]
	v_pk_mul_f32 v[78:79], v[72:73], v[78:79] op_sel_hi:[0,1]
	v_pk_mul_f32 v[82:83], v[72:73], v[82:83] op_sel_hi:[0,1]
	v_pk_mul_f32 v[80:81], v[72:73], v[80:81] op_sel_hi:[0,1]
	v_pk_mul_f32 v[84:85], v[72:73], v[84:85] op_sel_hi:[0,1]
	v_pk_mul_f32 v[88:89], v[72:73], v[88:89] op_sel_hi:[0,1]
	v_cvt_pk_bf16_f32 v74, v86, v87
	v_cvt_pk_bf16_f32 v75, v76, v77
	v_cvt_pk_bf16_f32 v76, v78, v79
	v_cvt_pk_bf16_f32 v77, v82, v83
	v_cvt_pk_bf16_f32 v78, v90, v91
	v_cvt_pk_bf16_f32 v79, v80, v81
	v_cvt_pk_bf16_f32 v80, v84, v85
	v_cvt_pk_bf16_f32 v81, v88, v89
	global_store_dwordx4 v[68:69], v[74:77], off offset:256
	global_store_dwordx4 v[68:69], v[78:81], off offset:320

;     __device__ __forceinline__ void operator()(const Acc& acc, const pg8::Unit& u, int wr, int wc, int fr, int fq) const {
;     ...
;                 const int row = row0 + ai * 128 + m * 16, b = row >> 12, s = row & 4095;
;                 const f32x4 s0 = *(const f32x4*)(stat + (size_t)row * 16), s1 = *(const f32x4*)(stat + (size_t)row * 16 + 4);
;                 const float rs = rsqrtf(((s0[0] + s0[1]) + (s0[2] + s0[3]) + (s1[0] + s1[1]) + (s1[2] + s1[3])) * (1.0f / 512.0f) + EPS);
;                 if (u.pn < 4) {
; #pragma unroll
;                     for (int bj = 0; bj < 2; ++bj) { const int h = 2 * u.pn + bj;
;                         bf16_t* dst = Q + ((size_t)(b * 8 + h) * 4096 + s) * 192 + wc * 32 + 8 * fq;
;                         *(u32x4*)dst = pack8(acc[ai][bj][m][0] * rs, acc[ai][bj][m][1] * rs); }
;                 } else {
;                     const int h = 4 * (u.pn - 4) + wc;
;                     const f32x2* cp = cs + (size_t)row * 32 + 8 * fq;
;                     f32x4 o1[2], o2[2];
; #pragma unroll
;                     for (int n = 0; n < 2; ++n)
; #pragma unroll
;                         for (int i = 0; i < 4; ++i) { const f32x2 c = cp[4 * n + i]; const float x1 = acc[ai][0][m][n][i], x2 = acc[ai][1][m][n][i];
;                             o1[n][i] = (x1 * c.x - x2 * c.y) * rs; o2[n][i] = (x2 * c.x + x1 * c.y) * rs; }
;                     bf16_t* dst = Q + ((size_t)(b * 8 + h) * 4096 + s) * 192 + 128 + 8 * fq;
;                     *(u32x4*)dst = pack8(o1[0], o1[1]); *(u32x4*)(dst + 32) = pack8(o2[0], o2[1]);
.LBB0_688:
	s_nop 1
	v_add_u32_e32 v52, 0x90, v156
	v_ashrrev_i32_e32 v53, 31, v52
	v_lshlrev_b64 v[50:51], 6, v[52:53]
	v_lshl_add_u64 v[50:51], s[10:11], 0, v[50:51]
	s_and_b64 vcc, exec, s[2:3]
	v_mov_b32_e32 v54, v238
	v_mov_b32_e32 v55, v239
	v_mov_b32_e32 v56, v240
	v_mov_b32_e32 v57, v241
	v_mov_b32_e32 v50, v55
	v_mov_b32_e32 v51, v56
	v_mov_b32_e32 v55, v57
	v_mov_b32_e32 v58, v242
	v_mov_b32_e32 v59, v243
	v_mov_b32_e32 v60, v244
	v_mov_b32_e32 v61, v245
	v_mov_b32_e32 v56, v60
	v_mov_b32_e32 v57, v58
	v_mov_b32_e32 v58, v61
	v_pk_add_f32 v[50:51], v[50:51], v[54:55]
	v_pk_add_f32 v[54:55], v[56:57], v[58:59]
	v_add_f32_e32 v50, v50, v51
	v_add_f32_e32 v50, v50, v55
	v_add_f32_e32 v50, v54, v50
	v_fmamk_f32 v50, v50, 0x3b000000, v167
	v_mul_f32_e32 v51, 0x4b800000, v50
	v_cmp_gt_f32_e64 s[4:5], s77, v50
	s_nop 1
	v_cndmask_b32_e64 v50, v50, v51, s[4:5]
	v_rsq_f32_e32 v50, v50
	v_and_b32_e32 v51, 0xfdf, v52
	v_mul_f32_e32 v54, 0x45800000, v50
	v_cndmask_b32_e64 v50, v50, v54, s[4:5]
	s_mov_b64 s[4:5], -1
	s_cbranch_vccnz .LBB0_690
	v_lshlrev_b64 v[52:53], 8, v[52:53]
	v_lshl_add_u64 v[64:65], v[142:143], 0, v[52:53]
	global_load_dwordx4 v[52:55], v[64:65], off
	global_load_dwordx4 v[56:59], v[64:65], off offset:16
	global_load_dwordx4 v[60:63], v[64:65], off offset:32
	global_load_dwordx4 v[72:75], v[64:65], off offset:48
	v_or_b32_e32 v64, v66, v51
	v_mad_u64_u32 v[64:65], s[4:5], v64, s78, v[146:147]
	v_mad_i32_i24 v65, v67, s78, v65
	s_mov_b64 s[4:5], 0
	s_waitcnt vmcnt(3)
	v_mov_b32_e32 v76, v52
	v_mov_b32_e32 v77, v54
	v_mov_b32_e32 v54, v53
	s_waitcnt vmcnt(2)
	v_mov_b32_e32 v53, v58
	v_mov_b32_e32 v58, v57
	s_waitcnt vmcnt(1)
	v_mov_b32_e32 v57, v62
	v_mov_b32_e32 v62, v61
	s_waitcnt vmcnt(0)
	v_mov_b32_e32 v61, v74
	v_mov_b32_e32 v74, v73
	v_mov_b32_e32 v52, v56
	v_mov_b32_e32 v56, v60
	v_mov_b32_e32 v60, v72
	v_pk_mul_f32 v[72:73], v[38:39], v[54:55]
	v_pk_mul_f32 v[78:79], v[38:39], v[76:77]
	v_pk_mul_f32 v[80:81], v[40:41], v[58:59]
	v_pk_mul_f32 v[84:85], v[34:35], v[62:63]
	v_pk_mul_f32 v[88:89], v[36:37], v[74:75]
	v_pk_mul_f32 v[82:83], v[40:41], v[52:53]
	v_pk_mul_f32 v[86:87], v[34:35], v[56:57]
	v_pk_mul_f32 v[90:91], v[36:37], v[60:61]
	v_pk_fma_f32 v[72:73], v[46:47], v[76:77], v[72:73] neg_lo:[0,0,1] neg_hi:[0,0,1]
	v_pk_fma_f32 v[54:55], v[46:47], v[54:55], v[78:79]
	v_pk_fma_f32 v[52:53], v[48:49], v[52:53], v[80:81] neg_lo:[0,0,1] neg_hi:[0,0,1]
	v_pk_fma_f32 v[56:57], v[42:43], v[56:57], v[84:85] neg_lo:[0,0,1] neg_hi:[0,0,1]
	v_pk_fma_f32 v[60:61], v[44:45], v[60:61], v[88:89] neg_lo:[0,0,1] neg_hi:[0,0,1]
	v_pk_fma_f32 v[58:59], v[48:49], v[58:59], v[82:83]
	v_pk_fma_f32 v[62:63], v[42:43], v[62:63], v[86:87]
	v_pk_fma_f32 v[74:75], v[44:45], v[74:75], v[90:91]
	v_pk_mul_f32 v[72:73], v[50:51], v[72:73] op_sel_hi:[0,1]
	v_pk_mul_f32 v[76:77], v[50:51], v[54:55] op_sel_hi:[0,1]
	v_pk_mul_f32 v[54:55], v[50:51], v[52:53] op_sel_hi:[0,1]
	v_pk_mul_f32 v[56:57], v[50:51], v[56:57] op_sel_hi:[0,1]
	v_pk_mul_f32 v[60:61], v[50:51], v[60:61] op_sel_hi:[0,1]
	v_pk_mul_f32 v[58:59], v[50:51], v[58:59] op_sel_hi:[0,1]
	v_pk_mul_f32 v[62:63], v[50:51], v[62:63] op_sel_hi:[0,1]
	v_pk_mul_f32 v[74:75], v[50:51], v[74:75] op_sel_hi:[0,1]
	v_cvt_pk_bf16_f32 v52, v72, v73
	v_cvt_pk_bf16_f32 v53, v54, v55
	v_cvt_pk_bf16_f32 v54, v56, v57
	v_cvt_pk_bf16_f32 v55, v60, v61
	v_cvt_pk_bf16_f32 v56, v76, v77
	v_cvt_pk_bf16_f32 v57, v58, v59
	v_cvt_pk_bf16_f32 v58, v62, v63
	v_cvt_pk_bf16_f32 v59, v74, v75
	global_store_dwordx4 v[64:65], v[52:55], off offset:256
	global_store_dwordx4 v[64:65], v[56:59], off offset:320

;     __host__ __device__ bool next(int i, Unit& u) const {
;         const long L = (long)i * G + c; if (L >= nwg) return false;
;         int wgid = (int)L; { const int q = nwg / NXCD, r = nwg % NXCD, xcd = wgid % NXCD, off = wgid / NXCD; wgid = (xcd < r ? xcd * (q + 1) : r * (q + 1) + (xcd - r) * q) + off; }
;         const int nig = WGM * nN, gid = wgid / nig, fm = gid * WGM, gsz = (nM - fm) < WGM ? (nM - fm) : WGM;
;         u.pm = fm + ((wgid % nig) % gsz); u.pn = (wgid % nig) / gsz; return true;
; template <class Epi, bool SEG = false>
; __device__ __forceinline__ void gemm_phase(LAS unsigned char* lds, const Gemm g, const StaticOrder& S, const Epi& E, const float* stat2 = nullptr) {
;     ...
;     if (!S.next(0, cur)) return;
.LBB0_704:
	s_mov_b32 s32, 0
	s_cmpk_gt_i32 s28, 0x3ff
	v_readfirstlane_b32 s2, v1
	s_cbranch_scc1 .LBB0_730
	s_ashr_i32 s34, s28, 31
	s_lshr_b32 s0, s34, 29
	s_add_i32 s5, s28, s0
	s_and_b32 s0, s5, -8
	s_sub_i32 s3, s28, s0
	s_cmp_gt_i32 s3, -1
	s_cbranch_scc0 .LBB0_707
	s_lshl_b32 s4, s3, 7
	s_ashr_i32 s0, s5, 3
	s_cbranch_execz .LBB0_708
	s_branch .LBB0_709

; #define PG8_MMA(ai, bj, At, Bt) do { __builtin_amdgcn_s_setprio(1); _Pragma("unroll") for (int m = 0; m < 4; ++m) _Pragma("unroll") for (int n = 0; n < 2; ++n) _Pragma("unroll") for (int k = 0; k < 2; ++k) \
;         acc[ai][bj][m][n] = __builtin_amdgcn_mfma_f32_16x16x32_bf16(Bt[n][k], At[m][k], acc[ai][bj][m][n], 0, 0, 0); __builtin_amdgcn_s_setprio(0); } while (0)
; #define PG8_WAIT_V(n) asm volatile("s_waitcnt vmcnt(" #n ")" ::: "memory")
; #define PG8_WAIT_L(n) asm volatile("s_waitcnt lgkmcnt(" #n ")" ::: "memory")
; #define PG8_BAR __builtin_amdgcn_s_barrier()
; #define PG8_SCHED __builtin_amdgcn_sched_barrier(0)
; template <class Epi, bool SEG = false>
; __device__ __forceinline__ void gemm_phase(LAS unsigned char* lds, const Gemm g, const StaticOrder& S, const Epi& E, const float* stat2 = nullptr) {
;     ...
;             PG8_WAIT_V(8); PG8_WAIT_L(0); PG8_BAR; PG8_MMA(0, 0, At, B0); PG8_MMA(0, 1, At, B1); PG8_BAR; PG8_SCHED;
.Lt1_rx2_0:
	s_waitcnt vmcnt(48)
	s_branch .Lt1_j2_0
.Lt1_rx2_1:
	s_waitcnt vmcnt(48)
	s_mov_b32 s32, 0
	s_branch .Lt1_j2_1

; #define PG8_STAGE(bufoff, gbase, voff) do { _Pragma("unroll") for (int _i = 0; _i < 2; ++_i) \
;         __builtin_amdgcn_global_load_lds((const unsigned*)((const char*)(gbase) + (voff)[_i]), (LAS unsigned*)(lds + (bufoff) + ldsw + _i * 8192), 16, 0, 0); } while (0)
; #define PG8_LDA(dst, b, h) do { _Pragma("unroll") for (int m = 0; m < 4; ++m) _Pragma("unroll") for (int k = 0; k < 2; ++k) dst[m][k] = *(const LAS bf16x8*)(lds + PG8_SA(b, h) + aoff + m * 2048 + k * 1024); } while (0)
; #define PG8_LDB(dst, b, h) do { _Pragma("unroll") for (int n = 0; n < 2; ++n) _Pragma("unroll") for (int k = 0; k < 2; ++k) dst[n][k] = *(const LAS bf16x8*)(lds + PG8_SB(b, h) + boff + n * 2048 + k * 1024); } while (0)
; #define PG8_MMA(ai, bj, At, Bt) do { __builtin_amdgcn_s_setprio(1); _Pragma("unroll") for (int m = 0; m < 4; ++m) _Pragma("unroll") for (int n = 0; n < 2; ++n) _Pragma("unroll") for (int k = 0; k < 2; ++k) \
;         acc[ai][bj][m][n] = __builtin_amdgcn_mfma_f32_16x16x32_bf16(Bt[n][k], At[m][k], acc[ai][bj][m][n], 0, 0, 0); __builtin_amdgcn_s_setprio(0); } while (0)
; #define PG8_WAIT_V(n) asm volatile("s_waitcnt vmcnt(" #n ")" ::: "memory")
; #define PG8_WAIT_L(n) asm volatile("s_waitcnt lgkmcnt(" #n ")" ::: "memory")
; #define PG8_BAR __builtin_amdgcn_s_barrier()
; #define PG8_SCHED __builtin_amdgcn_sched_barrier(0)
; template <class Epi, bool SEG = false>
; __device__ __forceinline__ void gemm_phase(LAS unsigned char* lds, const Gemm g, const StaticOrder& S, const Epi& E, const float* stat2 = nullptr) {
;     ...
;             const char* a2 = last ? nA : cA + (size_t)(t + 2) * kstep; const char* b2 = last ? nB : cB + (size_t)(t + 2) * kstep;
;             const char* a3 = a2 + kstep; const char* b3 = b2 + kstep;
;             PG8_LDB(B0, 0, 0); PG8_LDB(B1, 0, 1); PG8_SCHED; PG8_LDA(At, 0, 0); PG8_STAGE(PG8_SA(1, 1), a1 + hstepA, voffA);
;             PG8_WAIT_V(8); PG8_WAIT_L(0); PG8_BAR; PG8_MMA(0, 0, At, B0); PG8_MMA(0, 1, At, B1); PG8_BAR; PG8_SCHED;
;             PG8_LDA(At, 0, 1); PG8_STAGE(PG8_SB(0, 0), b2, voffB); PG8_STAGE(PG8_SB(0, 1), b2 + hstepB, voffB); PG8_STAGE(PG8_SA(0, 0), a2, voffA);
.LBB0_723:
	ds_read_b128 v[152:155], v156
	ds_read_b128 v[164:167], v156 offset:1024
	ds_read_b128 v[168:171], v156 offset:2048
	ds_read_b128 v[172:175], v156 offset:3072
	ds_read_b128 v[176:179], v157
	ds_read_b128 v[180:183], v157 offset:1024
	ds_read_b128 v[184:187], v157 offset:2048
	ds_read_b128 v[188:191], v157 offset:3072
	s_add_u32 s30, s4, 0xfff10080
	s_addc_u32 s31, s5, -1
	s_cmp_eq_u32 s93, 4
	s_cselect_b32 s47, s27, s31
	s_cselect_b32 s46, s26, s30
	s_cselect_b32 s45, s25, s92
	s_cselect_b32 s44, s90, s91
	v_lshl_add_u64 v[224:225], s[4:5], 0, v[142:143]
	s_add_i32 m0, s58, 0xc000
	ds_read_b128 v[192:195], v158
	ds_read_b128 v[196:199], v158 offset:1024
	ds_read_b128 v[200:203], v158 offset:2048
	ds_read_b128 v[204:207], v158 offset:3072
	ds_read_b128 v[208:211], v158 offset:4096
	ds_read_b128 v[212:215], v158 offset:5120
	ds_read_b128 v[216:219], v158 offset:6144
	ds_read_b128 v[220:223], v158 offset:7168
	global_load_lds_dwordx4 v[224:225], off
	v_lshl_add_u64 v[224:225], s[4:5], 0, v[144:145]
	s_add_i32 m0, s58, 0xe000
	s_nop 0
	global_load_lds_dwordx4 v[224:225], off
	s_cmp_eq_u32 s32, 0
	s_cbranch_scc0 .Lt1_rx2_0
	s_waitcnt vmcnt(8)
.Lt1_j2_0:
	s_waitcnt lgkmcnt(0)
	s_barrier
	s_setprio 1
	s_waitcnt lgkmcnt(0)
	v_mfma_f32_16x16x32_bf16 v[126:129], v[152:155], v[192:195], v[126:129]
	v_mfma_f32_16x16x32_bf16 v[122:125], v[168:171], v[192:195], v[122:125]
	v_mfma_f32_16x16x32_bf16 v[110:113], v[152:155], v[200:203], v[110:113]
	v_mfma_f32_16x16x32_bf16 v[106:109], v[168:171], v[200:203], v[106:109]
	v_mfma_f32_16x16x32_bf16 v[94:97], v[152:155], v[208:211], v[94:97]
	v_mfma_f32_16x16x32_bf16 v[90:93], v[168:171], v[208:211], v[90:93]
	v_mfma_f32_16x16x32_bf16 v[78:81], v[152:155], v[216:219], v[78:81]
	v_mfma_f32_16x16x32_bf16 v[74:77], v[168:171], v[216:219], v[74:77]
	v_mfma_f32_16x16x32_bf16 v[126:129], v[164:167], v[196:199], v[126:129]
	v_mfma_f32_16x16x32_bf16 v[122:125], v[172:175], v[196:199], v[122:125]
	v_mfma_f32_16x16x32_bf16 v[110:113], v[164:167], v[204:207], v[110:113]
	v_mfma_f32_16x16x32_bf16 v[106:109], v[172:175], v[204:207], v[106:109]
	v_mfma_f32_16x16x32_bf16 v[94:97], v[164:167], v[212:215], v[94:97]
	v_mfma_f32_16x16x32_bf16 v[90:93], v[172:175], v[212:215], v[90:93]
	v_mfma_f32_16x16x32_bf16 v[78:81], v[164:167], v[220:223], v[78:81]
	v_mfma_f32_16x16x32_bf16 v[74:77], v[172:175], v[220:223], v[74:77]
	s_setprio 0
	s_setprio 1
	v_mfma_f32_16x16x32_bf16 v[118:121], v[176:179], v[192:195], v[118:121]
	v_mfma_f32_16x16x32_bf16 v[114:117], v[184:187], v[192:195], v[114:117]
	v_mfma_f32_16x16x32_bf16 v[102:105], v[176:179], v[200:203], v[102:105]
	v_mfma_f32_16x16x32_bf16 v[98:101], v[184:187], v[200:203], v[98:101]
	v_mfma_f32_16x16x32_bf16 v[86:89], v[176:179], v[208:211], v[86:89]
	v_mfma_f32_16x16x32_bf16 v[82:85], v[184:187], v[208:211], v[82:85]
	v_mfma_f32_16x16x32_bf16 v[70:73], v[176:179], v[216:219], v[70:73]
	v_mfma_f32_16x16x32_bf16 v[66:69], v[184:187], v[216:219], v[66:69]
	v_mfma_f32_16x16x32_bf16 v[118:121], v[180:183], v[196:199], v[118:121]
	v_mfma_f32_16x16x32_bf16 v[114:117], v[188:191], v[196:199], v[114:117]
	v_mfma_f32_16x16x32_bf16 v[102:105], v[180:183], v[204:207], v[102:105]
	v_mfma_f32_16x16x32_bf16 v[98:101], v[188:191], v[204:207], v[98:101]
	v_mfma_f32_16x16x32_bf16 v[86:89], v[180:183], v[212:215], v[86:89]
	v_mfma_f32_16x16x32_bf16 v[82:85], v[188:191], v[212:215], v[82:85]
	v_mfma_f32_16x16x32_bf16 v[70:73], v[180:183], v[220:223], v[70:73]
	v_mfma_f32_16x16x32_bf16 v[66:69], v[188:191], v[220:223], v[66:69]
	s_setprio 0
	s_barrier
	s_add_i32 s30, s79, s57
	v_lshl_add_u64 v[224:225], s[44:45], 0, v[132:133]
	s_mov_b32 m0, s30
	ds_read_b128 v[192:195], v158 offset:16384
	ds_read_b128 v[196:199], v158 offset:17408
	ds_read_b128 v[200:203], v158 offset:18432
	ds_read_b128 v[204:207], v158 offset:19456
	ds_read_b128 v[208:211], v158 offset:20480
	ds_read_b128 v[212:215], v158 offset:21504
	ds_read_b128 v[216:219], v158 offset:22528
	ds_read_b128 v[220:223], v158 offset:23552
	global_load_lds_dwordx4 v[224:225], off
	s_add_i32 m0, s30, 0x2000
	s_add_u32 s30, s44, 0x20000
	v_lshl_add_u64 v[226:227], s[44:45], 0, v[136:137]
	s_addc_u32 s31, s45, 0
	s_add_i32 s94, s80, s57
	global_load_lds_dwordx4 v[226:227], off
	v_lshl_add_u64 v[228:229], s[30:31], 0, v[132:133]
	s_mov_b32 m0, s94
	v_lshl_add_u64 v[230:231], s[46:47], 0, v[134:135]
	global_load_lds_dwordx4 v[228:229], off
	v_lshl_add_u64 v[228:229], s[30:31], 0, v[136:137]
	s_add_i32 m0, s94, 0x2000
	s_nop 0
	global_load_lds_dwordx4 v[228:229], off
	v_lshl_add_u64 v[228:229], s[46:47], 0, v[130:131]
	s_mov_b32 m0, s58
	s_nop 0
	global_load_lds_dwordx4 v[228:229], off
	s_mov_b32 m0, s59
	s_nop 0
	global_load_lds_dwordx4 v[230:231], off
	s_cmp_eq_u32 s32, 0
	s_cbranch_scc0 .Lt1_rx2_1
	s_waitcnt vmcnt(8)
; #define PG8_STAGE(bufoff, gbase, voff) do { _Pragma("unroll") for (int _i = 0; _i < 2; ++_i) \
;         __builtin_amdgcn_global_load_lds((const unsigned*)((const char*)(gbase) + (voff)[_i]), (LAS unsigned*)(lds + (bufoff) + ldsw + _i * 8192), 16, 0, 0); } while (0)
; #define PG8_LDA(dst, b, h) do { _Pragma("unroll") for (int m = 0; m < 4; ++m) _Pragma("unroll") for (int k = 0; k < 2; ++k) dst[m][k] = *(const LAS bf16x8*)(lds + PG8_SA(b, h) + aoff + m * 2048 + k * 1024); } while (0)
; #define PG8_LDB(dst, b, h) do { _Pragma("unroll") for (int n = 0; n < 2; ++n) _Pragma("unroll") for (int k = 0; k < 2; ++k) dst[n][k] = *(const LAS bf16x8*)(lds + PG8_SB(b, h) + boff + n * 2048 + k * 1024); } while (0)
; #define PG8_MMA(ai, bj, At, Bt) do { __builtin_amdgcn_s_setprio(1); _Pragma("unroll") for (int m = 0; m < 4; ++m) _Pragma("unroll") for (int n = 0; n < 2; ++n) _Pragma("unroll") for (int k = 0; k < 2; ++k) \
;         acc[ai][bj][m][n] = __builtin_amdgcn_mfma_f32_16x16x32_bf16(Bt[n][k], At[m][k], acc[ai][bj][m][n], 0, 0, 0); __builtin_amdgcn_s_setprio(0); } while (0)
; #define PG8_WAIT_V(n) asm volatile("s_waitcnt vmcnt(" #n ")" ::: "memory")
; #define PG8_WAIT_L(n) asm volatile("s_waitcnt lgkmcnt(" #n ")" ::: "memory")
; #define PG8_BAR __builtin_amdgcn_s_barrier()
; #define PG8_SCHED __builtin_amdgcn_sched_barrier(0)
; template <class Epi, bool SEG = false>
; __device__ __forceinline__ void gemm_phase(LAS unsigned char* lds, const Gemm g, const StaticOrder& S, const Epi& E, const float* stat2 = nullptr) {
;     ...
;             PG8_WAIT_V(8); PG8_WAIT_L(0); PG8_BAR; PG8_MMA(1, 0, At, B0); PG8_MMA(1, 1, At, B1); PG8_BAR; PG8_SCHED;
;             PG8_LDB(B0, 1, 0); PG8_LDB(B1, 1, 1); PG8_SCHED; PG8_LDA(At, 1, 0); PG8_STAGE(PG8_SA(0, 1), a2 + hstepA, voffA);
;             PG8_WAIT_V(8); PG8_WAIT_L(0); PG8_BAR; PG8_MMA(0, 0, At, B0); PG8_MMA(0, 1, At, B1); PG8_BAR; PG8_SCHED;
.Lt1_j2_1:
	s_waitcnt lgkmcnt(0)
	s_barrier
	s_setprio 1
	s_waitcnt lgkmcnt(0)
	v_mfma_f32_16x16x32_bf16 v[62:65], v[152:155], v[192:195], v[62:65]
	v_mfma_f32_16x16x32_bf16 v[58:61], v[168:171], v[192:195], v[58:61]
	v_mfma_f32_16x16x32_bf16 v[46:49], v[152:155], v[200:203], v[46:49]
	v_mfma_f32_16x16x32_bf16 v[42:45], v[168:171], v[200:203], v[42:45]
	v_mfma_f32_16x16x32_bf16 v[30:33], v[152:155], v[208:211], v[30:33]
	v_mfma_f32_16x16x32_bf16 v[26:29], v[168:171], v[208:211], v[26:29]
	v_mfma_f32_16x16x32_bf16 v[14:17], v[152:155], v[216:219], v[14:17]
	v_mfma_f32_16x16x32_bf16 v[10:13], v[168:171], v[216:219], v[10:13]
	v_mfma_f32_16x16x32_bf16 v[62:65], v[164:167], v[196:199], v[62:65]
	v_mfma_f32_16x16x32_bf16 v[58:61], v[172:175], v[196:199], v[58:61]
	v_mfma_f32_16x16x32_bf16 v[46:49], v[164:167], v[204:207], v[46:49]
	v_mfma_f32_16x16x32_bf16 v[42:45], v[172:175], v[204:207], v[42:45]
	v_mfma_f32_16x16x32_bf16 v[30:33], v[164:167], v[212:215], v[30:33]
	v_mfma_f32_16x16x32_bf16 v[26:29], v[172:175], v[212:215], v[26:29]
	v_mfma_f32_16x16x32_bf16 v[14:17], v[164:167], v[220:223], v[14:17]
	v_mfma_f32_16x16x32_bf16 v[10:13], v[172:175], v[220:223], v[10:13]
	s_setprio 0
	s_setprio 1
	v_mfma_f32_16x16x32_bf16 v[54:57], v[176:179], v[192:195], v[54:57]
	v_mfma_f32_16x16x32_bf16 v[50:53], v[184:187], v[192:195], v[50:53]
	v_mfma_f32_16x16x32_bf16 v[38:41], v[176:179], v[200:203], v[38:41]
	v_mfma_f32_16x16x32_bf16 v[34:37], v[184:187], v[200:203], v[34:37]
	v_mfma_f32_16x16x32_bf16 v[22:25], v[176:179], v[208:211], v[22:25]
	v_mfma_f32_16x16x32_bf16 v[18:21], v[184:187], v[208:211], v[18:21]
	v_mfma_f32_16x16x32_bf16 v[6:9], v[176:179], v[216:219], v[6:9]
	v_mfma_f32_16x16x32_bf16 v[2:5], v[184:187], v[216:219], v[2:5]
	v_mfma_f32_16x16x32_bf16 v[54:57], v[180:183], v[196:199], v[54:57]
	v_mfma_f32_16x16x32_bf16 v[50:53], v[188:191], v[196:199], v[50:53]
	v_mfma_f32_16x16x32_bf16 v[38:41], v[180:183], v[204:207], v[38:41]
	v_mfma_f32_16x16x32_bf16 v[34:37], v[188:191], v[204:207], v[34:37]
	v_mfma_f32_16x16x32_bf16 v[22:25], v[180:183], v[212:215], v[22:25]
	v_mfma_f32_16x16x32_bf16 v[18:21], v[188:191], v[212:215], v[18:21]
	v_mfma_f32_16x16x32_bf16 v[6:9], v[180:183], v[220:223], v[6:9]
	v_mfma_f32_16x16x32_bf16 v[2:5], v[188:191], v[220:223], v[2:5]
	s_setprio 0
	s_barrier
	s_add_i32 s94, 0, 0x18000
	v_add_u32_e32 v138, s94, v141
	s_add_i32 s95, 0, 0x1c000
	ds_read_b128 v[152:155], v138
	ds_read_b128 v[164:167], v138 offset:1024
	ds_read_b128 v[168:171], v138 offset:2048
	ds_read_b128 v[172:175], v138 offset:3072
	v_add_u32_e32 v138, s95, v141
	ds_read_b128 v[176:179], v138
	ds_read_b128 v[180:183], v138 offset:1024
	ds_read_b128 v[184:187], v138 offset:2048
	ds_read_b128 v[188:191], v138 offset:3072
	s_add_u32 s30, s46, 0xf0000
	s_addc_u32 s31, s47, 0
	s_mov_b32 m0, s60
	v_lshl_add_u64 v[232:233], s[30:31], 0, v[130:131]
	ds_read_b128 v[192:195], v158 offset:32768
	ds_read_b128 v[196:199], v158 offset:33792
	ds_read_b128 v[200:203], v158 offset:34816
	ds_read_b128 v[204:207], v158 offset:35840
	ds_read_b128 v[208:211], v158 offset:36864
	ds_read_b128 v[212:215], v158 offset:37888
	ds_read_b128 v[216:219], v158 offset:38912
	ds_read_b128 v[220:223], v158 offset:39936
	global_load_lds_dwordx4 v[232:233], off
	v_lshl_add_u64 v[232:233], s[30:31], 0, v[134:135]
	s_mov_b32 m0, s61
	s_nop 0
	global_load_lds_dwordx4 v[232:233], off
	s_waitcnt vmcnt(8)
	s_waitcnt lgkmcnt(0)
	s_barrier
	s_setprio 1
	s_waitcnt lgkmcnt(0)
	v_mfma_f32_16x16x32_bf16 v[126:129], v[152:155], v[192:195], v[126:129]
	v_mfma_f32_16x16x32_bf16 v[122:125], v[168:171], v[192:195], v[122:125]
	v_mfma_f32_16x16x32_bf16 v[110:113], v[152:155], v[200:203], v[110:113]
	v_mfma_f32_16x16x32_bf16 v[106:109], v[168:171], v[200:203], v[106:109]
	v_mfma_f32_16x16x32_bf16 v[94:97], v[152:155], v[208:211], v[94:97]
	v_mfma_f32_16x16x32_bf16 v[90:93], v[168:171], v[208:211], v[90:93]
	v_mfma_f32_16x16x32_bf16 v[78:81], v[152:155], v[216:219], v[78:81]
	v_mfma_f32_16x16x32_bf16 v[74:77], v[168:171], v[216:219], v[74:77]
	v_mfma_f32_16x16x32_bf16 v[126:129], v[164:167], v[196:199], v[126:129]
	v_mfma_f32_16x16x32_bf16 v[122:125], v[172:175], v[196:199], v[122:125]
	v_mfma_f32_16x16x32_bf16 v[110:113], v[164:167], v[204:207], v[110:113]
	v_mfma_f32_16x16x32_bf16 v[106:109], v[172:175], v[204:207], v[106:109]
	v_mfma_f32_16x16x32_bf16 v[94:97], v[164:167], v[212:215], v[94:97]
	v_mfma_f32_16x16x32_bf16 v[90:93], v[172:175], v[212:215], v[90:93]
	v_mfma_f32_16x16x32_bf16 v[78:81], v[164:167], v[220:223], v[78:81]
	v_mfma_f32_16x16x32_bf16 v[74:77], v[172:175], v[220:223], v[74:77]
	s_setprio 0
	s_setprio 1
	v_mfma_f32_16x16x32_bf16 v[118:121], v[176:179], v[192:195], v[118:121]
	v_mfma_f32_16x16x32_bf16 v[114:117], v[184:187], v[192:195], v[114:117]
	v_mfma_f32_16x16x32_bf16 v[102:105], v[176:179], v[200:203], v[102:105]
	v_mfma_f32_16x16x32_bf16 v[98:101], v[184:187], v[200:203], v[98:101]
	v_mfma_f32_16x16x32_bf16 v[86:89], v[176:179], v[208:211], v[86:89]
	v_mfma_f32_16x16x32_bf16 v[82:85], v[184:187], v[208:211], v[82:85]
	v_mfma_f32_16x16x32_bf16 v[70:73], v[176:179], v[216:219], v[70:73]
	v_mfma_f32_16x16x32_bf16 v[66:69], v[184:187], v[216:219], v[66:69]
	v_mfma_f32_16x16x32_bf16 v[118:121], v[180:183], v[196:199], v[118:121]
	v_mfma_f32_16x16x32_bf16 v[114:117], v[188:191], v[196:199], v[114:117]
	v_mfma_f32_16x16x32_bf16 v[102:105], v[180:183], v[204:207], v[102:105]
	v_mfma_f32_16x16x32_bf16 v[98:101], v[188:191], v[204:207], v[98:101]
	v_mfma_f32_16x16x32_bf16 v[86:89], v[180:183], v[212:215], v[86:89]
	v_mfma_f32_16x16x32_bf16 v[82:85], v[188:191], v[212:215], v[82:85]
	v_mfma_f32_16x16x32_bf16 v[70:73], v[180:183], v[220:223], v[70:73]
	v_mfma_f32_16x16x32_bf16 v[66:69], v[188:191], v[220:223], v[66:69]
	s_setprio 0
	s_barrier
; #define PG8_STAGE(bufoff, gbase, voff) do { _Pragma("unroll") for (int _i = 0; _i < 2; ++_i) \
;         __builtin_amdgcn_global_load_lds((const unsigned*)((const char*)(gbase) + (voff)[_i]), (LAS unsigned*)(lds + (bufoff) + ldsw + _i * 8192), 16, 0, 0); } while (0)
; #define PG8_LDA(dst, b, h) do { _Pragma("unroll") for (int m = 0; m < 4; ++m) _Pragma("unroll") for (int k = 0; k < 2; ++k) dst[m][k] = *(const LAS bf16x8*)(lds + PG8_SA(b, h) + aoff + m * 2048 + k * 1024); } while (0)
; #define PG8_MMA(ai, bj, At, Bt) do { __builtin_amdgcn_s_setprio(1); _Pragma("unroll") for (int m = 0; m < 4; ++m) _Pragma("unroll") for (int n = 0; n < 2; ++n) _Pragma("unroll") for (int k = 0; k < 2; ++k) \
;         acc[ai][bj][m][n] = __builtin_amdgcn_mfma_f32_16x16x32_bf16(Bt[n][k], At[m][k], acc[ai][bj][m][n], 0, 0, 0); __builtin_amdgcn_s_setprio(0); } while (0)
; #define PG8_WAIT_V(n) asm volatile("s_waitcnt vmcnt(" #n ")" ::: "memory")
; #define PG8_WAIT_L(n) asm volatile("s_waitcnt lgkmcnt(" #n ")" ::: "memory")
; #define PG8_BAR __builtin_amdgcn_s_barrier()
; #define PG8_SCHED __builtin_amdgcn_sched_barrier(0)
; template <class Epi, bool SEG = false>
; __device__ __forceinline__ void gemm_phase(LAS unsigned char* lds, const Gemm g, const StaticOrder& S, const Epi& E, const float* stat2 = nullptr) {
;     ...
;             PG8_LDA(At, 1, 1); PG8_STAGE(PG8_SB(1, 0), b3, voffB); PG8_STAGE(PG8_SB(1, 1), b3 + hstepB, voffB); PG8_STAGE(PG8_SA(1, 0), a3, voffA);
;             PG8_WAIT_V(8); PG8_WAIT_L(0); PG8_BAR; PG8_MMA(1, 0, At, B0); PG8_MMA(1, 1, At, B1); PG8_BAR; PG8_SCHED;
;         }
;         }
;         if (wr == 0) PG8_BAR;
;     __device__ __forceinline__ void operator()(const Acc& acc, const pg8::Unit& u, int wr, int wc, int fr, int fq) const {
;     ...
;                 const int row = row0 + ai * 128 + m * 16, b = row >> 12, s = row & 4095;
;                 const f32x4 s0 = *(const f32x4*)(stat + (size_t)row * 16 + 8), s1 = *(const f32x4*)(stat + (size_t)row * 16 + 12);
;                 const float rs = rsqrtf(((s0[0] + s0[1]) + (s0[2] + s0[3]) + (s1[0] + s1[1]) + (s1[2] + s1[3])) * (1.0f / 512.0f) + EPS);
	s_add_i32 s30, s94, s57
	v_lshl_add_u64 v[224:225], v[224:225], 0, s[20:21]
	s_mov_b32 m0, s30
	ds_read_b128 v[192:195], v158 offset:49152
	ds_read_b128 v[196:199], v158 offset:50176
	ds_read_b128 v[200:203], v158 offset:51200
	ds_read_b128 v[204:207], v158 offset:52224
	ds_read_b128 v[208:211], v158 offset:53248
	ds_read_b128 v[212:215], v158 offset:54272
	ds_read_b128 v[216:219], v158 offset:55296
	ds_read_b128 v[220:223], v158 offset:56320
	global_load_lds_dwordx4 v[224:225], off
	s_add_i32 m0, s30, 0x2000
	s_add_u32 s30, s44, 0x20080
	v_lshl_add_u64 v[224:225], v[226:227], 0, s[20:21]
	s_addc_u32 s31, s45, 0
	s_add_i32 s44, s95, s57
	global_load_lds_dwordx4 v[224:225], off
	v_lshl_add_u64 v[224:225], s[30:31], 0, v[132:133]
	s_mov_b32 m0, s44
	s_nop 0
	global_load_lds_dwordx4 v[224:225], off
	v_lshl_add_u64 v[224:225], s[30:31], 0, v[136:137]
	s_add_i32 m0, s44, 0x2000
	s_nop 0
	global_load_lds_dwordx4 v[224:225], off
	v_lshl_add_u64 v[224:225], v[228:229], 0, s[20:21]
	s_mov_b32 m0, s76
	s_nop 0
	global_load_lds_dwordx4 v[224:225], off
	v_lshl_add_u64 v[224:225], v[230:231], 0, s[20:21]
	s_mov_b32 m0, s77
	s_nop 0
	global_load_lds_dwordx4 v[224:225], off
	s_waitcnt vmcnt(8)
	s_waitcnt lgkmcnt(0)
	s_barrier
	s_setprio 1
	s_waitcnt lgkmcnt(0)
	v_mfma_f32_16x16x32_bf16 v[62:65], v[152:155], v[192:195], v[62:65]
	v_mfma_f32_16x16x32_bf16 v[58:61], v[168:171], v[192:195], v[58:61]
	v_mfma_f32_16x16x32_bf16 v[46:49], v[152:155], v[200:203], v[46:49]
	v_mfma_f32_16x16x32_bf16 v[42:45], v[168:171], v[200:203], v[42:45]
	v_mfma_f32_16x16x32_bf16 v[30:33], v[152:155], v[208:211], v[30:33]
	v_mfma_f32_16x16x32_bf16 v[26:29], v[168:171], v[208:211], v[26:29]
	v_mfma_f32_16x16x32_bf16 v[14:17], v[152:155], v[216:219], v[14:17]
	v_mfma_f32_16x16x32_bf16 v[10:13], v[168:171], v[216:219], v[10:13]
	v_mfma_f32_16x16x32_bf16 v[62:65], v[164:167], v[196:199], v[62:65]
	v_mfma_f32_16x16x32_bf16 v[58:61], v[172:175], v[196:199], v[58:61]
	v_mfma_f32_16x16x32_bf16 v[46:49], v[164:167], v[204:207], v[46:49]
	v_mfma_f32_16x16x32_bf16 v[42:45], v[172:175], v[204:207], v[42:45]
	v_mfma_f32_16x16x32_bf16 v[30:33], v[164:167], v[212:215], v[30:33]
	v_mfma_f32_16x16x32_bf16 v[26:29], v[172:175], v[212:215], v[26:29]
	v_mfma_f32_16x16x32_bf16 v[14:17], v[164:167], v[220:223], v[14:17]
	v_mfma_f32_16x16x32_bf16 v[10:13], v[172:175], v[220:223], v[10:13]
	s_setprio 0
	s_setprio 1
	v_mfma_f32_16x16x32_bf16 v[54:57], v[176:179], v[192:195], v[54:57]
	v_mfma_f32_16x16x32_bf16 v[50:53], v[184:187], v[192:195], v[50:53]
	v_mfma_f32_16x16x32_bf16 v[38:41], v[176:179], v[200:203], v[38:41]
	v_mfma_f32_16x16x32_bf16 v[34:37], v[184:187], v[200:203], v[34:37]
	v_mfma_f32_16x16x32_bf16 v[22:25], v[176:179], v[208:211], v[22:25]
	v_mfma_f32_16x16x32_bf16 v[18:21], v[184:187], v[208:211], v[18:21]
	v_mfma_f32_16x16x32_bf16 v[6:9], v[176:179], v[216:219], v[6:9]
	v_mfma_f32_16x16x32_bf16 v[2:5], v[184:187], v[216:219], v[2:5]
	v_mfma_f32_16x16x32_bf16 v[54:57], v[180:183], v[196:199], v[54:57]
	v_mfma_f32_16x16x32_bf16 v[50:53], v[188:191], v[196:199], v[50:53]
	v_mfma_f32_16x16x32_bf16 v[38:41], v[180:183], v[204:207], v[38:41]
	v_mfma_f32_16x16x32_bf16 v[34:37], v[188:191], v[204:207], v[34:37]
	v_mfma_f32_16x16x32_bf16 v[22:25], v[180:183], v[212:215], v[22:25]
	v_mfma_f32_16x16x32_bf16 v[18:21], v[188:191], v[212:215], v[18:21]
	v_mfma_f32_16x16x32_bf16 v[6:9], v[180:183], v[220:223], v[6:9]
	v_mfma_f32_16x16x32_bf16 v[2:5], v[188:191], v[220:223], v[2:5]
	s_setprio 0
	s_barrier
	s_add_i32 s93, s93, 2
	s_add_u32 s4, s4, 0x100
	s_addc_u32 s5, s5, 0
	s_add_u32 s91, s91, 0x100
	s_addc_u32 s92, s92, 0
	s_cmp_gt_u32 s93, 5
	s_cbranch_scc0 .LBB0_723
	s_and_b64 vcc, exec, s[22:23]
	s_cbranch_vccz .LBB0_726
	s_barrier
.LBB0_726:
	s_mov_b32 s32, 1
	s_lshl_b32 s4, s33, 8
	s_add_i32 s4, s4, s65
	v_or_b32_e32 v152, s4, v159
	v_ashrrev_i32_e32 v153, 31, v152
	v_lshlrev_b64 v[154:155], 6, v[152:153]
	v_lshl_add_u64 v[154:155], s[10:11], 0, v[154:155]
	global_load_dwordx4 v[164:167], v[154:155], off offset:32
	global_load_dwordx4 v[168:171], v[154:155], off offset:48
	global_load_dwordx4 v[186:189], v[154:155], off offset:1056
	global_load_dwordx4 v[190:193], v[154:155], off offset:1072
	global_load_dwordx4 v[194:197], v[154:155], off offset:2080
	global_load_dwordx4 v[198:201], v[154:155], off offset:2096
	global_load_dwordx4 v[202:205], v[154:155], off offset:3104
	global_load_dwordx4 v[206:209], v[154:155], off offset:3120
	v_add_co_u32_e32 v242, vcc, 0x2000, v154
	s_nop 1
	v_addc_co_u32_e32 v243, vcc, 0, v155, vcc
	global_load_dwordx4 v[210:213], v[242:243], off offset:32
	global_load_dwordx4 v[214:217], v[242:243], off offset:48
	global_load_dwordx4 v[218:221], v[242:243], off offset:1056
	global_load_dwordx4 v[222:225], v[242:243], off offset:1072
	global_load_dwordx4 v[226:229], v[242:243], off offset:2080
	global_load_dwordx4 v[230:233], v[242:243], off offset:2096
	global_load_dwordx4 v[234:237], v[242:243], off offset:3104
	global_load_dwordx4 v[238:241], v[242:243], off offset:3120
	s_ashr_i32 s5, s4, 9
	v_and_b32_e32 v153, 64, v160
	v_bitop3_b32 v163, s4, v162, v159 bitop3:0xc8
	s_and_b32 s4, s5, -8
	v_xor_b32_e32 v138, 1, v160
	v_add_u32_e32 v153, 64, v153
	s_add_i32 s4, s4, s89
	v_cmp_lt_i32_e32 vcc, v138, v153
	v_or_b32_e32 v172, 16, v152
	s_ashr_i32 s5, s4, 31
	v_cndmask_b32_e32 v138, v160, v138, vcc
	v_ashrrev_i32_e32 v173, 31, v172
	s_lshl_b64 s[4:5], s[4:5], 20
	v_lshlrev_b32_e32 v153, 2, v138
	v_lshlrev_b32_e32 v138, 8, v152
	v_lshlrev_b64 v[154:155], 6, v[172:173]
	s_add_u32 s44, s16, s4
	v_and_b32_e32 v138, 0xfcf00, v138
	v_lshl_add_u64 v[174:175], s[10:11], 0, v[154:155]
	v_mov_b32_e32 v155, s5
	v_or_b32_e32 v154, s4, v140
	s_addc_u32 s45, s17, s5
	v_lshl_add_u64 v[154:155], s[18:19], 0, v[154:155]
	v_lshl_add_u64 v[176:177], s[44:45], 0, v[138:139]
	v_lshlrev_b32_e32 v138, 1, v163
	v_lshl_add_u64 v[178:179], v[154:155], 0, v[138:139]
	v_add_co_u32_e32 v180, vcc, s62, v178
	v_mov_b32_e32 v151, v139
	s_nop 0
	v_addc_co_u32_e32 v181, vcc, 0, v179, vcc
	v_add_co_u32_e32 v182, vcc, s63, v178
	v_lshl_add_u64 v[176:177], v[176:177], 0, s[12:13]
	s_nop 0
	v_addc_co_u32_e32 v183, vcc, 0, v179, vcc
	v_lshl_add_u64 v[176:177], v[176:177], 0, v[150:151]
	s_waitcnt vmcnt(0)
; __device__ __forceinline__ unsigned cvt_pk_bf16(float lo, float hi) { f32x2 v = {lo, hi}; bf16x2_t b = __builtin_convertvector(v, bf16x2_t); return __builtin_bit_cast(unsigned, b); }
;     __device__ __forceinline__ void operator()(const Acc& acc, const pg8::Unit& u, int wr, int wc, int fr, int fq) const {
;     ...
;                 const int row = row0 + ai * 128 + m * 16, b = row >> 12, s = row & 4095;
;                 const f32x4 s0 = *(const f32x4*)(stat + (size_t)row * 16 + 8), s1 = *(const f32x4*)(stat + (size_t)row * 16 + 12);
;                 const float rs = rsqrtf(((s0[0] + s0[1]) + (s0[2] + s0[3]) + (s1[0] + s1[1]) + (s1[2] + s1[3])) * (1.0f / 512.0f) + EPS);
;                 const size_t bh = (size_t)(b * 8 + h);
;                 *(u32x4*)(KN + (bh * 4096 + s) * 128 + wc * 32 + 8 * fq) = pack8(acc[ai][0][m][0] * rs, acc[ai][0][m][1] * rs);
;                 { const unsigned q0 = cvt_pk_bf16(acc[ai][1][m][0][0] * rs, acc[ai][1][m][0][1] * rs), q1 = cvt_pk_bf16(acc[ai][1][m][0][2] * rs, acc[ai][1][m][0][3] * rs),
;                                  q2 = cvt_pk_bf16(acc[ai][1][m][1][0] * rs, acc[ai][1][m][1][1] * rs), q3 = cvt_pk_bf16(acc[ai][1][m][1][2] * rs, acc[ai][1][m][1][3] * rs);
;                   const bool odd = fr & 1;
;                   const unsigned mine0 = odd ? q2 : q0, mine1 = odd ? q3 : q1, send0 = odd ? q0 : q2, send1 = odd ? q1 : q3;
;                   const unsigned oth0 = (unsigned)__shfl_xor((int)send0, 1), oth1 = (unsigned)__shfl_xor((int)send1, 1);
;                   const unsigned lo0 = odd ? oth0 : mine0, hi0 = odd ? mine0 : oth0, lo1 = odd ? oth1 : mine1, hi1 = odd ? mine1 : oth1;
;                   unsigned* vp = (unsigned*)(VT + (bh * 128 + wc * 32 + 8 * fq + (odd ? 4 : 0)) * 4096 + (s & ~1));
;                   vp[0 * 2048] = (lo0 & 0xffffu) | (hi0 << 16); vp[1 * 2048] = (lo0 >> 16) | (hi0 & 0xffff0000u);
;                   vp[2 * 2048] = (lo1 & 0xffffu) | (hi1 << 16); vp[3 * 2048] = (lo1 >> 16) | (hi1 & 0xffff0000u); }
	v_mov_b32_e32 v184, v165
	v_mov_b32_e32 v185, v166
	v_mov_b32_e32 v165, v167
	v_mov_b32_e32 v166, v170
	v_mov_b32_e32 v167, v168
	v_mov_b32_e32 v168, v171
	v_pk_add_f32 v[164:165], v[184:185], v[164:165]
	v_pk_add_f32 v[166:167], v[166:167], v[168:169]
	v_add_f32_e32 v138, v164, v165
	v_add_f32_e32 v138, v138, v167
	v_add_f32_e32 v138, v166, v138
	v_fmamk_f32 v138, v138, 0x3b000000, v161
	v_mul_f32_e32 v163, 0x4b800000, v138
	v_cmp_gt_f32_e32 vcc, s81, v138
	v_add_co_u32_e64 v164, s[4:5], s64, v178
	s_nop 0
	v_cndmask_b32_e32 v138, v138, v163, vcc
	v_rsq_f32_e32 v138, v138
	v_addc_co_u32_e64 v165, s[4:5], 0, v179, s[4:5]
	v_mul_f32_e32 v163, 0x45800000, v138
	v_cndmask_b32_e32 v138, v138, v163, vcc
	v_pk_mul_f32 v[118:119], v[118:119], v[138:139] op_sel_hi:[1,0]
	v_pk_mul_f32 v[120:121], v[120:121], v[138:139] op_sel_hi:[1,0]
	v_pk_mul_f32 v[166:167], v[114:115], v[138:139] op_sel_hi:[1,0]
	v_pk_mul_f32 v[168:169], v[116:117], v[138:139] op_sel_hi:[1,0]
	v_cvt_pk_bf16_f32 v118, v118, v119
	v_cvt_pk_bf16_f32 v119, v120, v121
	v_cvt_pk_bf16_f32 v120, v166, v167
	v_pk_mul_f32 v[122:123], v[122:123], v[138:139] op_sel_hi:[1,0]
	v_cvt_pk_bf16_f32 v121, v168, v169
	v_cndmask_b32_e64 v117, v118, v120, s[0:1]
	v_cvt_pk_bf16_f32 v116, v122, v123
	ds_bpermute_b32 v122, v153, v117
	v_cndmask_b32_e64 v117, v119, v121, s[0:1]
	ds_bpermute_b32 v123, v153, v117
	v_pk_mul_f32 v[128:129], v[128:129], v[138:139] op_sel_hi:[1,0]
	v_pk_mul_f32 v[126:127], v[126:127], v[138:139] op_sel_hi:[1,0]
	v_pk_mul_f32 v[124:125], v[124:125], v[138:139] op_sel_hi:[1,0]
	v_cvt_pk_bf16_f32 v114, v126, v127
	v_cvt_pk_bf16_f32 v115, v128, v129
	v_cvt_pk_bf16_f32 v117, v124, v125
	global_store_dwordx4 v[176:177], v[114:117], off
	v_lshlrev_b32_e32 v126, 8, v172
	v_bitop3_b32 v128, v152, s84, 16 bitop3:0xc8
	s_waitcnt lgkmcnt(1)
	v_cndmask_b32_e64 v115, v120, v122, s[0:1]
	v_cndmask_b32_e64 v114, v122, v118, s[0:1]
	s_waitcnt lgkmcnt(0)
	v_cndmask_b32_e64 v116, v123, v119, s[0:1]
	v_cndmask_b32_e64 v117, v121, v123, s[0:1]
	v_lshlrev_b32_e32 v118, 16, v115
	v_lshrrev_b32_e32 v119, 16, v114
	v_lshlrev_b32_e32 v120, 16, v117
	v_lshrrev_b32_e32 v121, 16, v116
	v_and_or_b32 v114, v114, s82, v118
	v_and_or_b32 v115, v115, s83, v119
	v_and_or_b32 v116, v116, s82, v120
	v_and_or_b32 v117, v117, s83, v121
	global_store_dword v[178:179], v114, off
	global_store_dword v[180:181], v115, off
	global_store_dword v[182:183], v116, off
	global_store_dword v[164:165], v117, off
	v_and_b32_e32 v138, 0xfdf00, v126
	v_lshl_add_u64 v[126:127], s[44:45], 0, v[138:139]
	v_lshlrev_b32_e32 v138, 1, v128
	v_lshl_add_u64 v[128:129], v[154:155], 0, v[138:139]
	v_add_co_u32_e32 v164, vcc, s62, v128
	v_lshl_add_u64 v[126:127], v[126:127], 0, s[12:13]
	s_nop 0
	v_addc_co_u32_e32 v165, vcc, 0, v129, vcc
	v_add_co_u32_e32 v166, vcc, s63, v128
	v_lshl_add_u64 v[126:127], v[126:127], 0, v[150:151]
	s_nop 0
	v_addc_co_u32_e32 v167, vcc, 0, v129, vcc
	v_or_b32_e32 v122, 32, v152
	v_ashrrev_i32_e32 v123, 31, v122
	v_lshlrev_b64 v[124:125], 6, v[122:123]
	v_lshl_add_u64 v[124:125], s[10:11], 0, v[124:125]
	v_mov_b32_e32 v114, v186
	v_mov_b32_e32 v115, v187
	v_mov_b32_e32 v116, v188
	v_mov_b32_e32 v117, v189
	v_mov_b32_e32 v168, v115
	v_mov_b32_e32 v169, v116
	v_mov_b32_e32 v115, v117
	v_mov_b32_e32 v118, v190
	v_mov_b32_e32 v119, v191
	v_mov_b32_e32 v120, v192
	v_mov_b32_e32 v121, v193
	v_mov_b32_e32 v116, v120
	v_mov_b32_e32 v117, v118
	v_mov_b32_e32 v118, v121
	v_pk_add_f32 v[114:115], v[168:169], v[114:115]
	v_pk_add_f32 v[116:117], v[116:117], v[118:119]
	v_add_f32_e32 v114, v114, v115
	v_add_f32_e32 v114, v114, v117
	v_add_f32_e32 v114, v116, v114
	v_fmamk_f32 v114, v114, 0x3b000000, v161
	v_mul_f32_e32 v115, 0x4b800000, v114
	v_cmp_gt_f32_e32 vcc, s81, v114
	s_nop 1
	v_cndmask_b32_e32 v114, v114, v115, vcc
	v_rsq_f32_e32 v116, v114
	v_add_co_u32_e64 v114, s[4:5], s64, v128
	v_mul_f32_e32 v117, 0x45800000, v116
	v_cndmask_b32_e32 v116, v116, v117, vcc
	v_pk_mul_f32 v[102:103], v[102:103], v[116:117] op_sel_hi:[1,0]
	v_pk_mul_f32 v[104:105], v[104:105], v[116:117] op_sel_hi:[1,0]
	v_pk_mul_f32 v[118:119], v[98:99], v[116:117] op_sel_hi:[1,0]
	v_pk_mul_f32 v[112:113], v[112:113], v[116:117] op_sel_hi:[1,0]
	v_pk_mul_f32 v[110:111], v[110:111], v[116:117] op_sel_hi:[1,0]
	v_pk_mul_f32 v[108:109], v[108:109], v[116:117] op_sel_hi:[1,0]
	v_pk_mul_f32 v[106:107], v[106:107], v[116:117] op_sel_hi:[1,0]
	v_pk_mul_f32 v[116:117], v[100:101], v[116:117] op_sel_hi:[1,0]
	v_cvt_pk_bf16_f32 v102, v102, v103
	v_cvt_pk_bf16_f32 v103, v104, v105
	v_cvt_pk_bf16_f32 v104, v118, v119
	v_cvt_pk_bf16_f32 v105, v116, v117
	v_cndmask_b32_e64 v101, v102, v104, s[0:1]
	v_cvt_pk_bf16_f32 v100, v106, v107
	ds_bpermute_b32 v106, v153, v101
	v_cndmask_b32_e64 v101, v103, v105, s[0:1]
	ds_bpermute_b32 v107, v153, v101
	v_cvt_pk_bf16_f32 v98, v110, v111
	v_cvt_pk_bf16_f32 v99, v112, v113
	v_cvt_pk_bf16_f32 v101, v108, v109
	global_store_dwordx4 v[126:127], v[98:101], off
	v_addc_co_u32_e64 v115, s[4:5], 0, v129, s[4:5]
	s_waitcnt lgkmcnt(1)
	v_cndmask_b32_e64 v99, v104, v106, s[0:1]
	v_cndmask_b32_e64 v98, v106, v102, s[0:1]
	s_waitcnt lgkmcnt(0)
; __device__ __forceinline__ unsigned cvt_pk_bf16(float lo, float hi) { f32x2 v = {lo, hi}; bf16x2_t b = __builtin_convertvector(v, bf16x2_t); return __builtin_bit_cast(unsigned, b); }
;     __device__ __forceinline__ void operator()(const Acc& acc, const pg8::Unit& u, int wr, int wc, int fr, int fq) const {
;     ...
;                 const int row = row0 + ai * 128 + m * 16, b = row >> 12, s = row & 4095;
;                 const f32x4 s0 = *(const f32x4*)(stat + (size_t)row * 16 + 8), s1 = *(const f32x4*)(stat + (size_t)row * 16 + 12);
;                 const float rs = rsqrtf(((s0[0] + s0[1]) + (s0[2] + s0[3]) + (s1[0] + s1[1]) + (s1[2] + s1[3])) * (1.0f / 512.0f) + EPS);
;                 const size_t bh = (size_t)(b * 8 + h);
;                 *(u32x4*)(KN + (bh * 4096 + s) * 128 + wc * 32 + 8 * fq) = pack8(acc[ai][0][m][0] * rs, acc[ai][0][m][1] * rs);
;                 { const unsigned q0 = cvt_pk_bf16(acc[ai][1][m][0][0] * rs, acc[ai][1][m][0][1] * rs), q1 = cvt_pk_bf16(acc[ai][1][m][0][2] * rs, acc[ai][1][m][0][3] * rs),
;                                  q2 = cvt_pk_bf16(acc[ai][1][m][1][0] * rs, acc[ai][1][m][1][1] * rs), q3 = cvt_pk_bf16(acc[ai][1][m][1][2] * rs, acc[ai][1][m][1][3] * rs);
;                   const bool odd = fr & 1;
;                   const unsigned mine0 = odd ? q2 : q0, mine1 = odd ? q3 : q1, send0 = odd ? q0 : q2, send1 = odd ? q1 : q3;
;                   const unsigned oth0 = (unsigned)__shfl_xor((int)send0, 1), oth1 = (unsigned)__shfl_xor((int)send1, 1);
;                   const unsigned lo0 = odd ? oth0 : mine0, hi0 = odd ? mine0 : oth0, lo1 = odd ? oth1 : mine1, hi1 = odd ? mine1 : oth1;
;                   unsigned* vp = (unsigned*)(VT + (bh * 128 + wc * 32 + 8 * fq + (odd ? 4 : 0)) * 4096 + (s & ~1));
;                   vp[0 * 2048] = (lo0 & 0xffffu) | (hi0 << 16); vp[1 * 2048] = (lo0 >> 16) | (hi0 & 0xffff0000u);
;                   vp[2 * 2048] = (lo1 & 0xffffu) | (hi1 << 16); vp[3 * 2048] = (lo1 >> 16) | (hi1 & 0xffff0000u); }
	v_cndmask_b32_e64 v100, v107, v103, s[0:1]
	v_cndmask_b32_e64 v101, v105, v107, s[0:1]
	v_lshlrev_b32_e32 v102, 16, v99
	v_lshrrev_b32_e32 v103, 16, v98
	v_lshlrev_b32_e32 v104, 16, v101
	v_lshrrev_b32_e32 v105, 16, v100
	v_and_or_b32 v98, v98, s82, v102
	v_and_or_b32 v99, v99, s83, v103
	v_and_or_b32 v100, v100, s82, v104
	v_and_or_b32 v101, v101, s83, v105
	global_store_dword v[128:129], v98, off
	global_store_dword v[164:165], v99, off
	global_store_dword v[166:167], v100, off
	global_store_dword v[114:115], v101, off
	v_lshlrev_b32_e32 v110, 8, v122
	v_bitop3_b32 v112, v152, s85, 32 bitop3:0xc8
	v_and_b32_e32 v138, 0xfef00, v110
	v_lshl_add_u64 v[110:111], s[44:45], 0, v[138:139]
	v_lshlrev_b32_e32 v138, 1, v112
	v_lshl_add_u64 v[112:113], v[154:155], 0, v[138:139]
	v_add_co_u32_e32 v114, vcc, s62, v112
	v_lshl_add_u64 v[110:111], v[110:111], 0, s[12:13]
	s_nop 0
	v_addc_co_u32_e32 v115, vcc, 0, v113, vcc
	v_add_co_u32_e32 v116, vcc, s63, v112
	v_lshl_add_u64 v[110:111], v[110:111], 0, v[150:151]
	s_nop 0
	v_addc_co_u32_e32 v117, vcc, 0, v113, vcc
	v_or_b32_e32 v106, 48, v152
	v_ashrrev_i32_e32 v107, 31, v106
	v_lshlrev_b64 v[108:109], 6, v[106:107]
	v_lshl_add_u64 v[108:109], s[10:11], 0, v[108:109]
	v_mov_b32_e32 v98, v194
	v_mov_b32_e32 v99, v195
	v_mov_b32_e32 v100, v196
	v_mov_b32_e32 v101, v197
	v_mov_b32_e32 v118, v99
	v_mov_b32_e32 v119, v100
	v_mov_b32_e32 v99, v101
	v_mov_b32_e32 v102, v198
	v_mov_b32_e32 v103, v199
	v_mov_b32_e32 v104, v200
	v_mov_b32_e32 v105, v201
	v_mov_b32_e32 v100, v104
	v_mov_b32_e32 v101, v102
	v_mov_b32_e32 v102, v105
	v_pk_add_f32 v[98:99], v[118:119], v[98:99]
	v_pk_add_f32 v[100:101], v[100:101], v[102:103]
	v_add_f32_e32 v98, v98, v99
	v_add_f32_e32 v98, v98, v101
	v_add_f32_e32 v98, v100, v98
	v_fmamk_f32 v98, v98, 0x3b000000, v161
	v_mul_f32_e32 v99, 0x4b800000, v98
	v_cmp_gt_f32_e32 vcc, s81, v98
	s_nop 1
	v_cndmask_b32_e32 v98, v98, v99, vcc
	v_rsq_f32_e32 v100, v98
	v_add_co_u32_e64 v98, s[4:5], s64, v112
	v_mul_f32_e32 v101, 0x45800000, v100
	v_cndmask_b32_e32 v100, v100, v101, vcc
	v_pk_mul_f32 v[86:87], v[86:87], v[100:101] op_sel_hi:[1,0]
	v_pk_mul_f32 v[88:89], v[88:89], v[100:101] op_sel_hi:[1,0]
	v_pk_mul_f32 v[102:103], v[82:83], v[100:101] op_sel_hi:[1,0]
	v_pk_mul_f32 v[96:97], v[96:97], v[100:101] op_sel_hi:[1,0]
	v_pk_mul_f32 v[94:95], v[94:95], v[100:101] op_sel_hi:[1,0]
	v_pk_mul_f32 v[92:93], v[92:93], v[100:101] op_sel_hi:[1,0]
	v_pk_mul_f32 v[90:91], v[90:91], v[100:101] op_sel_hi:[1,0]
	v_pk_mul_f32 v[100:101], v[84:85], v[100:101] op_sel_hi:[1,0]
	v_cvt_pk_bf16_f32 v86, v86, v87
	v_cvt_pk_bf16_f32 v87, v88, v89
	v_cvt_pk_bf16_f32 v88, v102, v103
	v_cvt_pk_bf16_f32 v89, v100, v101
	v_cndmask_b32_e64 v85, v86, v88, s[0:1]
	v_cvt_pk_bf16_f32 v84, v90, v91
	ds_bpermute_b32 v90, v153, v85
	v_cndmask_b32_e64 v85, v87, v89, s[0:1]
	ds_bpermute_b32 v91, v153, v85
	v_cvt_pk_bf16_f32 v82, v94, v95
	v_cvt_pk_bf16_f32 v83, v96, v97
	v_cvt_pk_bf16_f32 v85, v92, v93
	global_store_dwordx4 v[110:111], v[82:85], off
	v_addc_co_u32_e64 v99, s[4:5], 0, v113, s[4:5]
	s_waitcnt lgkmcnt(1)
	v_cndmask_b32_e64 v83, v88, v90, s[0:1]
	v_cndmask_b32_e64 v82, v90, v86, s[0:1]
	s_waitcnt lgkmcnt(0)
	v_cndmask_b32_e64 v84, v91, v87, s[0:1]
	v_cndmask_b32_e64 v85, v89, v91, s[0:1]
	v_lshlrev_b32_e32 v86, 16, v83
	v_lshrrev_b32_e32 v87, 16, v82
	v_lshlrev_b32_e32 v88, 16, v85
	v_lshrrev_b32_e32 v89, 16, v84
	v_and_or_b32 v82, v82, s82, v86
	v_and_or_b32 v83, v83, s83, v87
	v_and_or_b32 v84, v84, s82, v88
	v_and_or_b32 v85, v85, s83, v89
	global_store_dword v[112:113], v82, off
	global_store_dword v[114:115], v83, off
	global_store_dword v[116:117], v84, off
	global_store_dword v[98:99], v85, off
	v_lshlrev_b32_e32 v94, 8, v106
	v_bitop3_b32 v96, v152, s86, 48 bitop3:0xc8
	v_and_b32_e32 v138, 0xfff00, v94
	v_lshl_add_u64 v[94:95], s[44:45], 0, v[138:139]
	v_lshlrev_b32_e32 v138, 1, v96
	v_lshl_add_u64 v[96:97], v[154:155], 0, v[138:139]
	v_add_co_u32_e32 v98, vcc, s62, v96
	v_lshl_add_u64 v[94:95], v[94:95], 0, s[12:13]
	s_nop 0
	v_addc_co_u32_e32 v99, vcc, 0, v97, vcc
	v_add_co_u32_e32 v100, vcc, s63, v96
	v_lshl_add_u64 v[94:95], v[94:95], 0, v[150:151]
	s_nop 0
	v_addc_co_u32_e32 v101, vcc, 0, v97, vcc
	v_add_u32_e32 v90, 0x80, v152
	v_ashrrev_i32_e32 v91, 31, v90
	v_lshlrev_b64 v[92:93], 6, v[90:91]
	v_lshl_add_u64 v[92:93], s[10:11], 0, v[92:93]
	v_mov_b32_e32 v82, v202
	v_mov_b32_e32 v83, v203
	v_mov_b32_e32 v84, v204
	v_mov_b32_e32 v85, v205
	v_mov_b32_e32 v102, v83
	v_mov_b32_e32 v103, v84
	v_mov_b32_e32 v83, v85
	v_mov_b32_e32 v86, v206
	v_mov_b32_e32 v87, v207
	v_mov_b32_e32 v88, v208
	v_mov_b32_e32 v89, v209
	v_mov_b32_e32 v84, v88
	v_mov_b32_e32 v85, v86
	v_mov_b32_e32 v86, v89
	v_pk_add_f32 v[82:83], v[102:103], v[82:83]
	v_pk_add_f32 v[84:85], v[84:85], v[86:87]
	v_add_f32_e32 v82, v82, v83
	v_add_f32_e32 v82, v82, v85
	v_add_f32_e32 v82, v84, v82
	v_fmamk_f32 v82, v82, 0x3b000000, v161
	v_mul_f32_e32 v83, 0x4b800000, v82
	v_cmp_gt_f32_e32 vcc, s81, v82
	s_nop 1
	v_cndmask_b32_e32 v82, v82, v83, vcc
	v_rsq_f32_e32 v84, v82
	v_add_co_u32_e64 v82, s[4:5], s64, v96
	v_mul_f32_e32 v85, 0x45800000, v84
	v_cndmask_b32_e32 v84, v84, v85, vcc
	v_pk_mul_f32 v[70:71], v[70:71], v[84:85] op_sel_hi:[1,0]
	v_pk_mul_f32 v[72:73], v[72:73], v[84:85] op_sel_hi:[1,0]
	v_pk_mul_f32 v[86:87], v[66:67], v[84:85] op_sel_hi:[1,0]
	v_pk_mul_f32 v[80:81], v[80:81], v[84:85] op_sel_hi:[1,0]
	v_pk_mul_f32 v[78:79], v[78:79], v[84:85] op_sel_hi:[1,0]
	v_pk_mul_f32 v[76:77], v[76:77], v[84:85] op_sel_hi:[1,0]
	v_pk_mul_f32 v[74:75], v[74:75], v[84:85] op_sel_hi:[1,0]
	v_pk_mul_f32 v[84:85], v[68:69], v[84:85] op_sel_hi:[1,0]
	v_cvt_pk_bf16_f32 v70, v70, v71
	v_cvt_pk_bf16_f32 v71, v72, v73
	v_cvt_pk_bf16_f32 v72, v86, v87
	v_cvt_pk_bf16_f32 v73, v84, v85
	v_cndmask_b32_e64 v69, v70, v72, s[0:1]
	v_cvt_pk_bf16_f32 v68, v74, v75
	ds_bpermute_b32 v74, v153, v69
	v_cndmask_b32_e64 v69, v71, v73, s[0:1]
	ds_bpermute_b32 v75, v153, v69
	v_cvt_pk_bf16_f32 v66, v78, v79
	v_cvt_pk_bf16_f32 v67, v80, v81
	v_cvt_pk_bf16_f32 v69, v76, v77
	global_store_dwordx4 v[94:95], v[66:69], off
	v_addc_co_u32_e64 v83, s[4:5], 0, v97, s[4:5]
	s_waitcnt lgkmcnt(1)
; __device__ __forceinline__ unsigned cvt_pk_bf16(float lo, float hi) { f32x2 v = {lo, hi}; bf16x2_t b = __builtin_convertvector(v, bf16x2_t); return __builtin_bit_cast(unsigned, b); }
;     __device__ __forceinline__ void operator()(const Acc& acc, const pg8::Unit& u, int wr, int wc, int fr, int fq) const {
;     ...
;                 const int row = row0 + ai * 128 + m * 16, b = row >> 12, s = row & 4095;
;                 const f32x4 s0 = *(const f32x4*)(stat + (size_t)row * 16 + 8), s1 = *(const f32x4*)(stat + (size_t)row * 16 + 12);
;                 const float rs = rsqrtf(((s0[0] + s0[1]) + (s0[2] + s0[3]) + (s1[0] + s1[1]) + (s1[2] + s1[3])) * (1.0f / 512.0f) + EPS);
;                 const size_t bh = (size_t)(b * 8 + h);
;                 *(u32x4*)(KN + (bh * 4096 + s) * 128 + wc * 32 + 8 * fq) = pack8(acc[ai][0][m][0] * rs, acc[ai][0][m][1] * rs);
;                 { const unsigned q0 = cvt_pk_bf16(acc[ai][1][m][0][0] * rs, acc[ai][1][m][0][1] * rs), q1 = cvt_pk_bf16(acc[ai][1][m][0][2] * rs, acc[ai][1][m][0][3] * rs),
;                                  q2 = cvt_pk_bf16(acc[ai][1][m][1][0] * rs, acc[ai][1][m][1][1] * rs), q3 = cvt_pk_bf16(acc[ai][1][m][1][2] * rs, acc[ai][1][m][1][3] * rs);
;                   const bool odd = fr & 1;
;                   const unsigned mine0 = odd ? q2 : q0, mine1 = odd ? q3 : q1, send0 = odd ? q0 : q2, send1 = odd ? q1 : q3;
;                   const unsigned oth0 = (unsigned)__shfl_xor((int)send0, 1), oth1 = (unsigned)__shfl_xor((int)send1, 1);
;                   const unsigned lo0 = odd ? oth0 : mine0, hi0 = odd ? mine0 : oth0, lo1 = odd ? oth1 : mine1, hi1 = odd ? mine1 : oth1;
;                   unsigned* vp = (unsigned*)(VT + (bh * 128 + wc * 32 + 8 * fq + (odd ? 4 : 0)) * 4096 + (s & ~1));
;                   vp[0 * 2048] = (lo0 & 0xffffu) | (hi0 << 16); vp[1 * 2048] = (lo0 >> 16) | (hi0 & 0xffff0000u);
;                   vp[2 * 2048] = (lo1 & 0xffffu) | (hi1 << 16); vp[3 * 2048] = (lo1 >> 16) | (hi1 & 0xffff0000u); }
	v_cndmask_b32_e64 v67, v72, v74, s[0:1]
	v_cndmask_b32_e64 v66, v74, v70, s[0:1]
	s_waitcnt lgkmcnt(0)
	v_cndmask_b32_e64 v68, v75, v71, s[0:1]
	v_cndmask_b32_e64 v69, v73, v75, s[0:1]
	v_lshlrev_b32_e32 v70, 16, v67
	v_lshrrev_b32_e32 v71, 16, v66
	v_lshlrev_b32_e32 v72, 16, v69
	v_lshrrev_b32_e32 v73, 16, v68
	v_and_or_b32 v66, v66, s82, v70
	v_and_or_b32 v67, v67, s83, v71
	v_and_or_b32 v68, v68, s82, v72
	v_and_or_b32 v69, v69, s83, v73
	global_store_dword v[96:97], v66, off
	global_store_dword v[98:99], v67, off
	global_store_dword v[100:101], v68, off
	global_store_dword v[82:83], v69, off
	v_ashrrev_i32_e32 v66, 9, v90
	v_add_u32_e32 v78, 0x90, v152
	v_and_b32_e32 v68, -8, v66
	v_ashrrev_i32_e32 v79, 31, v78
	v_add_u32_e32 v68, s89, v68
	v_lshlrev_b64 v[66:67], 6, v[78:79]
	v_ashrrev_i32_e32 v69, 31, v68
	v_lshlrev_b32_e32 v84, 8, v90
	v_lshl_add_u64 v[80:81], s[10:11], 0, v[66:67]
	v_lshlrev_b64 v[66:67], 20, v[68:69]
	v_and_b32_e32 v85, 0xfce, v90
	v_or_b32_e32 v82, v66, v140
	v_mov_b32_e32 v83, v67
	v_lshl_add_u64 v[68:69], s[16:17], 0, v[66:67]
	v_and_b32_e32 v138, 0xfcf00, v84
	v_lshl_add_u64 v[66:67], s[18:19], 0, v[82:83]
	v_lshl_add_u64 v[82:83], v[68:69], 0, v[138:139]
	v_lshlrev_b32_e32 v138, 1, v85
	v_lshl_add_u64 v[84:85], v[66:67], 0, v[138:139]
	v_add_co_u32_e32 v86, vcc, s62, v84
	v_lshl_add_u64 v[82:83], v[82:83], 0, s[12:13]
	s_nop 0
	v_addc_co_u32_e32 v87, vcc, 0, v85, vcc
	v_add_co_u32_e32 v88, vcc, s63, v84
	v_lshl_add_u64 v[82:83], v[82:83], 0, v[150:151]
	s_nop 0
	v_addc_co_u32_e32 v89, vcc, 0, v85, vcc
	v_mov_b32_e32 v70, v210
	v_mov_b32_e32 v71, v211
	v_mov_b32_e32 v72, v212
	v_mov_b32_e32 v73, v213
	v_mov_b32_e32 v90, v71
	v_mov_b32_e32 v91, v72
	v_mov_b32_e32 v71, v73
	v_mov_b32_e32 v74, v214
	v_mov_b32_e32 v75, v215
	v_mov_b32_e32 v76, v216
	v_mov_b32_e32 v77, v217
	v_mov_b32_e32 v72, v76
	v_mov_b32_e32 v73, v74
	v_mov_b32_e32 v74, v77
	v_pk_add_f32 v[70:71], v[90:91], v[70:71]
	v_pk_add_f32 v[72:73], v[72:73], v[74:75]
	v_add_f32_e32 v70, v70, v71
	v_add_f32_e32 v70, v70, v73
	v_add_f32_e32 v70, v72, v70
	v_fmamk_f32 v70, v70, 0x3b000000, v161
	v_mul_f32_e32 v71, 0x4b800000, v70
	v_cmp_gt_f32_e32 vcc, s81, v70
	s_nop 1
	v_cndmask_b32_e32 v70, v70, v71, vcc
	v_rsq_f32_e32 v72, v70
	v_add_co_u32_e64 v70, s[4:5], s64, v84
	v_mul_f32_e32 v73, 0x45800000, v72
	v_cndmask_b32_e32 v72, v72, v73, vcc
	v_pk_mul_f32 v[54:55], v[54:55], v[72:73] op_sel_hi:[1,0]
	v_pk_mul_f32 v[56:57], v[56:57], v[72:73] op_sel_hi:[1,0]
	v_pk_mul_f32 v[74:75], v[50:51], v[72:73] op_sel_hi:[1,0]
	v_pk_mul_f32 v[64:65], v[64:65], v[72:73] op_sel_hi:[1,0]
	v_pk_mul_f32 v[62:63], v[62:63], v[72:73] op_sel_hi:[1,0]
	v_pk_mul_f32 v[60:61], v[60:61], v[72:73] op_sel_hi:[1,0]
	v_pk_mul_f32 v[58:59], v[58:59], v[72:73] op_sel_hi:[1,0]
	v_pk_mul_f32 v[72:73], v[52:53], v[72:73] op_sel_hi:[1,0]
	v_cvt_pk_bf16_f32 v54, v54, v55
	v_cvt_pk_bf16_f32 v55, v56, v57
	v_cvt_pk_bf16_f32 v56, v74, v75
	v_cvt_pk_bf16_f32 v57, v72, v73
	v_cndmask_b32_e64 v53, v54, v56, s[0:1]
	v_cvt_pk_bf16_f32 v52, v58, v59
	ds_bpermute_b32 v58, v153, v53
	v_cndmask_b32_e64 v53, v55, v57, s[0:1]
	ds_bpermute_b32 v59, v153, v53
	v_cvt_pk_bf16_f32 v50, v62, v63
	v_cvt_pk_bf16_f32 v51, v64, v65
	v_cvt_pk_bf16_f32 v53, v60, v61
	global_store_dwordx4 v[82:83], v[50:53], off
	v_addc_co_u32_e64 v71, s[4:5], 0, v85, s[4:5]
	s_waitcnt lgkmcnt(1)
	v_cndmask_b32_e64 v51, v56, v58, s[0:1]
	v_cndmask_b32_e64 v50, v58, v54, s[0:1]
	s_waitcnt lgkmcnt(0)
	v_cndmask_b32_e64 v52, v59, v55, s[0:1]
	v_cndmask_b32_e64 v53, v57, v59, s[0:1]
	v_lshlrev_b32_e32 v54, 16, v51
	v_lshrrev_b32_e32 v55, 16, v50
	v_lshlrev_b32_e32 v56, 16, v53
	v_lshrrev_b32_e32 v57, 16, v52
	v_and_or_b32 v50, v50, s82, v54
	v_and_or_b32 v51, v51, s83, v55
	v_and_or_b32 v52, v52, s82, v56
	v_and_or_b32 v53, v53, s83, v57
	global_store_dword v[84:85], v50, off
	global_store_dword v[86:87], v51, off
	global_store_dword v[88:89], v52, off
	global_store_dword v[70:71], v53, off
	v_lshlrev_b32_e32 v62, 8, v78
	v_and_b32_e32 v64, 0xfde, v78
	v_and_b32_e32 v138, 0xfdf00, v62
	v_lshl_add_u64 v[62:63], v[68:69], 0, v[138:139]
	v_lshlrev_b32_e32 v138, 1, v64
	v_lshl_add_u64 v[64:65], v[66:67], 0, v[138:139]
	v_add_co_u32_e32 v70, vcc, s62, v64
	v_lshl_add_u64 v[62:63], v[62:63], 0, s[12:13]
	s_nop 0
	v_addc_co_u32_e32 v71, vcc, 0, v65, vcc
	v_add_co_u32_e32 v72, vcc, s63, v64
	v_lshl_add_u64 v[62:63], v[62:63], 0, v[150:151]
	s_nop 0
	v_addc_co_u32_e32 v73, vcc, 0, v65, vcc
	v_add_u32_e32 v58, 0xa0, v152
	v_ashrrev_i32_e32 v59, 31, v58
	v_lshlrev_b64 v[60:61], 6, v[58:59]
	v_lshl_add_u64 v[60:61], s[10:11], 0, v[60:61]
	v_mov_b32_e32 v50, v218
	v_mov_b32_e32 v51, v219
	v_mov_b32_e32 v52, v220
	v_mov_b32_e32 v53, v221
	v_mov_b32_e32 v74, v51
	v_mov_b32_e32 v75, v52
	v_mov_b32_e32 v51, v53
	v_mov_b32_e32 v54, v222
	v_mov_b32_e32 v55, v223
	v_mov_b32_e32 v56, v224
	v_mov_b32_e32 v57, v225
	v_mov_b32_e32 v52, v56
	v_mov_b32_e32 v53, v54
	v_mov_b32_e32 v54, v57
	v_pk_add_f32 v[50:51], v[74:75], v[50:51]
	v_pk_add_f32 v[52:53], v[52:53], v[54:55]
	v_add_f32_e32 v50, v50, v51
	v_add_f32_e32 v50, v50, v53
	v_add_f32_e32 v50, v52, v50
	v_fmamk_f32 v50, v50, 0x3b000000, v161
	v_mul_f32_e32 v51, 0x4b800000, v50
	v_cmp_gt_f32_e32 vcc, s81, v50
	s_nop 1
	v_cndmask_b32_e32 v50, v50, v51, vcc
	v_rsq_f32_e32 v52, v50
	v_add_co_u32_e64 v50, s[4:5], s64, v64
	v_mul_f32_e32 v53, 0x45800000, v52
	v_cndmask_b32_e32 v52, v52, v53, vcc
	v_pk_mul_f32 v[38:39], v[38:39], v[52:53] op_sel_hi:[1,0]
	v_pk_mul_f32 v[40:41], v[40:41], v[52:53] op_sel_hi:[1,0]
	v_pk_mul_f32 v[54:55], v[34:35], v[52:53] op_sel_hi:[1,0]
	v_pk_mul_f32 v[48:49], v[48:49], v[52:53] op_sel_hi:[1,0]
	v_pk_mul_f32 v[46:47], v[46:47], v[52:53] op_sel_hi:[1,0]
	v_pk_mul_f32 v[44:45], v[44:45], v[52:53] op_sel_hi:[1,0]
	v_pk_mul_f32 v[42:43], v[42:43], v[52:53] op_sel_hi:[1,0]
	v_pk_mul_f32 v[52:53], v[36:37], v[52:53] op_sel_hi:[1,0]
	v_cvt_pk_bf16_f32 v38, v38, v39
	v_cvt_pk_bf16_f32 v39, v40, v41
	v_cvt_pk_bf16_f32 v40, v54, v55
	v_cvt_pk_bf16_f32 v41, v52, v53
	v_cndmask_b32_e64 v37, v38, v40, s[0:1]
	v_cvt_pk_bf16_f32 v36, v42, v43
	ds_bpermute_b32 v42, v153, v37
	v_cndmask_b32_e64 v37, v39, v41, s[0:1]
	ds_bpermute_b32 v43, v153, v37
	v_cvt_pk_bf16_f32 v34, v46, v47
	v_cvt_pk_bf16_f32 v35, v48, v49
	v_cvt_pk_bf16_f32 v37, v44, v45
	global_store_dwordx4 v[62:63], v[34:37], off
	v_addc_co_u32_e64 v51, s[4:5], 0, v65, s[4:5]
	s_waitcnt lgkmcnt(1)
; template <class Epi, bool SEG = false>
; __device__ __forceinline__ void gemm_phase(LAS unsigned char* lds, const Gemm g, const StaticOrder& S, const Epi& E, const float* stat2 = nullptr) {
;     ...
;         if (!has_next) break;
; #pragma unroll
;         for (int a = 0; a < 2; ++a)
; #pragma unroll
;             for (int b = 0; b < 2; ++b)
; #pragma unroll
;                 for (int m = 0; m < 4; ++m)
; #pragma unroll
;                     for (int n = 0; n < 2; ++n) acc[a][b][m][n] = (f32x4){0.f, 0.f, 0.f, 0.f};
;         cur = nxt; cA = nA; cB = nB; ++ui;
;     __device__ __forceinline__ void operator()(const Acc& acc, const pg8::Unit& u, int wr, int wc, int fr, int fq) const {
;     ...
;                 const int row = row0 + ai * 128 + m * 16, b = row >> 12, s = row & 4095;
;                 const f32x4 s0 = *(const f32x4*)(stat + (size_t)row * 16 + 8), s1 = *(const f32x4*)(stat + (size_t)row * 16 + 12);
;                 const float rs = rsqrtf(((s0[0] + s0[1]) + (s0[2] + s0[3]) + (s1[0] + s1[1]) + (s1[2] + s1[3])) * (1.0f / 512.0f) + EPS);
;                 const size_t bh = (size_t)(b * 8 + h);
;                 *(u32x4*)(KN + (bh * 4096 + s) * 128 + wc * 32 + 8 * fq) = pack8(acc[ai][0][m][0] * rs, acc[ai][0][m][1] * rs);
;                 { const unsigned q0 = cvt_pk_bf16(acc[ai][1][m][0][0] * rs, acc[ai][1][m][0][1] * rs), q1 = cvt_pk_bf16(acc[ai][1][m][0][2] * rs, acc[ai][1][m][0][3] * rs),
;                                  q2 = cvt_pk_bf16(acc[ai][1][m][1][0] * rs, acc[ai][1][m][1][1] * rs), q3 = cvt_pk_bf16(acc[ai][1][m][1][2] * rs, acc[ai][1][m][1][3] * rs);
;                   const bool odd = fr & 1;
;                   const unsigned mine0 = odd ? q2 : q0, mine1 = odd ? q3 : q1, send0 = odd ? q0 : q2, send1 = odd ? q1 : q3;
;                   const unsigned oth0 = (unsigned)__shfl_xor((int)send0, 1), oth1 = (unsigned)__shfl_xor((int)send1, 1);
;                   const unsigned lo0 = odd ? oth0 : mine0, hi0 = odd ? mine0 : oth0, lo1 = odd ? oth1 : mine1, hi1 = odd ? mine1 : oth1;
;                   unsigned* vp = (unsigned*)(VT + (bh * 128 + wc * 32 + 8 * fq + (odd ? 4 : 0)) * 4096 + (s & ~1));
;                   vp[0 * 2048] = (lo0 & 0xffffu) | (hi0 << 16); vp[1 * 2048] = (lo0 >> 16) | (hi0 & 0xffff0000u);
;                   vp[2 * 2048] = (lo1 & 0xffffu) | (hi1 << 16); vp[3 * 2048] = (lo1 >> 16) | (hi1 & 0xffff0000u); }
	v_cndmask_b32_e64 v35, v40, v42, s[0:1]
	v_cndmask_b32_e64 v34, v42, v38, s[0:1]
	s_waitcnt lgkmcnt(0)
	v_cndmask_b32_e64 v36, v43, v39, s[0:1]
	v_cndmask_b32_e64 v37, v41, v43, s[0:1]
	v_lshlrev_b32_e32 v38, 16, v35
	v_lshrrev_b32_e32 v39, 16, v34
	v_lshlrev_b32_e32 v40, 16, v37
	v_lshrrev_b32_e32 v41, 16, v36
	v_and_or_b32 v34, v34, s82, v38
	v_and_or_b32 v35, v35, s83, v39
	v_and_or_b32 v36, v36, s82, v40
	v_and_or_b32 v37, v37, s83, v41
	global_store_dword v[64:65], v34, off
	global_store_dword v[70:71], v35, off
	global_store_dword v[72:73], v36, off
	global_store_dword v[50:51], v37, off
	v_lshlrev_b32_e32 v46, 8, v58
	v_and_b32_e32 v48, 0xfee, v58
	v_and_b32_e32 v138, 0xfef00, v46
	v_lshl_add_u64 v[46:47], v[68:69], 0, v[138:139]
	v_lshlrev_b32_e32 v138, 1, v48
	v_lshl_add_u64 v[48:49], v[66:67], 0, v[138:139]
	v_add_co_u32_e32 v50, vcc, s62, v48
	v_lshl_add_u64 v[46:47], v[46:47], 0, s[12:13]
	s_nop 0
	v_addc_co_u32_e32 v51, vcc, 0, v49, vcc
	v_add_co_u32_e32 v52, vcc, s63, v48
	v_lshl_add_u64 v[46:47], v[46:47], 0, v[150:151]
	s_nop 0
	v_addc_co_u32_e32 v53, vcc, 0, v49, vcc
	v_add_u32_e32 v42, 0xb0, v152
	v_ashrrev_i32_e32 v43, 31, v42
	v_lshlrev_b64 v[44:45], 6, v[42:43]
	v_lshl_add_u64 v[44:45], s[10:11], 0, v[44:45]
	v_mov_b32_e32 v34, v226
	v_mov_b32_e32 v35, v227
	v_mov_b32_e32 v36, v228
	v_mov_b32_e32 v37, v229
	v_mov_b32_e32 v54, v35
	v_mov_b32_e32 v55, v36
	v_mov_b32_e32 v35, v37
	v_mov_b32_e32 v38, v230
	v_mov_b32_e32 v39, v231
	v_mov_b32_e32 v40, v232
	v_mov_b32_e32 v41, v233
	v_mov_b32_e32 v36, v40
	v_mov_b32_e32 v37, v38
	v_mov_b32_e32 v38, v41
	v_pk_add_f32 v[34:35], v[54:55], v[34:35]
	v_pk_add_f32 v[36:37], v[36:37], v[38:39]
	v_add_f32_e32 v34, v34, v35
	v_add_f32_e32 v34, v34, v37
	v_add_f32_e32 v34, v36, v34
	v_fmamk_f32 v34, v34, 0x3b000000, v161
	v_mul_f32_e32 v35, 0x4b800000, v34
	v_cmp_gt_f32_e32 vcc, s81, v34
	s_nop 1
	v_cndmask_b32_e32 v34, v34, v35, vcc
	v_rsq_f32_e32 v36, v34
	v_add_co_u32_e64 v34, s[4:5], s64, v48
	v_mul_f32_e32 v37, 0x45800000, v36
	v_cndmask_b32_e32 v36, v36, v37, vcc
	v_pk_mul_f32 v[22:23], v[22:23], v[36:37] op_sel_hi:[1,0]
	v_pk_mul_f32 v[24:25], v[24:25], v[36:37] op_sel_hi:[1,0]
	v_pk_mul_f32 v[38:39], v[18:19], v[36:37] op_sel_hi:[1,0]
	v_pk_mul_f32 v[32:33], v[32:33], v[36:37] op_sel_hi:[1,0]
	v_pk_mul_f32 v[30:31], v[30:31], v[36:37] op_sel_hi:[1,0]
	v_pk_mul_f32 v[28:29], v[28:29], v[36:37] op_sel_hi:[1,0]
	v_pk_mul_f32 v[26:27], v[26:27], v[36:37] op_sel_hi:[1,0]
	v_pk_mul_f32 v[36:37], v[20:21], v[36:37] op_sel_hi:[1,0]
	v_cvt_pk_bf16_f32 v22, v22, v23
	v_cvt_pk_bf16_f32 v23, v24, v25
	v_cvt_pk_bf16_f32 v24, v38, v39
	v_cvt_pk_bf16_f32 v25, v36, v37
	v_cndmask_b32_e64 v21, v22, v24, s[0:1]
	v_cvt_pk_bf16_f32 v20, v26, v27
	ds_bpermute_b32 v26, v153, v21
	v_cndmask_b32_e64 v21, v23, v25, s[0:1]
	ds_bpermute_b32 v27, v153, v21
	v_cvt_pk_bf16_f32 v18, v30, v31
	v_cvt_pk_bf16_f32 v19, v32, v33
	v_cvt_pk_bf16_f32 v21, v28, v29
	global_store_dwordx4 v[46:47], v[18:21], off
	v_addc_co_u32_e64 v35, s[4:5], 0, v49, s[4:5]
	s_waitcnt lgkmcnt(1)
	v_cndmask_b32_e64 v19, v24, v26, s[0:1]
	v_cndmask_b32_e64 v18, v26, v22, s[0:1]
	s_waitcnt lgkmcnt(0)
	v_cndmask_b32_e64 v20, v27, v23, s[0:1]
	v_cndmask_b32_e64 v21, v25, v27, s[0:1]
	v_lshlrev_b32_e32 v22, 16, v19
	v_lshrrev_b32_e32 v23, 16, v18
	v_lshlrev_b32_e32 v24, 16, v21
	v_lshrrev_b32_e32 v25, 16, v20
	v_and_or_b32 v18, v18, s82, v22
	v_and_or_b32 v19, v19, s83, v23
	v_and_or_b32 v20, v20, s82, v24
	v_and_or_b32 v21, v21, s83, v25
	global_store_dword v[48:49], v18, off
	global_store_dword v[50:51], v19, off
	global_store_dword v[52:53], v20, off
	global_store_dword v[34:35], v21, off
	v_lshlrev_b32_e32 v26, 8, v42
	v_and_b32_e32 v28, 0xffe, v42
	v_and_b32_e32 v138, 0xfff00, v26
	v_lshl_add_u64 v[26:27], v[68:69], 0, v[138:139]
	v_lshlrev_b32_e32 v138, 1, v28
	v_lshl_add_u64 v[28:29], v[66:67], 0, v[138:139]
	v_add_co_u32_e32 v30, vcc, s62, v28
	v_lshl_add_u64 v[26:27], v[26:27], 0, s[12:13]
	s_nop 0
	v_addc_co_u32_e32 v31, vcc, 0, v29, vcc
	v_add_co_u32_e32 v32, vcc, 0x4000, v28
	v_lshl_add_u64 v[26:27], v[26:27], 0, v[150:151]
	s_nop 0
	v_addc_co_u32_e32 v33, vcc, 0, v29, vcc
	v_add_co_u32_e32 v34, vcc, 0x6000, v28
	v_mov_b32_e32 v18, v234
	v_mov_b32_e32 v19, v235
	v_mov_b32_e32 v20, v236
	v_mov_b32_e32 v21, v237
	v_mov_b32_e32 v36, v19
	v_mov_b32_e32 v37, v20
	v_mov_b32_e32 v19, v21
	v_mov_b32_e32 v22, v238
	v_mov_b32_e32 v23, v239
	v_mov_b32_e32 v24, v240
	v_mov_b32_e32 v25, v241
	v_mov_b32_e32 v20, v24
	v_mov_b32_e32 v21, v22
	v_mov_b32_e32 v22, v25
	v_pk_add_f32 v[18:19], v[36:37], v[18:19]
	v_pk_add_f32 v[20:21], v[20:21], v[22:23]
	v_add_f32_e32 v18, v18, v19
	v_add_f32_e32 v18, v18, v21
	v_add_f32_e32 v18, v20, v18
	v_fmamk_f32 v18, v18, 0x3b000000, v161
	v_mul_f32_e32 v19, 0x4b800000, v18
	v_cmp_gt_f32_e64 s[4:5], s81, v18
	v_addc_co_u32_e32 v35, vcc, 0, v29, vcc
	s_nop 0
	v_cndmask_b32_e64 v18, v18, v19, s[4:5]
	v_rsq_f32_e32 v18, v18
	s_and_b64 vcc, exec, s[2:3]
	s_mov_b64 s[2:3], -1
	v_mul_f32_e32 v19, 0x45800000, v18
	v_cndmask_b32_e64 v18, v18, v19, s[4:5]
	v_pk_mul_f32 v[6:7], v[6:7], v[18:19] op_sel_hi:[1,0]
	v_pk_mul_f32 v[8:9], v[8:9], v[18:19] op_sel_hi:[1,0]
	v_pk_mul_f32 v[20:21], v[2:3], v[18:19] op_sel_hi:[1,0]
	v_pk_mul_f32 v[16:17], v[16:17], v[18:19] op_sel_hi:[1,0]
	v_pk_mul_f32 v[14:15], v[14:15], v[18:19] op_sel_hi:[1,0]
	v_pk_mul_f32 v[12:13], v[12:13], v[18:19] op_sel_hi:[1,0]
	v_pk_mul_f32 v[10:11], v[10:11], v[18:19] op_sel_hi:[1,0]
	v_pk_mul_f32 v[18:19], v[4:5], v[18:19] op_sel_hi:[1,0]
	v_cvt_pk_bf16_f32 v6, v6, v7
	v_cvt_pk_bf16_f32 v7, v8, v9
	v_cvt_pk_bf16_f32 v8, v20, v21
	v_cvt_pk_bf16_f32 v9, v18, v19
	v_cndmask_b32_e64 v5, v6, v8, s[0:1]
	v_cvt_pk_bf16_f32 v4, v10, v11
	ds_bpermute_b32 v10, v153, v5
	v_cndmask_b32_e64 v5, v7, v9, s[0:1]
	ds_bpermute_b32 v11, v153, v5
	v_cvt_pk_bf16_f32 v2, v14, v15
	v_cvt_pk_bf16_f32 v3, v16, v17
	v_cvt_pk_bf16_f32 v5, v12, v13
	global_store_dwordx4 v[26:27], v[2:5], off
	s_waitcnt lgkmcnt(1)
	s_nop 0
	v_cndmask_b32_e64 v3, v8, v10, s[0:1]
	v_cndmask_b32_e64 v2, v10, v6, s[0:1]
	s_waitcnt lgkmcnt(0)
	v_cndmask_b32_e64 v4, v11, v7, s[0:1]
	v_cndmask_b32_e64 v5, v9, v11, s[0:1]
	v_lshlrev_b32_e32 v6, 16, v3
	v_lshrrev_b32_e32 v7, 16, v2
	v_lshlrev_b32_e32 v8, 16, v5
	v_lshrrev_b32_e32 v9, 16, v4
	v_and_or_b32 v2, v2, s82, v6
	v_and_or_b32 v3, v3, s83, v7
	v_and_or_b32 v4, v4, s82, v8
	v_and_or_b32 v5, v5, s83, v9
	global_store_dword v[28:29], v2, off
	global_store_dword v[30:31], v3, off
	global_store_dword v[32:33], v4, off
	global_store_dword v[34:35], v5, off
	s_cbranch_vccnz .LBB0_713
	s_andn2_b64 vcc, exec, s[14:15]
	s_cbranch_vccnz .LBB0_712
	s_barrier
	s_branch .LBB0_712

; #define LAS __attribute__((address_space(3)))
; __device__ __forceinline__ unsigned cvt_pk_bf16(float lo, float hi) { f32x2 v = {lo, hi}; bf16x2_t b = __builtin_convertvector(v, bf16x2_t); return __builtin_bit_cast(unsigned, b); }
; #define MFMA32(a, b, c) __builtin_amdgcn_mfma_f32_32x32x16_bf16((a), (b), (c), 0, 0, 0)
; __device__ __forceinline__ void ssd_item(LAS unsigned char* lds, int b, int hh, const Args& a) {
;     ...
;         for (int sb = 0; sb <= lb; ++sb) {
;             f32x16 gt;
; #pragma unroll
;             for (int r = 0; r < 16; ++r) gt[r] = 0.f;
;             const LAS unsigned char* bp = lds + O_BM + (32 * sb + c) * RP + hi * 16;
; #pragma unroll
;             for (int ks = 0; ks < 8; ++ks) gt = MFMA32(*(const LAS bf16x8*)(bp + ks * 32), *(const LAS bf16x8*)(lds + cmoff + ks * 32), gt);
;             asm volatile("" : "+v"(cmoff));
; #pragma unroll
;             for (int g4 = 0; g4 < 4; ++g4) { const int sq = 32 * sb + 4 * hi + 8 * g4; const f32x4 av = *(const LAS f32x4*)(acum + sq), dv = *(const LAS f32x4*)(dtv + sq);
; #pragma unroll
;                 for (int i = 0; i < 4; ++i) { const float e = __expf(fminf(acl_l - av[i], 0.f)) * dv[i]; gt[4 * g4 + i] = (sq + i <= l) ? gt[4 * g4 + i] * e : 0.f; } }
;             const LAS unsigned char* xp = lds + O_XT + (32 * pb + c) * RP + (32 * sb + 4 * hi) * 2;
; #pragma unroll
;             for (int kk = 0; kk < 2; ++kk) { u32x4 t; t.x = cvt_pk_bf16(gt[8 * kk + 0], gt[8 * kk + 1]); t.y = cvt_pk_bf16(gt[8 * kk + 2], gt[8 * kk + 3]); t.z = cvt_pk_bf16(gt[8 * kk + 4], gt[8 * kk + 5]); t.w = cvt_pk_bf16(gt[8 * kk + 6], gt[8 * kk + 7]);
;                 const u32x2 lo = *(const LAS u32x2*)(xp + kk * 32), hi2 = *(const LAS u32x2*)(xp + kk * 32 + 16); const u32x4 xa = (u32x4){lo.x, lo.y, hi2.x, hi2.y};
;                 yd = MFMA32(__builtin_bit_cast(bf16x8, xa), __builtin_bit_cast(bf16x8, t), yd); }
.LBB0_914:
	v_add_u32_e32 v169, 0, v167
	v_add_u32_e32 v178, 0, v99
	ds_read_b128 v[34:37], v169
	ds_read_b128 v[38:41], v178
	ds_read_b128 v[170:173], v169 offset:32
	ds_read_b128 v[174:177], v178 offset:32
	ds_read_b128 v[216:219], v169 offset:64
	ds_read_b128 v[220:223], v178 offset:64
	ds_read_b128 v[224:227], v169 offset:96
	ds_read_b128 v[228:231], v178 offset:96
	v_add_u32_e32 v248, 0x22000, v51
	v_add_u32_e32 v249, 0x19800, v168
	ds_read_b128 v[232:235], v248 offset:512
	ds_read_b128 v[236:239], v248
	ds_read_b128 v[240:243], v248 offset:544
	ds_read_b128 v[244:247], v248 offset:32
	s_waitcnt lgkmcnt(10)
	v_mfma_f32_32x32x16_bf16 v[34:49], v[34:37], v[38:41], 0
	s_waitcnt lgkmcnt(8)
	v_mfma_f32_32x32x16_bf16 v[34:49], v[170:173], v[174:177], v[34:49]
	ds_read_b128 v[170:173], v169 offset:128
	ds_read_b128 v[174:177], v178 offset:128
	s_waitcnt lgkmcnt(8)
	v_mfma_f32_32x32x16_bf16 v[34:49], v[216:219], v[220:223], v[34:49]
	ds_read_b128 v[216:219], v169 offset:160
	ds_read_b128 v[220:223], v178 offset:160
	s_waitcnt lgkmcnt(8)
	v_mfma_f32_32x32x16_bf16 v[34:49], v[224:227], v[228:231], v[34:49]
	ds_read_b128 v[224:227], v169 offset:192
	ds_read_b128 v[228:231], v178 offset:192
	s_waitcnt lgkmcnt(4)
	v_mfma_f32_32x32x16_bf16 v[34:49], v[170:173], v[174:177], v[34:49]
	ds_read_b128 v[170:173], v169 offset:224
	ds_read_b128 v[174:177], v178 offset:224
	s_waitcnt lgkmcnt(4)
	v_mfma_f32_32x32x16_bf16 v[34:49], v[216:219], v[220:223], v[34:49]
	ds_read_b128 v[216:219], v248 offset:576
	ds_read_b128 v[220:223], v248 offset:64
	s_waitcnt lgkmcnt(4)
	v_mfma_f32_32x32x16_bf16 v[34:49], v[224:227], v[228:231], v[34:49]
	ds_read_b128 v[224:227], v248 offset:608
	ds_read_b128 v[228:231], v248 offset:96
	s_waitcnt lgkmcnt(4)
	v_mfma_f32_32x32x16_bf16 v[34:49], v[170:173], v[174:177], v[34:49]
	v_or_b32_e32 v184, 8, v105
	v_or_b32_e32 v188, 16, v105
	v_or_b32_e32 v193, 24, v105
	v_or_b32_e32 v180, 2, v105
	v_or_b32_e32 v181, 9, v105
	v_or_b32_e32 v186, 10, v105
	v_or_b32_e32 v185, 11, v105
	v_or_b32_e32 v187, 17, v105
	v_or_b32_e32 v190, 18, v105
	v_or_b32_e32 v189, 19, v105
	v_or_b32_e32 v192, 25, v105
	v_cmp_le_u32_e32 vcc, v105, v90
	v_sub_f32_e32 v169, v92, v232
	v_min_f32_e32 v169, 0, v169
	v_mul_f32_e32 v169, 0x3fb8aa3b, v169
	v_exp_f32_e32 v169, v169
	s_nop 0
	v_mul_f32_e32 v169, v236, v169
	s_nop 0
	v_mul_f32_e32 v34, v34, v169
	v_cndmask_b32_e32 v169, 0, v34, vcc
	v_sub_f32_e32 v34, v92, v233
	v_min_f32_e32 v34, 0, v34
	v_mul_f32_e32 v34, 0x3fb8aa3b, v34
	v_exp_f32_e32 v34, v34
	v_cmp_lt_u32_e32 vcc, v105, v90
	v_or_b32_e32 v171, 3, v105
	v_mul_f32_e32 v34, v237, v34
	v_mul_f32_e32 v34, v35, v34
	v_cndmask_b32_e32 v170, 0, v34, vcc
	v_sub_f32_e32 v34, v92, v234
	v_sub_f32_e32 v35, v92, v235
	v_min_f32_e32 v34, 0, v34
	v_min_f32_e32 v35, 0, v35
	v_mul_f32_e32 v34, 0x3fb8aa3b, v34
	v_mul_f32_e32 v35, 0x3fb8aa3b, v35
	v_exp_f32_e32 v34, v34
	v_exp_f32_e32 v35, v35
	v_cmp_le_u32_e32 vcc, v180, v90
	v_mul_f32_e32 v34, v238, v34
	v_mul_f32_e32 v35, v239, v35
	v_mul_f32_e32 v34, v36, v34
	v_mul_f32_e32 v35, v37, v35
	ds_read_b64 v[232:233], v249
	ds_read_b64 v[234:235], v249 offset:16
	ds_read_b64 v[236:237], v249 offset:32
	ds_read_b64 v[238:239], v249 offset:48
	v_cvt_pk_bf16_f32 v34, v34, v35
	v_cndmask_b32_e32 v35, 0, v34, vcc
	v_sub_f32_e32 v36, v92, v240
	v_sub_f32_e32 v37, v92, v241
	v_min_f32_e32 v36, 0, v36
	v_min_f32_e32 v37, 0, v37
	v_mul_f32_e32 v36, 0x3fb8aa3b, v36
	v_mul_f32_e32 v37, 0x3fb8aa3b, v37
	v_exp_f32_e32 v36, v36
	v_exp_f32_e32 v37, v37
	v_lshrrev_b32_e32 v34, 16, v34
	v_cmp_le_u32_e32 vcc, v171, v53
	v_mul_f32_e32 v36, v244, v36
	v_mul_f32_e32 v37, v245, v37
	v_mul_f32_e32 v36, v38, v36
	v_mul_f32_e32 v37, v39, v37
	v_sub_f32_e32 v38, v92, v242
	v_sub_f32_e32 v39, v92, v243
	v_min_f32_e32 v38, 0, v38
	v_min_f32_e32 v39, 0, v39
	v_mul_f32_e32 v38, 0x3fb8aa3b, v38
	v_mul_f32_e32 v39, 0x3fb8aa3b, v39
	v_exp_f32_e32 v38, v38
	v_exp_f32_e32 v39, v39
	v_cndmask_b32_e32 v34, 0, v34, vcc
	v_cmp_le_u32_e32 vcc, v184, v90
	v_mul_f32_e32 v38, v246, v38
	v_mul_f32_e32 v39, v247, v39
	v_mul_f32_e32 v40, v40, v38
	v_mul_f32_e32 v41, v41, v39
	s_waitcnt lgkmcnt(6)
; #define LAS __attribute__((address_space(3)))
; __device__ __forceinline__ unsigned cvt_pk_bf16(float lo, float hi) { f32x2 v = {lo, hi}; bf16x2_t b = __builtin_convertvector(v, bf16x2_t); return __builtin_bit_cast(unsigned, b); }
; #define MFMA32(a, b, c) __builtin_amdgcn_mfma_f32_32x32x16_bf16((a), (b), (c), 0, 0, 0)
; __device__ __forceinline__ void ssd_item(LAS unsigned char* lds, int b, int hh, const Args& a) {
;     ...
;             for (int g4 = 0; g4 < 4; ++g4) { const int sq = 32 * sb + 4 * hi + 8 * g4; const f32x4 av = *(const LAS f32x4*)(acum + sq), dv = *(const LAS f32x4*)(dtv + sq);
; #pragma unroll
;                 for (int i = 0; i < 4; ++i) { const float e = __expf(fminf(acl_l - av[i], 0.f)) * dv[i]; gt[4 * g4 + i] = (sq + i <= l) ? gt[4 * g4 + i] * e : 0.f; } }
;             const LAS unsigned char* xp = lds + O_XT + (32 * pb + c) * RP + (32 * sb + 4 * hi) * 2;
; #pragma unroll
;             for (int kk = 0; kk < 2; ++kk) { u32x4 t; t.x = cvt_pk_bf16(gt[8 * kk + 0], gt[8 * kk + 1]); t.y = cvt_pk_bf16(gt[8 * kk + 2], gt[8 * kk + 3]); t.z = cvt_pk_bf16(gt[8 * kk + 4], gt[8 * kk + 5]); t.w = cvt_pk_bf16(gt[8 * kk + 6], gt[8 * kk + 7]);
;                 const u32x2 lo = *(const LAS u32x2*)(xp + kk * 32), hi2 = *(const LAS u32x2*)(xp + kk * 32 + 16); const u32x4 xa = (u32x4){lo.x, lo.y, hi2.x, hi2.y};
;                 yd = MFMA32(__builtin_bit_cast(bf16x8, xa), __builtin_bit_cast(bf16x8, t), yd); }
;         }
;         if (ch + 1 < 32) SSD_FETCH(ch + 1);
	v_sub_f32_e32 v38, v92, v216
	v_sub_f32_e32 v39, v92, v217
	v_min_f32_e32 v38, 0, v38
	v_min_f32_e32 v39, 0, v39
	v_mul_f32_e32 v38, 0x3fb8aa3b, v38
	v_mul_f32_e32 v39, 0x3fb8aa3b, v39
	v_exp_f32_e32 v38, v38
	v_exp_f32_e32 v39, v39
	s_nop 0
	v_mul_f32_e32 v38, v220, v38
	v_mul_f32_e32 v39, v221, v39
	v_mul_f32_e32 v38, v42, v38
	v_mul_f32_e32 v39, v43, v39
	v_sub_f32_e32 v42, v92, v218
	v_sub_f32_e32 v43, v92, v219
	v_min_f32_e32 v42, 0, v42
	v_min_f32_e32 v43, 0, v43
	v_mul_f32_e32 v42, 0x3fb8aa3b, v42
	v_mul_f32_e32 v43, 0x3fb8aa3b, v43
	v_exp_f32_e32 v42, v42
	v_exp_f32_e32 v43, v43
	s_nop 0
	v_mul_f32_e32 v42, v222, v42
	v_mul_f32_e32 v43, v223, v43
	v_mul_f32_e32 v42, v44, v42
	v_mul_f32_e32 v43, v45, v43
	s_waitcnt lgkmcnt(4)
	v_sub_f32_e32 v44, v92, v224
	v_sub_f32_e32 v45, v92, v225
	v_min_f32_e32 v44, 0, v44
	v_min_f32_e32 v45, 0, v45
	v_mul_f32_e32 v44, 0x3fb8aa3b, v44
	v_mul_f32_e32 v45, 0x3fb8aa3b, v45
	v_exp_f32_e32 v44, v44
	v_exp_f32_e32 v45, v45
	s_nop 0
	v_mul_f32_e32 v44, v228, v44
	v_mul_f32_e32 v45, v229, v45
	v_mul_f32_e32 v44, v46, v44
	v_mul_f32_e32 v45, v47, v45
	v_sub_f32_e32 v46, v92, v226
	v_sub_f32_e32 v47, v92, v227
	v_min_f32_e32 v46, 0, v46
	v_min_f32_e32 v47, 0, v47
	v_mul_f32_e32 v46, 0x3fb8aa3b, v46
	v_mul_f32_e32 v47, 0x3fb8aa3b, v47
	v_exp_f32_e32 v46, v46
	v_exp_f32_e32 v47, v47
	v_or_b32_e32 v175, 26, v105
	s_nop 0
	v_mul_f32_e32 v46, v230, v46
	v_mul_f32_e32 v47, v231, v47
	v_or_b32_e32 v174, 27, v105
	v_mul_f32_e32 v172, v48, v46
	v_mul_f32_e32 v173, v49, v47
	v_perm_b32 v47, v34, v35, s85
	v_cvt_pk_bf16_f32 v34, v36, v37
	v_cndmask_b32_e32 v35, 0, v34, vcc
	v_lshrrev_b32_e32 v34, 16, v34
	v_cmp_le_u32_e32 vcc, v181, v53
	s_nop 1
	v_cndmask_b32_e32 v34, 0, v34, vcc
	v_perm_b32 v48, v34, v35, s85
	v_cvt_pk_bf16_f32 v34, v40, v41
	v_cmp_le_u32_e32 vcc, v186, v90
	v_cvt_pk_bf16_f32 v46, v169, v170
	s_nop 0
	v_cndmask_b32_e32 v35, 0, v34, vcc
	v_lshrrev_b32_e32 v34, 16, v34
	v_cmp_le_u32_e32 vcc, v185, v53
	s_nop 1
	v_cndmask_b32_e32 v34, 0, v34, vcc
	v_perm_b32 v49, v34, v35, s85
	v_cmp_le_u32_e32 vcc, v188, v90
	s_waitcnt lgkmcnt(2)
	v_mfma_f32_32x32x16_bf16 v[18:33], v[232:235], v[46:49], v[18:33]
	v_cvt_pk_bf16_f32 v34, v38, v39
	v_cndmask_b32_e32 v35, 0, v34, vcc
	v_lshrrev_b32_e32 v34, 16, v34
	v_cmp_le_u32_e32 vcc, v187, v53
	v_add_u32_e32 v105, 32, v105
	s_nop 0
	v_cndmask_b32_e32 v34, 0, v34, vcc
	v_perm_b32 v34, v34, v35, s85
	v_cvt_pk_bf16_f32 v35, v42, v43
	v_cmp_le_u32_e32 vcc, v190, v90
	s_nop 1
	v_cndmask_b32_e32 v36, 0, v35, vcc
	v_lshrrev_b32_e32 v35, 16, v35
	v_cmp_le_u32_e32 vcc, v189, v53
	s_nop 1
	v_cndmask_b32_e32 v35, 0, v35, vcc
	v_perm_b32 v35, v35, v36, s85
	v_cvt_pk_bf16_f32 v36, v44, v45
	v_cmp_le_u32_e32 vcc, v193, v90
	s_nop 1
	v_cndmask_b32_e32 v37, 0, v36, vcc
	v_lshrrev_b32_e32 v36, 16, v36
	v_cmp_le_u32_e32 vcc, v192, v53
	s_nop 1
	v_cndmask_b32_e32 v36, 0, v36, vcc
	v_perm_b32 v36, v36, v37, s85
	v_cvt_pk_bf16_f32 v37, v172, v173
	v_cmp_le_u32_e32 vcc, v175, v90
	s_nop 1
	v_cndmask_b32_e32 v38, 0, v37, vcc
	v_lshrrev_b32_e32 v37, 16, v37
	v_cmp_le_u32_e32 vcc, v174, v53
	s_nop 1
	v_cndmask_b32_e32 v37, 0, v37, vcc
	v_perm_b32 v37, v37, v38, s85
	v_add_u32_e32 v167, 0x2200, v167
	v_add_u32_e32 v51, 0x80, v51
	v_add_u32_e32 v168, 64, v168
	s_waitcnt lgkmcnt(0)
	v_mfma_f32_32x32x16_bf16 v[18:33], v[236:239], v[34:37], v[18:33]
	s_add_i32 s33, s33, -1
	s_cmp_lg_u32 s33, 0
	s_cbranch_scc1 .LBB0_914
	s_add_i32 s33, s59, 1
	s_cmp_eq_u32 s59, 31
	s_cbranch_scc1 .LBB0_948
	s_lshl_b32 s30, s33, 7
	s_add_i32 s30, s30, s88
	v_or_b32_e32 v34, s30, v55
	v_mov_b32_e32 v62, v50
	v_mov_b32_e32 v63, v50
	v_mad_i64_i32 v[34:35], s[62:63], v34, s76, v[94:95]
	v_mov_b64_e32 v[64:65], v[62:63]
	v_mov_b64_e32 v[66:67], v[62:63]
	s_and_saveexec_b64 s[62:63], s[2:3]
	s_cbranch_execz .LBB0_918
	v_add_co_u32_e32 v36, vcc, 0x24000, v34
	s_nop 1
	v_addc_co_u32_e32 v37, vcc, 0, v35, vcc
	global_load_dwordx2 v[64:65], v[34:35], off
	global_load_dwordx2 v[66:67], v[36:37], off

; #define LAS __attribute__((address_space(3)))
; __device__ __forceinline__ unsigned cvt_pk_bf16(float lo, float hi) { f32x2 v = {lo, hi}; bf16x2_t b = __builtin_convertvector(v, bf16x2_t); return __builtin_bit_cast(unsigned, b); }
; __device__ __forceinline__ float bf2f(unsigned short v) { return __uint_as_float(((unsigned)v) << 16); }
; __device__ __forceinline__ float bflo(unsigned v) { return __uint_as_float(v << 16); }
; __device__ __forceinline__ float bfhi(unsigned v) { return __uint_as_float(v & 0xffff0000u); }
; #define LDS_BARRIER() asm volatile("s_waitcnt lgkmcnt(0)\n\ts_barrier" ::: "memory")
; __device__ __forceinline__ void ssd_item(LAS unsigned char* lds, int b, int hh, const Args& a) {
;     ...
;         if (ch + 1 < 32) SSD_FETCH(ch + 1);
;         { const LAS unsigned char* hp = lds + O_HS + (32 * pb + c) * RP + hi * 16;
; #pragma unroll
;             for (int ks = 0; ks < 8; ++ks) yo = MFMA32(*(const LAS bf16x8*)(hp + ks * 32), *(const LAS bf16x8*)(lds + cmoff + ks * 32), yo); }
;         { const float cd = __expf(acl);
; #pragma unroll
;             for (int r = 0; r < 16; ++r) hT[r] *= cd;
;             const LAS unsigned char* ap = lds + O_BWT + (32 * nb + c) * RP + hi * 16; const LAS unsigned char* xq = lds + O_XT + (32 * pb + c) * RP + hi * 16;
; #pragma unroll
;             for (int ks = 0; ks < 8; ++ks) hT = MFMA32(*(const LAS bf16x8*)(ap + ks * 32), *(const LAS bf16x8*)(xq + ks * 32), hT); }
;         LDS_BARRIER();
; #pragma unroll
;         for (int g4 = 0; g4 < 4; ++g4) { u32x2 pk; pk.x = cvt_pk_bf16(hT[4 * g4], hT[4 * g4 + 1]); pk.y = cvt_pk_bf16(hT[4 * g4 + 2], hT[4 * g4 + 3]);
;             *(LAS u32x2*)(lds + O_HS + (32 * pb + c) * RP + (32 * nb + 8 * g4 + 4 * hi) * 2) = pk; }
;         { const size_t row = (size_t)(row0 + l); float ssq = 0.f;
; #pragma unroll
;             for (int g4 = 0; g4 < 4; ++g4) { const int p0 = 32 * pb + 8 * g4 + 4 * hi;
;                 const u32x2 zq = zz[g4];
;                 float o[4];
; #pragma unroll
;                 for (int i = 0; i < 4; ++i) { const float xv = bf2f(*(const LAS unsigned short*)(lds + O_XT + (p0 + i) * RP + l * 2));
;                     const float zf = (i == 0) ? bflo(zq.x) : (i == 1) ? bfhi(zq.x) : (i == 2) ? bflo(zq.y) : bfhi(zq.y);
;                     o[i] = (yd[4 * g4 + i] + ea * yo[4 * g4 + i] + Dh * xv) * silu_f(zf); }
.LBB0_947:
	v_or_b32_e32 v38, s30, v91
	v_mov_b64_e32 v[34:35], s[46:47]
	v_mad_i64_i32 v[36:37], s[26:27], v38, s77, v[34:35]
	v_or_b32_e32 v38, 1, v38
	s_lshl_b32 s26, s87, 1
	s_mov_b32 s27, s44
	v_mad_i64_i32 v[34:35], s[30:31], v38, s77, v[34:35]
	v_lshl_add_u64 v[34:35], v[34:35], 0, s[26:27]
	v_add_co_u32_e32 v34, vcc, 0x1000, v34
	v_lshl_add_u64 v[36:37], v[36:37], 0, s[26:27]
	s_nop 0
	v_addc_co_u32_e32 v35, vcc, 0, v35, vcc
	v_add_co_u32_e32 v36, vcc, 0x1000, v36
	s_nop 1
	v_addc_co_u32_e32 v37, vcc, 0, v37, vcc
	global_load_ushort v97, v[36:37], off offset:3200
	s_nop 0
	global_load_ushort v96, v[34:35], off offset:3200
.LBB0_948:
	v_add_u32_e32 v51, v161, v138
	ds_read_b128 v[34:37], v51
	v_add_u32_e32 v99, 0, v99
	ds_read_b128 v[38:41], v99
	ds_read_b128 v[168:171], v51 offset:32
	ds_read_b128 v[172:175], v99 offset:32
	v_mul_f32_e32 v59, 0x3fb8aa3b, v59
	v_exp_f32_e32 v180, v59
	ds_read_b128 v[176:179], v163 offset:34816
	ds_read_b128 v[184:187], v163 offset:34848
	ds_read_b128 v[192:195], v51 offset:64
	v_mul_f32_e32 v59, 0x3fb8aa3b, v92
	v_exp_f32_e32 v92, v59
	v_pk_mul_f32 v[16:17], v[16:17], v[180:181] op_sel_hi:[1,0]
	s_waitcnt lgkmcnt(5)
	v_mfma_f32_32x32x16_bf16 v[34:49], v[34:37], v[38:41], 0
	v_mul_f32_e64 v14, v14, v180
	v_mul_f32_e64 v15, v15, v180
	v_mul_f32_e64 v12, v12, v180
	v_mul_f32_e64 v13, v13, v180
	v_mul_f32_e64 v10, v10, v180
	v_mul_f32_e64 v11, v11, v180
	v_pk_mul_f32 v[8:9], v[8:9], v[180:181] op_sel_hi:[1,0]
	v_pk_mul_f32 v[6:7], v[6:7], v[180:181] op_sel_hi:[1,0]
	v_pk_mul_f32 v[4:5], v[4:5], v[180:181] op_sel_hi:[1,0]
	v_pk_mul_f32 v[2:3], v[2:3], v[180:181] op_sel_hi:[1,0]
	s_waitcnt lgkmcnt(3)
	v_mfma_f32_32x32x16_bf16 v[34:49], v[168:171], v[172:175], v[34:49]
	ds_read_b128 v[168:171], v99 offset:64
	ds_read_b128 v[172:175], v164
	ds_read_b128 v[196:199], v164 offset:32
	ds_read_b128 v[200:203], v51 offset:96
	ds_read_b128 v[204:207], v99 offset:96
	s_mov_b32 s59, s44
	s_waitcnt lgkmcnt(3)
	v_mfma_f32_32x32x16_bf16 v[2:17], v[176:179], v[172:175], v[2:17]
	s_waitcnt lgkmcnt(2)
	v_mfma_f32_32x32x16_bf16 v[2:17], v[184:187], v[196:199], v[2:17]
	v_mfma_f32_32x32x16_bf16 v[34:49], v[192:195], v[168:171], v[34:49]
	ds_read_b128 v[168:171], v163 offset:34880
	ds_read_b128 v[172:175], v164 offset:64
	ds_read_b128 v[176:179], v163 offset:34912
	ds_read_b128 v[184:187], v164 offset:96
	s_waitcnt lgkmcnt(2)
	v_mfma_f32_32x32x16_bf16 v[2:17], v[168:171], v[172:175], v[2:17]
	s_waitcnt lgkmcnt(0)
	v_mfma_f32_32x32x16_bf16 v[2:17], v[176:179], v[184:187], v[2:17]
	ds_read_b128 v[168:171], v163 offset:34944
	ds_read_b128 v[172:175], v164 offset:128
	ds_read_b128 v[176:179], v163 offset:34976
	ds_read_b128 v[184:187], v164 offset:160
	s_waitcnt lgkmcnt(2)
	v_mfma_f32_32x32x16_bf16 v[2:17], v[168:171], v[172:175], v[2:17]
	s_waitcnt lgkmcnt(0)
	v_mfma_f32_32x32x16_bf16 v[2:17], v[176:179], v[184:187], v[2:17]
	ds_read_b128 v[168:171], v163 offset:35008
	ds_read_b128 v[172:175], v164 offset:192
	ds_read_b128 v[176:179], v163 offset:35040
	ds_read_b128 v[184:187], v164 offset:224
	s_waitcnt lgkmcnt(2)
	v_mfma_f32_32x32x16_bf16 v[2:17], v[168:171], v[172:175], v[2:17]
	ds_read_b128 v[168:171], v51 offset:128
	ds_read_b128 v[172:175], v51 offset:160
	v_mfma_f32_32x32x16_bf16 v[34:49], v[200:203], v[204:207], v[34:49]
	s_waitcnt lgkmcnt(2)
	v_mfma_f32_32x32x16_bf16 v[2:17], v[176:179], v[184:187], v[2:17]
	ds_read_b128 v[176:179], v99 offset:128
	ds_read_b128 v[184:187], v99 offset:160
	ds_read_b128 v[192:195], v51 offset:192
	ds_read_b128 v[196:199], v51 offset:224
	ds_read_b128 v[208:211], v99 offset:192
	ds_read_b128 v[212:215], v99 offset:224
	s_and_b64 vcc, exec, s[56:57]
	s_cbranch_vccz .Lssd_dr_skip
	s_waitcnt vmcnt(0)
	v_lshlrev_b32_e32 v97, 16, v97
	v_lshlrev_b32_e32 v96, 16, v96
.Lssd_dr_skip:
	s_waitcnt lgkmcnt(0)
	s_barrier
	s_nop 5
	v_cvt_pk_bf16_f32 v180, v2, v3
	s_waitcnt lgkmcnt(5)
	v_mfma_f32_32x32x16_bf16 v[34:49], v[168:171], v[176:179], v[34:49]
	s_waitcnt vmcnt(3)
	v_lshlrev_b32_e32 v170, 16, v132
	v_mul_f32_e32 v51, 0xbfb8aa3b, v170
	v_exp_f32_e32 v51, v51
	v_and_b32_e32 v171, 0xffff0000, v132
	v_cvt_pk_bf16_f32 v181, v4, v5
	v_cvt_pk_bf16_f32 v188, v6, v7
	v_add_f32_e32 v51, 1.0, v51
	s_waitcnt lgkmcnt(4)
	v_mfma_f32_32x32x16_bf16 v[34:49], v[172:175], v[184:187], v[34:49]
	v_rcp_f32_e32 v172, v51
	v_mul_f32_e32 v51, 0xbfb8aa3b, v171
	v_exp_f32_e32 v51, v51
	v_cvt_pk_bf16_f32 v189, v8, v9
	ds_write2_b64 v165, v[180:181], v[188:189] offset1:2
	v_cvt_pk_bf16_f32 v180, v10, v11
	v_add_f32_e32 v51, 1.0, v51
	s_waitcnt lgkmcnt(2)
	v_mfma_f32_32x32x16_bf16 v[34:49], v[192:195], v[208:211], v[34:49]
	v_rcp_f32_e32 v173, v51
	v_cvt_pk_bf16_f32 v181, v12, v13
	v_cvt_pk_bf16_f32 v188, v14, v15
	v_cvt_pk_bf16_f32 v189, v16, v17
	ds_write2_b64 v165, v[180:181], v[188:189] offset0:4 offset1:6
	ds_read_u16 v59, v166
	ds_read_u16 v99, v166 offset:272
	ds_read_u16 v105, v166 offset:544
	ds_read_u16 v167, v166 offset:816
	ds_read_u16 v176, v166 offset:2176
	ds_read_u16 v177, v166 offset:2448
	ds_read_u16 v178, v166 offset:2720
	ds_read_u16 v179, v166 offset:2992
	s_waitcnt lgkmcnt(6)
	v_lshlrev_b32_e32 v175, 16, v99
	v_mfma_f32_32x32x16_bf16 v[34:49], v[196:199], v[212:215], v[34:49]
	v_lshlrev_b32_e32 v174, 16, v59
	v_lshlrev_b64 v[168:169], 12, v[124:125]
	v_lshl_add_u64 v[168:169], s[50:51], 0, v[168:169]
	v_lshl_add_u64 v[168:169], v[168:169], 0, s[58:59]
	s_nop 7
	v_pk_fma_f32 v[18:19], v[92:93], v[34:35], v[18:19] op_sel_hi:[0,1,1]
	v_pk_fma_f32 v[18:19], v[60:61], v[174:175], v[18:19]
	v_pk_mul_f32 v[34:35], v[172:173], v[170:171]
	s_waitcnt lgkmcnt(4)
; #define LAS __attribute__((address_space(3)))
; __device__ __forceinline__ unsigned cvt_pk_bf16(float lo, float hi) { f32x2 v = {lo, hi}; bf16x2_t b = __builtin_convertvector(v, bf16x2_t); return __builtin_bit_cast(unsigned, b); }
; __device__ __forceinline__ float bf2f(unsigned short v) { return __uint_as_float(((unsigned)v) << 16); }
; __device__ __forceinline__ float bflo(unsigned v) { return __uint_as_float(v << 16); }
; __device__ __forceinline__ float bfhi(unsigned v) { return __uint_as_float(v & 0xffff0000u); }
; __device__ __forceinline__ float silu_f(float v) { return v * __builtin_amdgcn_rcpf(1.0f + __expf(-v)); }
; __device__ __forceinline__ void ssd_item(LAS unsigned char* lds, int b, int hh, const Args& a) {
;     ...
;         { const size_t row = (size_t)(row0 + l); float ssq = 0.f;
; #pragma unroll
;             for (int g4 = 0; g4 < 4; ++g4) { const int p0 = 32 * pb + 8 * g4 + 4 * hi;
;                 const u32x2 zq = zz[g4];
;                 float o[4];
; #pragma unroll
;                 for (int i = 0; i < 4; ++i) { const float xv = bf2f(*(const LAS unsigned short*)(lds + O_XT + (p0 + i) * RP + l * 2));
;                     const float zf = (i == 0) ? bflo(zq.x) : (i == 1) ? bfhi(zq.x) : (i == 2) ? bflo(zq.y) : bfhi(zq.y);
;                     o[i] = (yd[4 * g4 + i] + ea * yo[4 * g4 + i] + Dh * xv) * silu_f(zf); }
;                 ssq += (o[0] * o[0] + o[1] * o[1]) + (o[2] * o[2] + o[3] * o[3]);
;                 u32x2 pk; pk.x = cvt_pk_bf16(o[0], o[1]); pk.y = cvt_pk_bf16(o[2], o[3]);
;                 *(u32x2*)(MIXIN + row * DM + 1024 + hh * 64 + p0) = pk; }
;             ssq += __shfl_xor(ssq, 32);
;             if (hi == 0) atomicAdd(a.out + STAT2_OFF + row * 4 + 1 + g, ssq); }
	v_lshlrev_b32_e32 v171, 16, v167
	v_pk_mul_f32 v[18:19], v[34:35], v[18:19]
	v_lshlrev_b32_e32 v34, 16, v133
	v_mul_f32_e32 v35, 0xbfb8aa3b, v34
	v_exp_f32_e32 v51, v35
	v_and_b32_e32 v35, 0xffff0000, v133
	v_mul_f32_e32 v59, 0xbfb8aa3b, v35
	v_exp_f32_e32 v59, v59
	v_add_f32_e32 v51, 1.0, v51
	v_rcp_f32_e32 v132, v51
	v_lshlrev_b32_e32 v170, 16, v105
	v_add_f32_e32 v51, 1.0, v59
	v_rcp_f32_e32 v133, v51
	v_pk_fma_f32 v[20:21], v[92:93], v[36:37], v[20:21] op_sel_hi:[0,1,1]
	v_pk_fma_f32 v[20:21], v[60:61], v[170:171], v[20:21]
	v_mov_b32_e32 v105, v50
	v_pk_mul_f32 v[34:35], v[132:133], v[34:35]
	v_cvt_pk_bf16_f32 v132, v18, v19
	v_pk_mul_f32 v[20:21], v[34:35], v[20:21]
	v_pk_mul_f32 v[34:35], v[18:19], v[18:19]
	v_pk_mul_f32 v[36:37], v[20:21], v[20:21]
	v_cvt_pk_bf16_f32 v133, v20, v21
	v_lshl_add_u64 v[20:21], v[168:169], 0, v[104:105]
	v_lshl_add_u64 v[18:19], v[20:21], 0, s[54:55]
	v_add_co_u32_e32 v20, vcc, s86, v20
	s_waitcnt lgkmcnt(2)
	v_lshlrev_b32_e32 v169, 16, v177
	v_addc_co_u32_e32 v21, vcc, 0, v21, vcc
	global_store_dwordx2 v[20:21], v[132:133], off offset:2048
	s_waitcnt vmcnt(3)
	v_lshlrev_b32_e32 v20, 16, v130
	v_mul_f32_e32 v21, 0xbfb8aa3b, v20
	v_exp_f32_e32 v51, v21
	v_and_b32_e32 v21, 0xffff0000, v130
	v_mul_f32_e32 v59, 0xbfb8aa3b, v21
	v_exp_f32_e32 v59, v59
	v_add_f32_e32 v51, 1.0, v51
	v_rcp_f32_e32 v132, v51
	v_lshlrev_b32_e32 v168, 16, v176
	v_add_f32_e32 v51, 1.0, v59
	v_rcp_f32_e32 v133, v51
	v_pk_fma_f32 v[22:23], v[92:93], v[38:39], v[22:23] op_sel_hi:[0,1,1]
	v_pk_fma_f32 v[22:23], v[60:61], v[168:169], v[22:23]
	s_waitcnt lgkmcnt(1)
	v_lshlrev_b32_e32 v130, 16, v178
	v_pk_mul_f32 v[20:21], v[132:133], v[20:21]
	v_pk_fma_f32 v[24:25], v[92:93], v[40:41], v[24:25] op_sel_hi:[0,1,1]
	v_pk_mul_f32 v[20:21], v[20:21], v[22:23]
	v_lshlrev_b32_e32 v22, 16, v131
	v_mul_f32_e32 v23, 0xbfb8aa3b, v22
	v_exp_f32_e32 v38, v23
	v_and_b32_e32 v23, 0xffff0000, v131
	v_mul_f32_e32 v39, 0xbfb8aa3b, v23
	v_exp_f32_e32 v39, v39
	v_add_f32_e32 v38, 1.0, v38
	v_rcp_f32_e32 v38, v38
	s_waitcnt lgkmcnt(0)
	v_lshlrev_b32_e32 v131, 16, v179
	v_add_f32_e32 v39, 1.0, v39
	v_rcp_f32_e32 v39, v39
	v_pk_fma_f32 v[24:25], v[60:61], v[130:131], v[24:25]
	s_waitcnt vmcnt(2)
	v_lshlrev_b32_e32 v40, 16, v128
	v_and_b32_e32 v41, 0xffff0000, v128
	v_pk_mul_f32 v[22:23], v[38:39], v[22:23]
	v_pk_fma_f32 v[26:27], v[92:93], v[42:43], v[26:27] op_sel_hi:[0,1,1]
	v_pk_mul_f32 v[22:23], v[22:23], v[24:25]
	v_pk_mul_f32 v[24:25], v[20:21], v[20:21]
	v_cvt_pk_bf16_f32 v20, v20, v21
	v_mul_f32_e32 v21, 0xbfb8aa3b, v40
	v_exp_f32_e32 v51, v21
	v_cvt_pk_bf16_f32 v21, v22, v23
	global_store_dwordx2 v[18:19], v[20:21], off offset:16
	v_mul_f32_e32 v21, 0xbfb8aa3b, v41
	v_exp_f32_e32 v21, v21
	v_add_f32_e32 v20, 1.0, v51
	v_rcp_f32_e32 v20, v20
	v_pk_mul_f32 v[38:39], v[22:23], v[22:23]
	v_add_f32_e32 v21, 1.0, v21
	v_rcp_f32_e32 v21, v21
	ds_read_u16 v22, v166 offset:4352
	ds_read_u16 v23, v166 offset:4624
	ds_read_u16 v51, v166 offset:4896
	ds_read_u16 v59, v166 offset:5168
	ds_read_u16 v99, v166 offset:6528
	ds_read_u16 v105, v166 offset:6800
	ds_read_u16 v128, v166 offset:7072
	ds_read_u16 v130, v166 offset:7344
	s_waitcnt lgkmcnt(6)
	v_lshlrev_b32_e32 v23, 16, v23
	v_lshlrev_b32_e32 v22, 16, v22
	v_pk_fma_f32 v[22:23], v[60:61], v[22:23], v[26:27]
	v_pk_mul_f32 v[20:21], v[20:21], v[40:41]
	s_waitcnt lgkmcnt(4)
	v_lshlrev_b32_e32 v41, 16, v59
	v_pk_mul_f32 v[20:21], v[20:21], v[22:23]
	v_lshlrev_b32_e32 v22, 16, v129
	v_mul_f32_e32 v23, 0xbfb8aa3b, v22
	v_exp_f32_e32 v26, v23
	v_and_b32_e32 v23, 0xffff0000, v129
	v_mul_f32_e32 v27, 0xbfb8aa3b, v23
	v_exp_f32_e32 v27, v27
	v_add_f32_e32 v26, 1.0, v26
	v_rcp_f32_e32 v26, v26
	v_lshlrev_b32_e32 v40, 16, v51
	v_add_f32_e32 v27, 1.0, v27
	v_rcp_f32_e32 v27, v27
	v_pk_fma_f32 v[28:29], v[92:93], v[44:45], v[28:29] op_sel_hi:[0,1,1]
	v_pk_fma_f32 v[28:29], v[60:61], v[40:41], v[28:29]
	v_cvt_pk_bf16_f32 v40, v20, v21
	v_pk_mul_f32 v[22:23], v[26:27], v[22:23]
	v_pk_mul_f32 v[26:27], v[20:21], v[20:21]
	s_waitcnt vmcnt(2)
	v_lshlrev_b32_e32 v20, 16, v126
	v_pk_mul_f32 v[22:23], v[22:23], v[28:29]
	v_mul_f32_e32 v21, 0xbfb8aa3b, v20
	v_pk_mul_f32 v[28:29], v[22:23], v[22:23]
	v_cvt_pk_bf16_f32 v41, v22, v23
	v_exp_f32_e32 v22, v21
	v_and_b32_e32 v21, 0xffff0000, v126
	v_mul_f32_e32 v23, 0xbfb8aa3b, v21
	v_exp_f32_e32 v23, v23
	v_add_f32_e32 v22, 1.0, v22
	v_rcp_f32_e32 v22, v22
	s_waitcnt lgkmcnt(2)
	v_lshlrev_b32_e32 v43, 16, v105
	v_add_f32_e32 v23, 1.0, v23
	v_rcp_f32_e32 v23, v23
	v_lshlrev_b32_e32 v42, 16, v99
	v_pk_fma_f32 v[30:31], v[92:93], v[46:47], v[30:31] op_sel_hi:[0,1,1]
	v_pk_fma_f32 v[30:31], v[60:61], v[42:43], v[30:31]
	v_pk_mul_f32 v[20:21], v[22:23], v[20:21]
	s_waitcnt lgkmcnt(0)
	v_lshlrev_b32_e32 v43, 16, v130
	v_pk_mul_f32 v[22:23], v[20:21], v[30:31]
	v_lshlrev_b32_e32 v20, 16, v127
	v_mul_f32_e32 v21, 0xbfb8aa3b, v20
	v_exp_f32_e32 v30, v21
	v_and_b32_e32 v21, 0xffff0000, v127
	v_mul_f32_e32 v31, 0xbfb8aa3b, v21
	v_exp_f32_e32 v31, v31
	v_add_f32_e32 v30, 1.0, v30
	v_rcp_f32_e32 v30, v30
	v_lshlrev_b32_e32 v42, 16, v128
	v_add_f32_e32 v31, 1.0, v31
	v_rcp_f32_e32 v31, v31
	v_pk_fma_f32 v[32:33], v[92:93], v[48:49], v[32:33] op_sel_hi:[0,1,1]
	v_add_f32_e32 v38, v38, v39
	v_add_f32_e32 v24, v24, v25
	v_add_f32_e32 v25, v36, v37
	v_add_f32_e32 v34, v34, v35
	v_pk_fma_f32 v[32:33], v[60:61], v[42:43], v[32:33]
	v_pk_mul_f32 v[20:21], v[30:31], v[20:21]
	v_add_f32_e32 v24, v24, v38
	v_add_f32_e32 v25, v34, v25
	v_pk_mul_f32 v[30:31], v[20:21], v[32:33]
	v_add_f32_e32 v24, v25, v24
	v_add_f32_e32 v25, v28, v29
	v_add_f32_e32 v26, v26, v27
	v_pk_mul_f32 v[20:21], v[22:23], v[22:23]
	v_pk_mul_f32 v[32:33], v[30:31], v[30:31]
	v_add_f32_e32 v25, v26, v25
	v_add_f32_e32 v24, v24, v25
	v_add_f32_e32 v25, v32, v33
	v_add_f32_e32 v20, v20, v21
	v_add_f32_e32 v20, v20, v25
	v_add_f32_e32 v20, v24, v20
	v_and_b32_e32 v24, 64, v191
	v_xor_b32_e32 v21, 32, v191
	v_add_u32_e32 v24, 64, v24
	v_cmp_lt_i32_e32 vcc, v21, v24
	v_cvt_pk_bf16_f32 v22, v22, v23
	v_cvt_pk_bf16_f32 v23, v30, v31
	v_cndmask_b32_e32 v21, v191, v21, vcc
	v_lshlrev_b32_e32 v21, 2, v21
	ds_bpermute_b32 v21, v21, v20
	global_store_dwordx2 v[18:19], v[40:41], off offset:32
	global_store_dwordx2 v[18:19], v[22:23], off offset:48
	s_and_saveexec_b64 s[26:27], s[14:15]
	s_cbranch_execz .LBB0_852
	v_lshl_add_u64 v[18:19], v[124:125], 4, s[48:49]
	s_mov_b32 s61, s44
	v_lshl_add_u64 v[18:19], v[18:19], 0, s[60:61]
	v_add_co_u32_e32 v18, vcc, 0x8000000, v18
	s_waitcnt lgkmcnt(0)
	v_add_f32_e32 v20, v20, v21
	v_addc_co_u32_e32 v19, vcc, 0, v19, vcc
	global_atomic_add_f32 v[18:19], v20, off offset:4
	s_branch .LBB0_852

; #define LAS __attribute__((address_space(3)))
; #define MFMA32(a, b, c) __builtin_amdgcn_mfma_f32_32x32x16_bf16((a), (b), (c), 0, 0, 0)
; #define AT_EXP2(P, r) do { f32x2 dd = (f32x2){P[r], P[(r) + 1]} - mm; dd.x = __builtin_amdgcn_exp2f(dd.x); dd.y = __builtin_amdgcn_exp2f(dd.y); ssum += dd; P[r] = dd.x; P[(r) + 1] = dd.y; } while (0)
; #define AT_PACK(P, b8) ((u32x4){cvt_pk_bf16(P[(b8)], P[(b8) + 1]), cvt_pk_bf16(P[(b8) + 2], P[(b8) + 3]), cvt_pk_bf16(P[(b8) + 4], P[(b8) + 5]), cvt_pk_bf16(P[(b8) + 6], P[(b8) + 7])})
; __device__ __forceinline__ void attn_item(LAS unsigned char* lds, int b, int h, int qb, const bf16_t* Q, const bf16_t* KN, const bf16_t* KR, const bf16_t* VT, bf16_t* MIXIN, float* STAT2) {
;     ...
;             {
;                 const f32x2 mm = (f32x2){mrow, mrow}; f32x2 ssum = (f32x2){0.f, 0.f};
;                 const LAS unsigned char* vbase = lds + VOFF + vcur * VB + c * VP + hi * 16;
;     ...
; #pragma unroll
;                 for (int kk = 0; kk < 4; ++kk) {
;                     const bf16x8 vf0 = *(const LAS bf16x8*)(vbase + kk * 32), vf1 = *(const LAS bf16x8*)(vbase + 32 * VP + kk * 32);
;                     __builtin_amdgcn_sched_barrier(0);
;                     bf16x8 pfk;
;                     if (kk < 2) { AT_EXP2(p0, 8 * kk); AT_EXP2(p0, 8 * kk + 2); AT_EXP2(p0, 8 * kk + 4); AT_EXP2(p0, 8 * kk + 6); pfk = __builtin_bit_cast(bf16x8, AT_PACK(p0, 8 * kk)); }
;                     else { const int k2 = kk - 2; AT_EXP2(p1, 8 * k2); AT_EXP2(p1, 8 * k2 + 2); AT_EXP2(p1, 8 * k2 + 4); AT_EXP2(p1, 8 * k2 + 6); pfk = __builtin_bit_cast(bf16x8, AT_PACK(p1, 8 * k2)); }
;                     { const bf16x8 vf2 = *(const LAS bf16x8*)(vbase + 64 * VP + kk * 32), vf3 = *(const LAS bf16x8*)(vbase + 96 * VP + kk * 32);
;                       oT[0] = MFMA32(vf0, pfk, oT[0]); oT[1] = MFMA32(vf1, pfk, oT[1]); oT[2] = MFMA32(vf2, pfk, oT[2]); oT[3] = MFMA32(vf3, pfk, oT[3]); }
;                     __builtin_amdgcn_sched_barrier(0);
;                 }
;     ...
;                 lrow += ssum.x + ssum.y; }
.LBB0_967:
	s_mul_i32 s8, s45, 0x4800
	v_add_u32_e32 v2, s8, v220
	ds_read_b128 v[6:9], v2 offset:51200
	ds_read_b128 v[10:13], v2 offset:55808
	v_sub_f32_e32 v14, v98, v4
	v_sub_f32_e32 v15, v99, v4
	v_exp_f32_e32 v98, v14
	v_exp_f32_e32 v99, v15
	v_sub_f32_e32 v14, v100, v4
	v_sub_f32_e32 v15, v101, v4
	v_exp_f32_e32 v100, v14
	v_exp_f32_e32 v101, v15
	v_sub_f32_e32 v14, v102, v4
	v_sub_f32_e32 v15, v103, v4
	v_exp_f32_e32 v102, v14
	v_exp_f32_e32 v103, v15
	v_sub_f32_e32 v14, v104, v4
	v_sub_f32_e32 v15, v105, v4
	v_cvt_pk_bf16_f32 v16, v102, v103
	v_exp_f32_e32 v104, v14
	v_exp_f32_e32 v105, v15
	v_cvt_pk_bf16_f32 v14, v98, v99
	v_cvt_pk_bf16_f32 v15, v100, v101
	v_cvt_pk_bf16_f32 v17, v104, v105
	s_waitcnt lgkmcnt(1)
	s_nop 0
	v_mfma_f32_32x32x16_bf16 v[66:81], v[6:9], v[14:17], v[66:81]
	s_waitcnt lgkmcnt(0)
	v_mfma_f32_32x32x16_bf16 v[50:65], v[10:13], v[14:17], v[50:65]
	ds_read_b128 v[6:9], v2 offset:60416
	ds_read_b128 v[10:13], v2 offset:65024
	s_waitcnt lgkmcnt(1)
	v_mfma_f32_32x32x16_bf16 v[34:49], v[6:9], v[14:17], v[34:49]
	s_waitcnt lgkmcnt(0)
	v_mfma_f32_32x32x16_bf16 v[18:33], v[10:13], v[14:17], v[18:33]
	ds_read_b128 v[6:9], v2 offset:51232
	ds_read_b128 v[10:13], v2 offset:55840
	v_add_f32_e64 v14, v106, -v4
	v_add_f32_e64 v15, v107, -v4
	v_exp_f32_e32 v106, v14
	v_exp_f32_e32 v107, v15
	v_sub_f32_e32 v14, v108, v4
	v_sub_f32_e32 v15, v109, v4
	v_exp_f32_e32 v108, v14
	v_exp_f32_e32 v109, v15
	v_sub_f32_e32 v14, v110, v4
	v_sub_f32_e32 v15, v111, v4
	v_exp_f32_e32 v110, v14
	v_exp_f32_e32 v111, v15
	v_sub_f32_e32 v14, v112, v4
	v_sub_f32_e32 v15, v113, v4
	v_cvt_pk_bf16_f32 v16, v110, v111
	v_exp_f32_e32 v112, v14
	v_exp_f32_e32 v113, v15
	v_cvt_pk_bf16_f32 v14, v106, v107
	v_cvt_pk_bf16_f32 v15, v108, v109
	v_cvt_pk_bf16_f32 v17, v112, v113
	s_waitcnt lgkmcnt(1)
	s_nop 0
	v_mfma_f32_32x32x16_bf16 v[66:81], v[6:9], v[14:17], v[66:81]
	s_waitcnt lgkmcnt(0)
	v_mfma_f32_32x32x16_bf16 v[50:65], v[10:13], v[14:17], v[50:65]
	ds_read_b128 v[6:9], v2 offset:60448
	ds_read_b128 v[10:13], v2 offset:65056
	s_waitcnt lgkmcnt(1)
	v_mfma_f32_32x32x16_bf16 v[34:49], v[6:9], v[14:17], v[34:49]
	s_waitcnt lgkmcnt(0)
	v_mfma_f32_32x32x16_bf16 v[18:33], v[10:13], v[14:17], v[18:33]
	ds_read_b128 v[6:9], v2 offset:51264
	ds_read_b128 v[10:13], v2 offset:55872
	v_add_f32_e64 v14, v82, -v4
	v_add_f32_e64 v15, v83, -v4
	v_exp_f32_e32 v82, v14
	v_exp_f32_e32 v83, v15
	v_sub_f32_e32 v14, v84, v4
	v_sub_f32_e32 v15, v85, v4
	v_exp_f32_e32 v84, v14
	v_exp_f32_e32 v85, v15
	v_sub_f32_e32 v14, v86, v4
	v_sub_f32_e32 v15, v87, v4
	v_exp_f32_e32 v86, v14
	v_exp_f32_e32 v87, v15
	v_sub_f32_e32 v14, v88, v4
	v_sub_f32_e32 v15, v89, v4
	v_cvt_pk_bf16_f32 v16, v86, v87
	v_exp_f32_e32 v88, v14
	v_exp_f32_e32 v89, v15
	v_cvt_pk_bf16_f32 v14, v82, v83
	v_cvt_pk_bf16_f32 v15, v84, v85
	v_cvt_pk_bf16_f32 v17, v88, v89
	s_waitcnt lgkmcnt(1)
	s_nop 0
	v_mfma_f32_32x32x16_bf16 v[66:81], v[6:9], v[14:17], v[66:81]
	s_waitcnt lgkmcnt(0)
	v_mfma_f32_32x32x16_bf16 v[50:65], v[10:13], v[14:17], v[50:65]
	ds_read_b128 v[6:9], v2 offset:60480
	ds_read_b128 v[10:13], v2 offset:65088
	s_waitcnt lgkmcnt(1)
	v_mfma_f32_32x32x16_bf16 v[34:49], v[6:9], v[14:17], v[34:49]
	s_waitcnt lgkmcnt(0)
	v_mfma_f32_32x32x16_bf16 v[18:33], v[10:13], v[14:17], v[18:33]
	ds_read_b128 v[6:9], v2 offset:51296
	ds_read_b128 v[10:13], v2 offset:55904
	v_add_f32_e64 v14, v90, -v4
	v_add_f32_e64 v15, v91, -v4
	v_exp_f32_e32 v90, v14
	v_exp_f32_e32 v91, v15
	v_sub_f32_e32 v14, v92, v4
	v_sub_f32_e32 v15, v93, v4
	v_exp_f32_e32 v92, v14
	v_exp_f32_e32 v93, v15
	v_sub_f32_e32 v14, v94, v4
	v_sub_f32_e32 v15, v95, v4
	v_exp_f32_e32 v94, v14
	v_exp_f32_e32 v95, v15
	v_sub_f32_e32 v14, v96, v4
	v_sub_f32_e32 v15, v97, v4
	v_cvt_pk_bf16_f32 v16, v94, v95
	v_exp_f32_e32 v96, v14
	v_exp_f32_e32 v97, v15
	v_cvt_pk_bf16_f32 v14, v90, v91
	v_cvt_pk_bf16_f32 v15, v92, v93
	v_cvt_pk_bf16_f32 v17, v96, v97
	s_waitcnt lgkmcnt(1)
	s_nop 0
	v_mfma_f32_32x32x16_bf16 v[66:81], v[6:9], v[14:17], v[66:81]
	v_add_f32_e64 v6, v98, 0
	v_add_f32_e64 v7, v99, 0
	v_add_f32_e64 v6, v100, v6
	v_add_f32_e64 v7, v101, v7
	v_add_f32_e64 v98, v102, v6
	v_add_f32_e64 v99, v103, v7
	ds_read_b128 v[6:9], v2 offset:60512
	s_waitcnt lgkmcnt(1)
	v_mfma_f32_32x32x16_bf16 v[50:65], v[10:13], v[14:17], v[50:65]
	v_add_f32_e64 v10, v104, v98
	v_add_f32_e64 v11, v105, v99
	v_add_f32_e64 v10, v106, v10
	v_add_f32_e64 v11, v107, v11
	v_add_f32_e64 v10, v108, v10
	v_add_f32_e64 v11, v109, v11
	v_add_f32_e32 v10, v110, v10
	v_add_f32_e32 v11, v111, v11
	v_add_f32_e32 v10, v112, v10
	v_add_f32_e32 v11, v113, v11
	v_add_f32_e32 v82, v82, v10
	v_add_f32_e32 v83, v83, v11
	ds_read_b128 v[10:13], v2 offset:65120
	s_waitcnt lgkmcnt(1)
	v_mfma_f32_32x32x16_bf16 v[34:49], v[6:9], v[14:17], v[34:49]
	v_add_f32_e64 v6, v84, v82
	v_add_f32_e64 v7, v85, v83
	v_add_f32_e64 v6, v86, v6
	v_add_f32_e64 v7, v87, v7
	v_add_f32_e64 v6, v88, v6
	v_add_f32_e64 v7, v89, v7
	v_add_f32_e32 v6, v90, v6
	v_add_f32_e32 v7, v91, v7
	s_waitcnt lgkmcnt(0)
	v_mfma_f32_32x32x16_bf16 v[18:33], v[10:13], v[14:17], v[18:33]
	v_add_f32_e64 v6, v92, v6
	v_add_f32_e64 v7, v93, v7
	v_add_f32_e64 v6, v94, v6
	v_add_f32_e64 v7, v95, v7
	v_add_f32_e64 v6, v96, v6
	v_add_f32_e64 v7, v97, v7
	v_add_f32_e32 v2, v6, v7
	v_add_f32_e32 v5, v5, v2

; #define LAS __attribute__((address_space(3)))
; __global__ void __launch_bounds__(512, 2) fwd_kernel(Args a) {
;     ...
;     if (IN(1)) { pg8::Gemm g{(const bf16_t*)(ws + WS_U), (const bf16_t*)(ws + WS_WIN), M, PROJ_LD, DM, DM}; pg8::StaticOrder S; S.init(M, PROJ_LD, G, (int)blockIdx.x);
;         EpiStore E{(bf16_t*)(ws + WS_PROJ), PROJ_LD, (float*)(ws + WS_STAT), 4}; pg8::gemm_phase(lds, g, S, E);
;         deferred_weight_items(a, lds); } SEAM(1);
;     if (IN(2)) {
;         { pg8::Gemm g{(const bf16_t*)(ws + WS_PROJ) + P_CQ, (const bf16_t*)(ws + WS_WUQ), M, 1536, 512, PROJ_LD}; pg8::StaticOrder S; S.init(M, 1536, G, (int)blockIdx.x);
;           EpiQ E{(bf16_t*)(ws + WS_Q), (const float*)(ws + WS_STAT), (const f32x2*)(ws + WS_CS)}; pg8::gemm_phase(lds, g, S, E); }
;         { pg8::Gemm g{(const bf16_t*)(ws + WS_PROJ) + P_CKV, (const bf16_t*)(ws + WS_WUKV), M, 2048, 512, PROJ_LD}; pg8::StaticOrder S; S.init(M, 2048, G, (int)blockIdx.x);
;           EpiKV E{(bf16_t*)(ws + WS_KN), (bf16_t*)(ws + WS_VT), (const float*)(ws + WS_STAT)}; pg8::gemm_phase(lds, g, S, E); }
;         p2_krope(a);
;         p2_conv(a);
;     } SEAM(2);
;     if (IN(3)) {
;         unsigned* ctr = (unsigned*)(ws + WS_CTL); volatile LAS unsigned* misc = (volatile LAS unsigned*)(lds + LDS_MISC);
;         constexpr int N_SSD = BATCH * 16, N_ATT = BATCH * NH * 16;
;         int it;
;         for (;;) {
;             __syncthreads();
;             if (threadIdx.x == 0) misc[0] = atomicAdd(ctr, 1u);
;             __syncthreads();
;             it = (int)misc[0];
;             if (it >= N_SSD) break;
;             ssd_item(lds, it >> 4, it & 15, a);
;         }
;         while (it < N_SSD + N_ATT) {
;             const int r = it - N_SSD, qb = 15 - (r >> 6), bh = r & 63;
;             attn_item(lds, bh >> 3, bh & 7, qb, (const bf16_t*)(ws + WS_Q), (const bf16_t*)(ws + WS_KN), (const bf16_t*)(ws + WS_KR), (const bf16_t*)(ws + WS_VT), (bf16_t*)(ws + WS_MIXIN), a.out + STAT2_OFF);
;             __syncthreads();
;             if (threadIdx.x == 0) misc[0] = atomicAdd(ctr, 1u);
;             __syncthreads();
;             it = (int)misc[0];
;         }
;     } SEAM(3);
;     if (IN(5)) { pg8::Gemm g{(const bf16_t*)(ws + WS_MIXIN), (const bf16_t*)(ws + WS_WOUT), M, DM, DM, DM}; pg8::StaticOrder S; S.init(M, DM, G, (int)blockIdx.x);
.LBB0_1024:
	s_or_b64 exec, exec, s[0:1]
	s_waitcnt lgkmcnt(0)
	s_barrier
	s_mov_b32 s32, 0

; #define PG8_STAGE(bufoff, gbase, voff) do { _Pragma("unroll") for (int _i = 0; _i < 2; ++_i) \
;         __builtin_amdgcn_global_load_lds((const unsigned*)((const char*)(gbase) + (voff)[_i]), (LAS unsigned*)(lds + (bufoff) + ldsw + _i * 8192), 16, 0, 0); } while (0)
; #define PG8_LDA(dst, b, h) do { _Pragma("unroll") for (int m = 0; m < 4; ++m) _Pragma("unroll") for (int k = 0; k < 2; ++k) dst[m][k] = *(const LAS bf16x8*)(lds + PG8_SA(b, h) + aoff + m * 2048 + k * 1024); } while (0)
; #define PG8_MMA(ai, bj, At, Bt) do { __builtin_amdgcn_s_setprio(1); _Pragma("unroll") for (int m = 0; m < 4; ++m) _Pragma("unroll") for (int n = 0; n < 2; ++n) _Pragma("unroll") for (int k = 0; k < 2; ++k) \
;         acc[ai][bj][m][n] = __builtin_amdgcn_mfma_f32_16x16x32_bf16(Bt[n][k], At[m][k], acc[ai][bj][m][n], 0, 0, 0); __builtin_amdgcn_s_setprio(0); } while (0)
; #define PG8_WAIT_V(n) asm volatile("s_waitcnt vmcnt(" #n ")" ::: "memory")
; #define PG8_WAIT_L(n) asm volatile("s_waitcnt lgkmcnt(" #n ")" ::: "memory")
; #define PG8_BAR __builtin_amdgcn_s_barrier()
; #define PG8_SCHED __builtin_amdgcn_sched_barrier(0)
; template <class Epi, bool SEG = false>
; __device__ __forceinline__ void gemm_phase(LAS unsigned char* lds, const Gemm g, const StaticOrder& S, const Epi& E, const float* stat2 = nullptr) {
;     ...
;             PG8_WAIT_V(8); PG8_WAIT_L(0); PG8_BAR; PG8_MMA(0, 0, At, B0); PG8_MMA(0, 1, At, B1); PG8_BAR; PG8_SCHED;
;             PG8_LDA(At, 0, 1); PG8_STAGE(PG8_SB(0, 0), b2, voffB); PG8_STAGE(PG8_SB(0, 1), b2 + hstepB, voffB); PG8_STAGE(PG8_SA(0, 0), a2, voffA);
;             PG8_WAIT_V(8); PG8_WAIT_L(0); PG8_BAR; PG8_MMA(1, 0, At, B0); PG8_MMA(1, 1, At, B1); PG8_BAR; PG8_SCHED;
.Lt1_rx3_0:
	s_waitcnt vmcnt(16)
	s_branch .Lt1_j3_0
.Lt1_rx3_1:
	s_waitcnt vmcnt(16)
	s_mov_b32 s32, 0
	s_branch .Lt1_j3_1

; #define PG8_STAGE(bufoff, gbase, voff) do { _Pragma("unroll") for (int _i = 0; _i < 2; ++_i) \
;         __builtin_amdgcn_global_load_lds((const unsigned*)((const char*)(gbase) + (voff)[_i]), (LAS unsigned*)(lds + (bufoff) + ldsw + _i * 8192), 16, 0, 0); } while (0)
; #define PG8_LDA(dst, b, h) do { _Pragma("unroll") for (int m = 0; m < 4; ++m) _Pragma("unroll") for (int k = 0; k < 2; ++k) dst[m][k] = *(const LAS bf16x8*)(lds + PG8_SA(b, h) + aoff + m * 2048 + k * 1024); } while (0)
; #define PG8_LDB(dst, b, h) do { _Pragma("unroll") for (int n = 0; n < 2; ++n) _Pragma("unroll") for (int k = 0; k < 2; ++k) dst[n][k] = *(const LAS bf16x8*)(lds + PG8_SB(b, h) + boff + n * 2048 + k * 1024); } while (0)
; #define PG8_MMA(ai, bj, At, Bt) do { __builtin_amdgcn_s_setprio(1); _Pragma("unroll") for (int m = 0; m < 4; ++m) _Pragma("unroll") for (int n = 0; n < 2; ++n) _Pragma("unroll") for (int k = 0; k < 2; ++k) \
;         acc[ai][bj][m][n] = __builtin_amdgcn_mfma_f32_16x16x32_bf16(Bt[n][k], At[m][k], acc[ai][bj][m][n], 0, 0, 0); __builtin_amdgcn_s_setprio(0); } while (0)
; #define PG8_WAIT_V(n) asm volatile("s_waitcnt vmcnt(" #n ")" ::: "memory")
; #define PG8_WAIT_L(n) asm volatile("s_waitcnt lgkmcnt(" #n ")" ::: "memory")
; #define PG8_BAR __builtin_amdgcn_s_barrier()
; template <class Epi, bool SEG = false>
; __device__ __forceinline__ void gemm_phase(LAS unsigned char* lds, const Gemm g, const StaticOrder& S, const Epi& E, const float* stat2 = nullptr) {
;     ...
;         for (int t = tb; t < te; t += 2) {
;             const bool last = (t == nt - 2);
;             const char* a1 = cA + (size_t)(t + 1) * kstep;
;             const char* a2 = last ? nA : cA + (size_t)(t + 2) * kstep; const char* b2 = last ? nB : cB + (size_t)(t + 2) * kstep;
;             const char* a3 = a2 + kstep; const char* b3 = b2 + kstep;
;             PG8_LDB(B0, 0, 0); PG8_LDB(B1, 0, 1); PG8_SCHED; PG8_LDA(At, 0, 0); PG8_STAGE(PG8_SA(1, 1), a1 + hstepA, voffA);
;             PG8_WAIT_V(8); PG8_WAIT_L(0); PG8_BAR; PG8_MMA(0, 0, At, B0); PG8_MMA(0, 1, At, B1); PG8_BAR; PG8_SCHED;
;             PG8_LDA(At, 0, 1); PG8_STAGE(PG8_SB(0, 0), b2, voffB); PG8_STAGE(PG8_SB(0, 1), b2 + hstepB, voffB); PG8_STAGE(PG8_SA(0, 0), a2, voffA);
;             PG8_WAIT_V(8); PG8_WAIT_L(0); PG8_BAR; PG8_MMA(1, 0, At, B0); PG8_MMA(1, 1, At, B1); PG8_BAR; PG8_SCHED;
.LBB0_1207:
	ds_read_b128 v[152:155], v148
	ds_read_b128 v[156:159], v148 offset:1024
	ds_read_b128 v[160:163], v148 offset:2048
	ds_read_b128 v[164:167], v148 offset:3072
	ds_read_b128 v[168:171], v149
	ds_read_b128 v[172:175], v149 offset:1024
	ds_read_b128 v[176:179], v149 offset:2048
	ds_read_b128 v[180:183], v149 offset:3072
	s_add_u32 s24, s22, 0xfff80080
	s_addc_u32 s25, s23, -1
	s_cmp_eq_u32 s61, 28
	s_cselect_b32 s27, s15, s25
	s_cselect_b32 s26, s57, s24
	s_cselect_b32 s25, s13, s60
	s_cselect_b32 s24, s58, s59
	v_lshl_add_u64 v[216:217], s[22:23], 0, v[138:139]
	s_add_i32 m0, s21, 0xc000
	ds_read_b128 v[184:187], v150
	ds_read_b128 v[188:191], v150 offset:1024
	ds_read_b128 v[192:195], v150 offset:2048
	ds_read_b128 v[196:199], v150 offset:3072
	ds_read_b128 v[200:203], v150 offset:4096
	ds_read_b128 v[204:207], v150 offset:5120
	ds_read_b128 v[208:211], v150 offset:6144
	ds_read_b128 v[212:215], v150 offset:7168
	global_load_lds_dwordx4 v[216:217], off
	v_lshl_add_u64 v[216:217], s[22:23], 0, v[140:141]
	s_add_i32 m0, s21, 0xe000
	s_nop 0
	global_load_lds_dwordx4 v[216:217], off
	s_cmp_eq_u32 s32, 0
	s_cbranch_scc0 .Lt1_rx3_0
	s_waitcnt vmcnt(8)
.Lt1_j3_0:
	s_waitcnt lgkmcnt(0)
	s_barrier
	s_setprio 1
	s_waitcnt lgkmcnt(0)
	v_mfma_f32_16x16x32_bf16 v[126:129], v[152:155], v[184:187], v[126:129]
	v_mfma_f32_16x16x32_bf16 v[122:125], v[160:163], v[184:187], v[122:125]
	v_mfma_f32_16x16x32_bf16 v[110:113], v[152:155], v[192:195], v[110:113]
	v_mfma_f32_16x16x32_bf16 v[106:109], v[160:163], v[192:195], v[106:109]
	v_mfma_f32_16x16x32_bf16 v[94:97], v[152:155], v[200:203], v[94:97]
	v_mfma_f32_16x16x32_bf16 v[90:93], v[160:163], v[200:203], v[90:93]
	v_mfma_f32_16x16x32_bf16 v[78:81], v[152:155], v[208:211], v[78:81]
	v_mfma_f32_16x16x32_bf16 v[74:77], v[160:163], v[208:211], v[74:77]
	v_mfma_f32_16x16x32_bf16 v[126:129], v[156:159], v[188:191], v[126:129]
	v_mfma_f32_16x16x32_bf16 v[122:125], v[164:167], v[188:191], v[122:125]
	v_mfma_f32_16x16x32_bf16 v[110:113], v[156:159], v[196:199], v[110:113]
	v_mfma_f32_16x16x32_bf16 v[106:109], v[164:167], v[196:199], v[106:109]
	v_mfma_f32_16x16x32_bf16 v[94:97], v[156:159], v[204:207], v[94:97]
	v_mfma_f32_16x16x32_bf16 v[90:93], v[164:167], v[204:207], v[90:93]
	v_mfma_f32_16x16x32_bf16 v[78:81], v[156:159], v[212:215], v[78:81]
	v_mfma_f32_16x16x32_bf16 v[74:77], v[164:167], v[212:215], v[74:77]
	s_setprio 0
	s_setprio 1
	v_mfma_f32_16x16x32_bf16 v[118:121], v[168:171], v[184:187], v[118:121]
	v_mfma_f32_16x16x32_bf16 v[114:117], v[176:179], v[184:187], v[114:117]
	v_mfma_f32_16x16x32_bf16 v[102:105], v[168:171], v[192:195], v[102:105]
	v_mfma_f32_16x16x32_bf16 v[98:101], v[176:179], v[192:195], v[98:101]
	v_mfma_f32_16x16x32_bf16 v[86:89], v[168:171], v[200:203], v[86:89]
	v_mfma_f32_16x16x32_bf16 v[82:85], v[176:179], v[200:203], v[82:85]
	v_mfma_f32_16x16x32_bf16 v[70:73], v[168:171], v[208:211], v[70:73]
	v_mfma_f32_16x16x32_bf16 v[66:69], v[176:179], v[208:211], v[66:69]
	v_mfma_f32_16x16x32_bf16 v[118:121], v[172:175], v[188:191], v[118:121]
	v_mfma_f32_16x16x32_bf16 v[114:117], v[180:183], v[188:191], v[114:117]
	v_mfma_f32_16x16x32_bf16 v[102:105], v[172:175], v[196:199], v[102:105]
	v_mfma_f32_16x16x32_bf16 v[98:101], v[180:183], v[196:199], v[98:101]
	v_mfma_f32_16x16x32_bf16 v[86:89], v[172:175], v[204:207], v[86:89]
	v_mfma_f32_16x16x32_bf16 v[82:85], v[180:183], v[204:207], v[82:85]
	v_mfma_f32_16x16x32_bf16 v[70:73], v[172:175], v[212:215], v[70:73]
	v_mfma_f32_16x16x32_bf16 v[66:69], v[180:183], v[212:215], v[66:69]
	s_setprio 0
	s_barrier
	s_add_i32 s30, s53, s38
	v_lshl_add_u64 v[216:217], s[24:25], 0, v[134:135]
	s_mov_b32 m0, s30
	ds_read_b128 v[184:187], v150 offset:16384
	ds_read_b128 v[188:191], v150 offset:17408
	ds_read_b128 v[192:195], v150 offset:18432
	ds_read_b128 v[196:199], v150 offset:19456
	ds_read_b128 v[200:203], v150 offset:20480
	ds_read_b128 v[204:207], v150 offset:21504
	ds_read_b128 v[208:211], v150 offset:22528
	ds_read_b128 v[212:215], v150 offset:23552
	global_load_lds_dwordx4 v[216:217], off
	s_add_i32 m0, s30, 0x2000
	s_add_u32 s30, s24, 0x80000
	v_lshl_add_u64 v[218:219], s[24:25], 0, v[130:131]
	s_addc_u32 s31, s25, 0
	s_add_i32 s62, s54, s38
	global_load_lds_dwordx4 v[218:219], off
	v_lshl_add_u64 v[220:221], s[30:31], 0, v[134:135]
	s_mov_b32 m0, s62
	v_lshl_add_u64 v[222:223], s[26:27], 0, v[132:133]
	global_load_lds_dwordx4 v[220:221], off
	v_lshl_add_u64 v[220:221], s[30:31], 0, v[130:131]
	s_add_i32 m0, s62, 0x2000
	s_nop 0
	global_load_lds_dwordx4 v[220:221], off
	v_lshl_add_u64 v[220:221], s[26:27], 0, v[136:137]
	s_mov_b32 m0, s21
	s_nop 0
	global_load_lds_dwordx4 v[220:221], off
	s_mov_b32 m0, s33
	s_nop 0
	global_load_lds_dwordx4 v[222:223], off
	s_cmp_eq_u32 s32, 0
	s_cbranch_scc0 .Lt1_rx3_1
	s_waitcnt vmcnt(8)
; #define PG8_STAGE(bufoff, gbase, voff) do { _Pragma("unroll") for (int _i = 0; _i < 2; ++_i) \
;         __builtin_amdgcn_global_load_lds((const unsigned*)((const char*)(gbase) + (voff)[_i]), (LAS unsigned*)(lds + (bufoff) + ldsw + _i * 8192), 16, 0, 0); } while (0)
; #define PG8_LDA(dst, b, h) do { _Pragma("unroll") for (int m = 0; m < 4; ++m) _Pragma("unroll") for (int k = 0; k < 2; ++k) dst[m][k] = *(const LAS bf16x8*)(lds + PG8_SA(b, h) + aoff + m * 2048 + k * 1024); } while (0)
; #define PG8_LDB(dst, b, h) do { _Pragma("unroll") for (int n = 0; n < 2; ++n) _Pragma("unroll") for (int k = 0; k < 2; ++k) dst[n][k] = *(const LAS bf16x8*)(lds + PG8_SB(b, h) + boff + n * 2048 + k * 1024); } while (0)
; #define PG8_MMA(ai, bj, At, Bt) do { __builtin_amdgcn_s_setprio(1); _Pragma("unroll") for (int m = 0; m < 4; ++m) _Pragma("unroll") for (int n = 0; n < 2; ++n) _Pragma("unroll") for (int k = 0; k < 2; ++k) \
;         acc[ai][bj][m][n] = __builtin_amdgcn_mfma_f32_16x16x32_bf16(Bt[n][k], At[m][k], acc[ai][bj][m][n], 0, 0, 0); __builtin_amdgcn_s_setprio(0); } while (0)
; #define PG8_WAIT_V(n) asm volatile("s_waitcnt vmcnt(" #n ")" ::: "memory")
; #define PG8_WAIT_L(n) asm volatile("s_waitcnt lgkmcnt(" #n ")" ::: "memory")
; #define PG8_BAR __builtin_amdgcn_s_barrier()
; #define PG8_SCHED __builtin_amdgcn_sched_barrier(0)
; template <class Epi, bool SEG = false>
; __device__ __forceinline__ void gemm_phase(LAS unsigned char* lds, const Gemm g, const StaticOrder& S, const Epi& E, const float* stat2 = nullptr) {
;     ...
;             PG8_WAIT_V(8); PG8_WAIT_L(0); PG8_BAR; PG8_MMA(1, 0, At, B0); PG8_MMA(1, 1, At, B1); PG8_BAR; PG8_SCHED;
;             PG8_LDB(B0, 1, 0); PG8_LDB(B1, 1, 1); PG8_SCHED; PG8_LDA(At, 1, 0); PG8_STAGE(PG8_SA(0, 1), a2 + hstepA, voffA);
;             PG8_WAIT_V(8); PG8_WAIT_L(0); PG8_BAR; PG8_MMA(0, 0, At, B0); PG8_MMA(0, 1, At, B1); PG8_BAR; PG8_SCHED;
;             PG8_LDA(At, 1, 1); PG8_STAGE(PG8_SB(1, 0), b3, voffB); PG8_STAGE(PG8_SB(1, 1), b3 + hstepB, voffB); PG8_STAGE(PG8_SA(1, 0), a3, voffA);
;             PG8_WAIT_V(8); PG8_WAIT_L(0); PG8_BAR; PG8_MMA(1, 0, At, B0); PG8_MMA(1, 1, At, B1); PG8_BAR; PG8_SCHED;
.Lt1_j3_1:
	s_waitcnt lgkmcnt(0)
	s_barrier
	s_setprio 1
	s_waitcnt lgkmcnt(0)
	v_mfma_f32_16x16x32_bf16 v[62:65], v[152:155], v[184:187], v[62:65]
	v_mfma_f32_16x16x32_bf16 v[58:61], v[160:163], v[184:187], v[58:61]
	v_mfma_f32_16x16x32_bf16 v[46:49], v[152:155], v[192:195], v[46:49]
	v_mfma_f32_16x16x32_bf16 v[42:45], v[160:163], v[192:195], v[42:45]
	v_mfma_f32_16x16x32_bf16 v[30:33], v[152:155], v[200:203], v[30:33]
	v_mfma_f32_16x16x32_bf16 v[26:29], v[160:163], v[200:203], v[26:29]
	v_mfma_f32_16x16x32_bf16 v[14:17], v[152:155], v[208:211], v[14:17]
	v_mfma_f32_16x16x32_bf16 v[10:13], v[160:163], v[208:211], v[10:13]
	v_mfma_f32_16x16x32_bf16 v[62:65], v[156:159], v[188:191], v[62:65]
	v_mfma_f32_16x16x32_bf16 v[58:61], v[164:167], v[188:191], v[58:61]
	v_mfma_f32_16x16x32_bf16 v[46:49], v[156:159], v[196:199], v[46:49]
	v_mfma_f32_16x16x32_bf16 v[42:45], v[164:167], v[196:199], v[42:45]
	v_mfma_f32_16x16x32_bf16 v[30:33], v[156:159], v[204:207], v[30:33]
	v_mfma_f32_16x16x32_bf16 v[26:29], v[164:167], v[204:207], v[26:29]
	v_mfma_f32_16x16x32_bf16 v[14:17], v[156:159], v[212:215], v[14:17]
	v_mfma_f32_16x16x32_bf16 v[10:13], v[164:167], v[212:215], v[10:13]
	s_setprio 0
	s_setprio 1
	v_mfma_f32_16x16x32_bf16 v[54:57], v[168:171], v[184:187], v[54:57]
	v_mfma_f32_16x16x32_bf16 v[50:53], v[176:179], v[184:187], v[50:53]
	v_mfma_f32_16x16x32_bf16 v[38:41], v[168:171], v[192:195], v[38:41]
	v_mfma_f32_16x16x32_bf16 v[34:37], v[176:179], v[192:195], v[34:37]
	v_mfma_f32_16x16x32_bf16 v[22:25], v[168:171], v[200:203], v[22:25]
	v_mfma_f32_16x16x32_bf16 v[18:21], v[176:179], v[200:203], v[18:21]
	v_mfma_f32_16x16x32_bf16 v[6:9], v[168:171], v[208:211], v[6:9]
	v_mfma_f32_16x16x32_bf16 v[2:5], v[176:179], v[208:211], v[2:5]
	v_mfma_f32_16x16x32_bf16 v[54:57], v[172:175], v[188:191], v[54:57]
	v_mfma_f32_16x16x32_bf16 v[50:53], v[180:183], v[188:191], v[50:53]
	v_mfma_f32_16x16x32_bf16 v[38:41], v[172:175], v[196:199], v[38:41]
	v_mfma_f32_16x16x32_bf16 v[34:37], v[180:183], v[196:199], v[34:37]
	v_mfma_f32_16x16x32_bf16 v[22:25], v[172:175], v[204:207], v[22:25]
	v_mfma_f32_16x16x32_bf16 v[18:21], v[180:183], v[204:207], v[18:21]
	v_mfma_f32_16x16x32_bf16 v[6:9], v[172:175], v[212:215], v[6:9]
	v_mfma_f32_16x16x32_bf16 v[2:5], v[180:183], v[212:215], v[2:5]
	s_setprio 0
	s_barrier
	s_add_i32 s30, 0, 0x18000
	v_add_u32_e32 v151, s30, v146
	s_add_i32 s31, 0, 0x1c000
	ds_read_b128 v[152:155], v151
	ds_read_b128 v[156:159], v151 offset:1024
	ds_read_b128 v[160:163], v151 offset:2048
	ds_read_b128 v[164:167], v151 offset:3072
	v_add_u32_e32 v151, s31, v146
	ds_read_b128 v[168:171], v151
	ds_read_b128 v[172:175], v151 offset:1024
	ds_read_b128 v[176:179], v151 offset:2048
	ds_read_b128 v[180:183], v151 offset:3072
	s_add_u32 s26, s26, 0x80000
	s_addc_u32 s27, s27, 0
	s_mov_b32 m0, s43
	v_lshl_add_u64 v[224:225], s[26:27], 0, v[136:137]
	ds_read_b128 v[184:187], v150 offset:32768
	ds_read_b128 v[188:191], v150 offset:33792
	ds_read_b128 v[192:195], v150 offset:34816
	ds_read_b128 v[196:199], v150 offset:35840
	ds_read_b128 v[200:203], v150 offset:36864
	ds_read_b128 v[204:207], v150 offset:37888
	ds_read_b128 v[208:211], v150 offset:38912
	ds_read_b128 v[212:215], v150 offset:39936
	global_load_lds_dwordx4 v[224:225], off
	v_lshl_add_u64 v[224:225], s[26:27], 0, v[132:133]
	s_mov_b32 m0, s44
	s_nop 0
	global_load_lds_dwordx4 v[224:225], off
	s_waitcnt vmcnt(8)
	s_waitcnt lgkmcnt(0)
	s_barrier
	s_setprio 1
	s_waitcnt lgkmcnt(0)
	v_mfma_f32_16x16x32_bf16 v[126:129], v[152:155], v[184:187], v[126:129]
	v_mfma_f32_16x16x32_bf16 v[122:125], v[160:163], v[184:187], v[122:125]
	v_mfma_f32_16x16x32_bf16 v[110:113], v[152:155], v[192:195], v[110:113]
	v_mfma_f32_16x16x32_bf16 v[106:109], v[160:163], v[192:195], v[106:109]
	v_mfma_f32_16x16x32_bf16 v[94:97], v[152:155], v[200:203], v[94:97]
	v_mfma_f32_16x16x32_bf16 v[90:93], v[160:163], v[200:203], v[90:93]
	v_mfma_f32_16x16x32_bf16 v[78:81], v[152:155], v[208:211], v[78:81]
	v_mfma_f32_16x16x32_bf16 v[74:77], v[160:163], v[208:211], v[74:77]
	v_mfma_f32_16x16x32_bf16 v[126:129], v[156:159], v[188:191], v[126:129]
	v_mfma_f32_16x16x32_bf16 v[122:125], v[164:167], v[188:191], v[122:125]
	v_mfma_f32_16x16x32_bf16 v[110:113], v[156:159], v[196:199], v[110:113]
	v_mfma_f32_16x16x32_bf16 v[106:109], v[164:167], v[196:199], v[106:109]
	v_mfma_f32_16x16x32_bf16 v[94:97], v[156:159], v[204:207], v[94:97]
	v_mfma_f32_16x16x32_bf16 v[90:93], v[164:167], v[204:207], v[90:93]
	v_mfma_f32_16x16x32_bf16 v[78:81], v[156:159], v[212:215], v[78:81]
	v_mfma_f32_16x16x32_bf16 v[74:77], v[164:167], v[212:215], v[74:77]
	s_setprio 0
	s_setprio 1
	v_mfma_f32_16x16x32_bf16 v[118:121], v[168:171], v[184:187], v[118:121]
	v_mfma_f32_16x16x32_bf16 v[114:117], v[176:179], v[184:187], v[114:117]
	v_mfma_f32_16x16x32_bf16 v[102:105], v[168:171], v[192:195], v[102:105]
	v_mfma_f32_16x16x32_bf16 v[98:101], v[176:179], v[192:195], v[98:101]
	v_mfma_f32_16x16x32_bf16 v[86:89], v[168:171], v[200:203], v[86:89]
	v_mfma_f32_16x16x32_bf16 v[82:85], v[176:179], v[200:203], v[82:85]
	v_mfma_f32_16x16x32_bf16 v[70:73], v[168:171], v[208:211], v[70:73]
	v_mfma_f32_16x16x32_bf16 v[66:69], v[176:179], v[208:211], v[66:69]
	v_mfma_f32_16x16x32_bf16 v[118:121], v[172:175], v[188:191], v[118:121]
	v_mfma_f32_16x16x32_bf16 v[114:117], v[180:183], v[188:191], v[114:117]
	v_mfma_f32_16x16x32_bf16 v[102:105], v[172:175], v[196:199], v[102:105]
	v_mfma_f32_16x16x32_bf16 v[98:101], v[180:183], v[196:199], v[98:101]
	v_mfma_f32_16x16x32_bf16 v[86:89], v[172:175], v[204:207], v[86:89]
	v_mfma_f32_16x16x32_bf16 v[82:85], v[180:183], v[204:207], v[82:85]
	v_mfma_f32_16x16x32_bf16 v[70:73], v[172:175], v[212:215], v[70:73]
	v_mfma_f32_16x16x32_bf16 v[66:69], v[180:183], v[212:215], v[66:69]
	s_setprio 0
	s_barrier
; __device__ __forceinline__ float silu_f(float v) { return v * __builtin_amdgcn_rcpf(1.0f + __expf(-v)); }
; #define PG8_STAGE(bufoff, gbase, voff) do { _Pragma("unroll") for (int _i = 0; _i < 2; ++_i) \
;         __builtin_amdgcn_global_load_lds((const unsigned*)((const char*)(gbase) + (voff)[_i]), (LAS unsigned*)(lds + (bufoff) + ldsw + _i * 8192), 16, 0, 0); } while (0)
; #define PG8_LDA(dst, b, h) do { _Pragma("unroll") for (int m = 0; m < 4; ++m) _Pragma("unroll") for (int k = 0; k < 2; ++k) dst[m][k] = *(const LAS bf16x8*)(lds + PG8_SA(b, h) + aoff + m * 2048 + k * 1024); } while (0)
; #define PG8_MMA(ai, bj, At, Bt) do { __builtin_amdgcn_s_setprio(1); _Pragma("unroll") for (int m = 0; m < 4; ++m) _Pragma("unroll") for (int n = 0; n < 2; ++n) _Pragma("unroll") for (int k = 0; k < 2; ++k) \
;         acc[ai][bj][m][n] = __builtin_amdgcn_mfma_f32_16x16x32_bf16(Bt[n][k], At[m][k], acc[ai][bj][m][n], 0, 0, 0); __builtin_amdgcn_s_setprio(0); } while (0)
; #define PG8_WAIT_V(n) asm volatile("s_waitcnt vmcnt(" #n ")" ::: "memory")
; #define PG8_WAIT_L(n) asm volatile("s_waitcnt lgkmcnt(" #n ")" ::: "memory")
; #define PG8_BAR __builtin_amdgcn_s_barrier()
; #define PG8_SCHED __builtin_amdgcn_sched_barrier(0)
; template <class Epi, bool SEG = false>
; __device__ __forceinline__ void gemm_phase(LAS unsigned char* lds, const Gemm g, const StaticOrder& S, const Epi& E, const float* stat2 = nullptr) {
;     ...
;             PG8_LDA(At, 1, 1); PG8_STAGE(PG8_SB(1, 0), b3, voffB); PG8_STAGE(PG8_SB(1, 1), b3 + hstepB, voffB); PG8_STAGE(PG8_SA(1, 0), a3, voffA);
;             PG8_WAIT_V(8); PG8_WAIT_L(0); PG8_BAR; PG8_MMA(1, 0, At, B0); PG8_MMA(1, 1, At, B1); PG8_BAR; PG8_SCHED;
;         }
;         }
;         if (wr == 0) PG8_BAR;
;         if constexpr (SEG) seg_scale(acc, lds, ui & 1, 2, wr, fr);
;         E(acc, cur, wr, wc, fr, fq);
;         if constexpr (SEG) { if (has_next) seg_fill(lds, stat2, nxt.pm, (ui + 1) & 1); }
;         if (!has_next) break;
;     __device__ __forceinline__ void operator()(const Acc& acc, const pg8::Unit& u, int wr, int wc, int fr, int fq) const {
;     ...
;                     for (int i = 0; i < 4; ++i) o[n][i] = silu_f(acc[ai][0][m][n][i]) * acc[ai][1][m][n][i];
;                 *(u32x4*)(ACT + (size_t)row * DFF + col0) = pack8(o[0], o[1]);
	s_add_i32 s26, s30, s38
	v_lshl_add_u64 v[216:217], v[216:217], 0, s[8:9]
	s_mov_b32 m0, s26
	ds_read_b128 v[184:187], v150 offset:49152
	ds_read_b128 v[188:191], v150 offset:50176
	ds_read_b128 v[192:195], v150 offset:51200
	ds_read_b128 v[196:199], v150 offset:52224
	ds_read_b128 v[200:203], v150 offset:53248
	ds_read_b128 v[204:207], v150 offset:54272
	ds_read_b128 v[208:211], v150 offset:55296
	ds_read_b128 v[212:215], v150 offset:56320
	global_load_lds_dwordx4 v[216:217], off
	s_add_i32 m0, s26, 0x2000
	s_add_u32 s24, s24, 0x80080
	v_lshl_add_u64 v[216:217], v[218:219], 0, s[8:9]
	s_addc_u32 s25, s25, 0
	s_add_i32 s26, s31, s38
	global_load_lds_dwordx4 v[216:217], off
	v_lshl_add_u64 v[216:217], s[24:25], 0, v[134:135]
	s_mov_b32 m0, s26
	s_nop 0
	global_load_lds_dwordx4 v[216:217], off
	v_lshl_add_u64 v[216:217], s[24:25], 0, v[130:131]
	s_add_i32 m0, s26, 0x2000
	s_nop 0
	global_load_lds_dwordx4 v[216:217], off
	v_lshl_add_u64 v[216:217], v[220:221], 0, s[8:9]
	s_mov_b32 m0, s46
	s_nop 0
	global_load_lds_dwordx4 v[216:217], off
	v_lshl_add_u64 v[216:217], v[222:223], 0, s[8:9]
	s_mov_b32 m0, s47
	s_nop 0
	global_load_lds_dwordx4 v[216:217], off
	s_waitcnt vmcnt(8)
	s_waitcnt lgkmcnt(0)
	s_barrier
	s_setprio 1
	s_waitcnt lgkmcnt(0)
	v_mfma_f32_16x16x32_bf16 v[62:65], v[152:155], v[184:187], v[62:65]
	v_mfma_f32_16x16x32_bf16 v[58:61], v[160:163], v[184:187], v[58:61]
	v_mfma_f32_16x16x32_bf16 v[46:49], v[152:155], v[192:195], v[46:49]
	v_mfma_f32_16x16x32_bf16 v[42:45], v[160:163], v[192:195], v[42:45]
	v_mfma_f32_16x16x32_bf16 v[30:33], v[152:155], v[200:203], v[30:33]
	v_mfma_f32_16x16x32_bf16 v[26:29], v[160:163], v[200:203], v[26:29]
	v_mfma_f32_16x16x32_bf16 v[14:17], v[152:155], v[208:211], v[14:17]
	v_mfma_f32_16x16x32_bf16 v[10:13], v[160:163], v[208:211], v[10:13]
	v_mfma_f32_16x16x32_bf16 v[62:65], v[156:159], v[188:191], v[62:65]
	v_mfma_f32_16x16x32_bf16 v[58:61], v[164:167], v[188:191], v[58:61]
	v_mfma_f32_16x16x32_bf16 v[46:49], v[156:159], v[196:199], v[46:49]
	v_mfma_f32_16x16x32_bf16 v[42:45], v[164:167], v[196:199], v[42:45]
	v_mfma_f32_16x16x32_bf16 v[30:33], v[156:159], v[204:207], v[30:33]
	v_mfma_f32_16x16x32_bf16 v[26:29], v[164:167], v[204:207], v[26:29]
	v_mfma_f32_16x16x32_bf16 v[14:17], v[156:159], v[212:215], v[14:17]
	v_mfma_f32_16x16x32_bf16 v[10:13], v[164:167], v[212:215], v[10:13]
	s_setprio 0
	s_setprio 1
	v_mfma_f32_16x16x32_bf16 v[54:57], v[168:171], v[184:187], v[54:57]
	v_mfma_f32_16x16x32_bf16 v[50:53], v[176:179], v[184:187], v[50:53]
	v_mfma_f32_16x16x32_bf16 v[38:41], v[168:171], v[192:195], v[38:41]
	v_mfma_f32_16x16x32_bf16 v[34:37], v[176:179], v[192:195], v[34:37]
	v_mfma_f32_16x16x32_bf16 v[22:25], v[168:171], v[200:203], v[22:25]
	v_mfma_f32_16x16x32_bf16 v[18:21], v[176:179], v[200:203], v[18:21]
	v_mfma_f32_16x16x32_bf16 v[6:9], v[168:171], v[208:211], v[6:9]
	v_mfma_f32_16x16x32_bf16 v[2:5], v[176:179], v[208:211], v[2:5]
	v_mfma_f32_16x16x32_bf16 v[54:57], v[172:175], v[188:191], v[54:57]
	v_mfma_f32_16x16x32_bf16 v[50:53], v[180:183], v[188:191], v[50:53]
	v_mfma_f32_16x16x32_bf16 v[38:41], v[172:175], v[196:199], v[38:41]
	v_mfma_f32_16x16x32_bf16 v[34:37], v[180:183], v[196:199], v[34:37]
	v_mfma_f32_16x16x32_bf16 v[22:25], v[172:175], v[204:207], v[22:25]
	v_mfma_f32_16x16x32_bf16 v[18:21], v[180:183], v[204:207], v[18:21]
	v_mfma_f32_16x16x32_bf16 v[6:9], v[172:175], v[212:215], v[6:9]
	v_mfma_f32_16x16x32_bf16 v[2:5], v[180:183], v[212:215], v[2:5]
	s_setprio 0
	s_barrier
	s_add_i32 s61, s61, 2
	s_add_u32 s22, s22, 0x100
	s_addc_u32 s23, s23, 0
	s_add_u32 s59, s59, 0x100
	s_addc_u32 s60, s60, 0
	s_cmp_gt_u32 s61, 29
	s_cbranch_scc0 .LBB0_1207
	s_and_b64 vcc, exec, s[10:11]
	s_cbranch_vccz .LBB0_1210
	s_barrier
.LBB0_1210:
	s_mov_b32 s32, 1
	v_mul_f32_e32 v151, 0xbfb8aa3b, v126
	v_mul_f32_e32 v152, 0xbfb8aa3b, v127
	v_exp_f32_e32 v151, v151
	v_exp_f32_e32 v152, v152
	v_lshl_or_b32 v154, s56, 7, v147
	v_ashrrev_i32_e32 v155, 31, v154
	v_add_f32_e32 v151, 1.0, v151
	v_add_f32_e32 v153, 1.0, v152
	v_rcp_f32_e32 v152, v151
	v_rcp_f32_e32 v153, v153
	v_lshl_add_u32 v151, s20, 8, v1
	s_andn2_b64 vcc, exec, s[0:1]
	s_mov_b64 s[0:1], -1
	v_pk_mul_f32 v[126:127], v[126:127], v[152:153]
	v_mul_f32_e32 v152, 0xbfb8aa3b, v128
	v_mul_f32_e32 v153, 0xbfb8aa3b, v129
	v_exp_f32_e32 v152, v152
	v_exp_f32_e32 v153, v153
	v_pk_mul_f32 v[118:119], v[126:127], v[118:119]
	v_add_f32_e32 v126, 1.0, v152
	v_add_f32_e32 v127, 1.0, v153
	v_mul_f32_e32 v152, 0xbfb8aa3b, v122
	v_mul_f32_e32 v153, 0xbfb8aa3b, v123
	v_rcp_f32_e32 v126, v126
	v_rcp_f32_e32 v127, v127
	v_exp_f32_e32 v152, v152
	v_exp_f32_e32 v153, v153
	v_cvt_pk_bf16_f32 v118, v118, v119
	v_pk_mul_f32 v[126:127], v[128:129], v[126:127]
	v_add_f32_e32 v128, 1.0, v152
	v_add_f32_e32 v129, 1.0, v153
	v_mul_f32_e32 v152, 0xbfb8aa3b, v124
	v_mul_f32_e32 v153, 0xbfb8aa3b, v125
	v_exp_f32_e32 v152, v152
	v_exp_f32_e32 v153, v153
	v_rcp_f32_e32 v128, v128
	v_rcp_f32_e32 v129, v129
	v_add_f32_e32 v152, 1.0, v152
	v_add_f32_e32 v153, 1.0, v153
	v_rcp_f32_e32 v152, v152
	v_rcp_f32_e32 v153, v153
	v_pk_mul_f32 v[122:123], v[122:123], v[128:129]
	v_pk_mul_f32 v[120:121], v[126:127], v[120:121]
	v_pk_mul_f32 v[114:115], v[122:123], v[114:115]
	v_pk_mul_f32 v[122:123], v[124:125], v[152:153]
	v_cvt_pk_bf16_f32 v119, v120, v121
	v_pk_mul_f32 v[116:117], v[122:123], v[116:117]
	v_cvt_pk_bf16_f32 v120, v114, v115
	v_cvt_pk_bf16_f32 v121, v116, v117
	v_mul_f32_e32 v116, 0xbfb8aa3b, v110
	v_exp_f32_e32 v116, v116
	v_mul_f32_e32 v117, 0xbfb8aa3b, v111
	v_exp_f32_e32 v117, v117
	v_mov_b64_e32 v[114:115], s[6:7]
	v_add_f32_e32 v116, 1.0, v116
	v_rcp_f32_e32 v124, v116
; __device__ __forceinline__ float silu_f(float v) { return v * __builtin_amdgcn_rcpf(1.0f + __expf(-v)); }
;     __device__ __forceinline__ void operator()(const Acc& acc, const pg8::Unit& u, int wr, int wc, int fr, int fq) const {
;         const int row0 = u.pm * 256 + wr * 64 + fr, col0 = u.pn * 128 + wc * 32 + 8 * fq;
; #pragma unroll
;         for (int ai = 0; ai < 2; ++ai)
; #pragma unroll
;             for (int m = 0; m < 4; ++m) {
;                 const int row = row0 + ai * 128 + m * 16; f32x4 o[2];
; #pragma unroll
;                 for (int n = 0; n < 2; ++n)
; #pragma unroll
;                     for (int i = 0; i < 4; ++i) o[n][i] = silu_f(acc[ai][0][m][n][i]) * acc[ai][1][m][n][i];
;                 *(u32x4*)(ACT + (size_t)row * DFF + col0) = pack8(o[0], o[1]);
	v_add_f32_e32 v116, 1.0, v117
	v_mad_i64_i32 v[122:123], s[22:23], v151, s55, v[114:115]
	v_rcp_f32_e32 v125, v116
	v_lshlrev_b64 v[116:117], 1, v[154:155]
	v_lshl_add_u64 v[122:123], v[122:123], 0, v[116:117]
	global_store_dwordx4 v[122:123], v[118:121], off
	v_pk_mul_f32 v[110:111], v[110:111], v[124:125]
	s_nop 0
	v_mul_f32_e32 v118, 0xbfb8aa3b, v112
	v_mul_f32_e32 v119, 0xbfb8aa3b, v113
	v_exp_f32_e32 v118, v118
	v_exp_f32_e32 v119, v119
	v_pk_mul_f32 v[102:103], v[110:111], v[102:103]
	v_add_f32_e32 v110, 1.0, v118
	v_add_f32_e32 v111, 1.0, v119
	v_mul_f32_e32 v118, 0xbfb8aa3b, v106
	v_mul_f32_e32 v119, 0xbfb8aa3b, v107
	v_rcp_f32_e32 v110, v110
	v_rcp_f32_e32 v111, v111
	v_exp_f32_e32 v118, v118
	v_exp_f32_e32 v119, v119
	v_pk_mul_f32 v[110:111], v[112:113], v[110:111]
	v_add_f32_e32 v112, 1.0, v118
	v_add_f32_e32 v113, 1.0, v119
	v_mul_f32_e32 v118, 0xbfb8aa3b, v108
	v_mul_f32_e32 v119, 0xbfb8aa3b, v109
	v_exp_f32_e32 v118, v118
	v_exp_f32_e32 v119, v119
	v_rcp_f32_e32 v112, v112
	v_rcp_f32_e32 v113, v113
	v_add_f32_e32 v118, 1.0, v118
	v_add_f32_e32 v119, 1.0, v119
	v_rcp_f32_e32 v118, v118
	v_rcp_f32_e32 v119, v119
	v_pk_mul_f32 v[106:107], v[106:107], v[112:113]
	v_pk_mul_f32 v[104:105], v[110:111], v[104:105]
	v_pk_mul_f32 v[106:107], v[106:107], v[98:99]
	v_pk_mul_f32 v[98:99], v[108:109], v[118:119]
	v_or_b32_e32 v110, 16, v151
	v_pk_mul_f32 v[108:109], v[98:99], v[100:101]
	v_mul_f32_e32 v101, 0xbfb8aa3b, v94
	v_cvt_pk_bf16_f32 v98, v102, v103
	v_exp_f32_e32 v102, v101
	v_mul_f32_e32 v101, 0xbfb8aa3b, v95
	v_exp_f32_e32 v103, v101
	v_cvt_pk_bf16_f32 v99, v104, v105
	v_mad_i64_i32 v[104:105], s[22:23], v110, s55, v[114:115]
	v_cvt_pk_bf16_f32 v100, v106, v107
	v_cvt_pk_bf16_f32 v101, v108, v109
	v_add_f32_e32 v102, 1.0, v102
	v_add_f32_e32 v103, 1.0, v103
	v_lshl_add_u64 v[104:105], v[104:105], 0, v[116:117]
	v_rcp_f32_e32 v102, v102
	v_rcp_f32_e32 v103, v103
	global_store_dwordx4 v[104:105], v[98:101], off
	v_pk_mul_f32 v[94:95], v[94:95], v[102:103]
	s_nop 0
	v_mul_f32_e32 v98, 0xbfb8aa3b, v96
	v_mul_f32_e32 v99, 0xbfb8aa3b, v97
	v_exp_f32_e32 v98, v98
	v_exp_f32_e32 v99, v99
	v_pk_mul_f32 v[86:87], v[94:95], v[86:87]
	v_add_f32_e32 v94, 1.0, v98
	v_add_f32_e32 v95, 1.0, v99
	v_mul_f32_e32 v98, 0xbfb8aa3b, v90
	v_mul_f32_e32 v99, 0xbfb8aa3b, v91
	v_rcp_f32_e32 v94, v94
	v_rcp_f32_e32 v95, v95
	v_exp_f32_e32 v98, v98
	v_exp_f32_e32 v99, v99
	v_pk_mul_f32 v[94:95], v[96:97], v[94:95]
	v_add_f32_e32 v96, 1.0, v98
	v_add_f32_e32 v97, 1.0, v99
	v_mul_f32_e32 v98, 0xbfb8aa3b, v92
	v_mul_f32_e32 v99, 0xbfb8aa3b, v93
	v_exp_f32_e32 v98, v98
	v_exp_f32_e32 v99, v99
	v_rcp_f32_e32 v96, v96
	v_rcp_f32_e32 v97, v97
	v_add_f32_e32 v98, 1.0, v98
	v_add_f32_e32 v99, 1.0, v99
	v_rcp_f32_e32 v98, v98
	v_rcp_f32_e32 v99, v99
	v_pk_mul_f32 v[90:91], v[90:91], v[96:97]
	v_pk_mul_f32 v[88:89], v[94:95], v[88:89]
	v_pk_mul_f32 v[90:91], v[90:91], v[82:83]
	v_pk_mul_f32 v[82:83], v[92:93], v[98:99]
	v_or_b32_e32 v94, 32, v151
	v_pk_mul_f32 v[92:93], v[82:83], v[84:85]
	v_mul_f32_e32 v85, 0xbfb8aa3b, v78
	v_cvt_pk_bf16_f32 v82, v86, v87
	v_exp_f32_e32 v86, v85
	v_mul_f32_e32 v85, 0xbfb8aa3b, v79
	v_exp_f32_e32 v87, v85
	v_cvt_pk_bf16_f32 v83, v88, v89
	v_mad_i64_i32 v[88:89], s[22:23], v94, s55, v[114:115]
	v_cvt_pk_bf16_f32 v84, v90, v91
	v_cvt_pk_bf16_f32 v85, v92, v93
	v_add_f32_e32 v86, 1.0, v86
	v_add_f32_e32 v87, 1.0, v87
	v_lshl_add_u64 v[88:89], v[88:89], 0, v[116:117]
	v_rcp_f32_e32 v86, v86
	v_rcp_f32_e32 v87, v87
	global_store_dwordx4 v[88:89], v[82:85], off
	v_pk_mul_f32 v[78:79], v[78:79], v[86:87]
	s_nop 0
	v_mul_f32_e32 v82, 0xbfb8aa3b, v80
	v_mul_f32_e32 v83, 0xbfb8aa3b, v81
	v_exp_f32_e32 v82, v82
	v_exp_f32_e32 v83, v83
	v_pk_mul_f32 v[70:71], v[78:79], v[70:71]
	v_add_f32_e32 v78, 1.0, v82
	v_add_f32_e32 v79, 1.0, v83
	v_mul_f32_e32 v82, 0xbfb8aa3b, v74
	v_mul_f32_e32 v83, 0xbfb8aa3b, v75
	v_rcp_f32_e32 v78, v78
	v_rcp_f32_e32 v79, v79
	v_exp_f32_e32 v82, v82
	v_exp_f32_e32 v83, v83
	v_pk_mul_f32 v[78:79], v[80:81], v[78:79]
	v_add_f32_e32 v80, 1.0, v82
	v_add_f32_e32 v81, 1.0, v83
	v_mul_f32_e32 v82, 0xbfb8aa3b, v76
	v_mul_f32_e32 v83, 0xbfb8aa3b, v77
	v_exp_f32_e32 v82, v82
	v_exp_f32_e32 v83, v83
	v_rcp_f32_e32 v80, v80
	v_rcp_f32_e32 v81, v81
	v_add_f32_e32 v82, 1.0, v82
	v_add_f32_e32 v83, 1.0, v83
	v_rcp_f32_e32 v82, v82
	v_rcp_f32_e32 v83, v83
	v_pk_mul_f32 v[74:75], v[74:75], v[80:81]
	v_pk_mul_f32 v[72:73], v[78:79], v[72:73]
	v_pk_mul_f32 v[74:75], v[74:75], v[66:67]
	v_pk_mul_f32 v[66:67], v[76:77], v[82:83]
	v_or_b32_e32 v78, 48, v151
	v_pk_mul_f32 v[76:77], v[66:67], v[68:69]
	v_cvt_pk_bf16_f32 v66, v70, v71
	v_mul_f32_e32 v70, 0xbfb8aa3b, v62
	v_cvt_pk_bf16_f32 v67, v72, v73
	v_exp_f32_e32 v72, v70
	v_mul_f32_e32 v70, 0xbfb8aa3b, v63
	v_exp_f32_e32 v73, v70
	v_mad_i64_i32 v[70:71], s[22:23], v78, s55, v[114:115]
	v_cvt_pk_bf16_f32 v68, v74, v75
	v_cvt_pk_bf16_f32 v69, v76, v77
	v_add_f32_e32 v72, 1.0, v72
	v_add_f32_e32 v73, 1.0, v73
	v_lshl_add_u64 v[70:71], v[70:71], 0, v[116:117]
	v_rcp_f32_e32 v72, v72
	v_rcp_f32_e32 v73, v73
	global_store_dwordx4 v[70:71], v[66:69], off
	v_pk_mul_f32 v[62:63], v[62:63], v[72:73]
	s_nop 0
	v_mul_f32_e32 v66, 0xbfb8aa3b, v64
	v_mul_f32_e32 v67, 0xbfb8aa3b, v65
	v_exp_f32_e32 v66, v66
	v_exp_f32_e32 v67, v67
	v_pk_mul_f32 v[54:55], v[62:63], v[54:55]
	v_add_u32_e32 v68, 0x80, v151
	v_add_f32_e32 v62, 1.0, v66
	v_add_f32_e32 v63, 1.0, v67
	v_mul_f32_e32 v66, 0xbfb8aa3b, v58
	v_mul_f32_e32 v67, 0xbfb8aa3b, v59
	v_rcp_f32_e32 v62, v62
	v_rcp_f32_e32 v63, v63
	v_exp_f32_e32 v66, v66
	v_exp_f32_e32 v67, v67
	v_pk_mul_f32 v[62:63], v[64:65], v[62:63]
	v_add_f32_e32 v64, 1.0, v66
; __device__ __forceinline__ float silu_f(float v) { return v * __builtin_amdgcn_rcpf(1.0f + __expf(-v)); }
; #define PG8_BAR __builtin_amdgcn_s_barrier()
; template <class Epi, bool SEG = false>
; __device__ __forceinline__ void gemm_phase(LAS unsigned char* lds, const Gemm g, const StaticOrder& S, const Epi& E, const float* stat2 = nullptr) {
;     ...
;         if (!has_next) break;
; #pragma unroll
;         for (int a = 0; a < 2; ++a)
; #pragma unroll
;             for (int b = 0; b < 2; ++b)
; #pragma unroll
;                 for (int m = 0; m < 4; ++m)
; #pragma unroll
;                     for (int n = 0; n < 2; ++n) acc[a][b][m][n] = (f32x4){0.f, 0.f, 0.f, 0.f};
;         cur = nxt; cA = nA; cB = nB; ++ui;
;         if (wr == 1) PG8_BAR;
;     }
;     __device__ __forceinline__ void operator()(const Acc& acc, const pg8::Unit& u, int wr, int wc, int fr, int fq) const {
;     ...
;         for (int ai = 0; ai < 2; ++ai)
; #pragma unroll
;             for (int m = 0; m < 4; ++m) {
;                 const int row = row0 + ai * 128 + m * 16; f32x4 o[2];
; #pragma unroll
;                 for (int n = 0; n < 2; ++n)
; #pragma unroll
;                     for (int i = 0; i < 4; ++i) o[n][i] = silu_f(acc[ai][0][m][n][i]) * acc[ai][1][m][n][i];
;                 *(u32x4*)(ACT + (size_t)row * DFF + col0) = pack8(o[0], o[1]);
	v_add_f32_e32 v65, 1.0, v67
	v_mul_f32_e32 v66, 0xbfb8aa3b, v60
	v_mul_f32_e32 v67, 0xbfb8aa3b, v61
	v_exp_f32_e32 v66, v66
	v_exp_f32_e32 v67, v67
	v_rcp_f32_e32 v64, v64
	v_rcp_f32_e32 v65, v65
	v_add_f32_e32 v66, 1.0, v66
	v_add_f32_e32 v67, 1.0, v67
	v_rcp_f32_e32 v66, v66
	v_rcp_f32_e32 v67, v67
	v_pk_mul_f32 v[58:59], v[58:59], v[64:65]
	v_pk_mul_f32 v[56:57], v[62:63], v[56:57]
	v_pk_mul_f32 v[58:59], v[58:59], v[50:51]
	v_pk_mul_f32 v[50:51], v[60:61], v[66:67]
	s_nop 0
	v_pk_mul_f32 v[60:61], v[50:51], v[52:53]
	v_mul_f32_e32 v53, 0xbfb8aa3b, v46
	v_cvt_pk_bf16_f32 v50, v54, v55
	v_exp_f32_e32 v54, v53
	v_mul_f32_e32 v53, 0xbfb8aa3b, v47
	v_exp_f32_e32 v55, v53
	v_cvt_pk_bf16_f32 v51, v56, v57
	v_mad_i64_i32 v[56:57], s[22:23], v68, s55, v[114:115]
	v_cvt_pk_bf16_f32 v52, v58, v59
	v_cvt_pk_bf16_f32 v53, v60, v61
	v_add_f32_e32 v54, 1.0, v54
	v_add_f32_e32 v55, 1.0, v55
	v_lshl_add_u64 v[56:57], v[56:57], 0, v[116:117]
	v_rcp_f32_e32 v54, v54
	v_rcp_f32_e32 v55, v55
	global_store_dwordx4 v[56:57], v[50:53], off
	v_pk_mul_f32 v[46:47], v[46:47], v[54:55]
	s_nop 0
	v_mul_f32_e32 v50, 0xbfb8aa3b, v48
	v_mul_f32_e32 v51, 0xbfb8aa3b, v49
	v_exp_f32_e32 v50, v50
	v_exp_f32_e32 v51, v51
	v_pk_mul_f32 v[38:39], v[46:47], v[38:39]
	v_add_f32_e32 v46, 1.0, v50
	v_add_f32_e32 v47, 1.0, v51
	v_mul_f32_e32 v50, 0xbfb8aa3b, v42
	v_mul_f32_e32 v51, 0xbfb8aa3b, v43
	v_rcp_f32_e32 v46, v46
	v_rcp_f32_e32 v47, v47
	v_exp_f32_e32 v50, v50
	v_exp_f32_e32 v51, v51
	v_pk_mul_f32 v[46:47], v[48:49], v[46:47]
	v_add_f32_e32 v48, 1.0, v50
	v_add_f32_e32 v49, 1.0, v51
	v_mul_f32_e32 v50, 0xbfb8aa3b, v44
	v_mul_f32_e32 v51, 0xbfb8aa3b, v45
	v_exp_f32_e32 v50, v50
	v_exp_f32_e32 v51, v51
	v_rcp_f32_e32 v48, v48
	v_rcp_f32_e32 v49, v49
	v_add_f32_e32 v50, 1.0, v50
	v_add_f32_e32 v51, 1.0, v51
	v_rcp_f32_e32 v50, v50
	v_rcp_f32_e32 v51, v51
	v_pk_mul_f32 v[42:43], v[42:43], v[48:49]
	v_pk_mul_f32 v[40:41], v[46:47], v[40:41]
	v_pk_mul_f32 v[42:43], v[42:43], v[34:35]
	v_pk_mul_f32 v[34:35], v[44:45], v[50:51]
	v_add_u32_e32 v46, 0x90, v151
	v_pk_mul_f32 v[44:45], v[34:35], v[36:37]
	v_mul_f32_e32 v37, 0xbfb8aa3b, v30
	v_cvt_pk_bf16_f32 v34, v38, v39
	v_exp_f32_e32 v38, v37
	v_mul_f32_e32 v37, 0xbfb8aa3b, v31
	v_exp_f32_e32 v39, v37
	v_cvt_pk_bf16_f32 v35, v40, v41
	v_mad_i64_i32 v[40:41], s[22:23], v46, s55, v[114:115]
	v_cvt_pk_bf16_f32 v36, v42, v43
	v_cvt_pk_bf16_f32 v37, v44, v45
	v_add_f32_e32 v38, 1.0, v38
	v_add_f32_e32 v39, 1.0, v39
	v_lshl_add_u64 v[40:41], v[40:41], 0, v[116:117]
	v_rcp_f32_e32 v38, v38
	v_rcp_f32_e32 v39, v39
	global_store_dwordx4 v[40:41], v[34:37], off
	v_pk_mul_f32 v[30:31], v[30:31], v[38:39]
	s_nop 0
	v_mul_f32_e32 v34, 0xbfb8aa3b, v32
	v_mul_f32_e32 v35, 0xbfb8aa3b, v33
	v_exp_f32_e32 v34, v34
	v_exp_f32_e32 v35, v35
	v_pk_mul_f32 v[22:23], v[30:31], v[22:23]
	v_add_f32_e32 v30, 1.0, v34
	v_add_f32_e32 v31, 1.0, v35
	v_mul_f32_e32 v34, 0xbfb8aa3b, v26
	v_mul_f32_e32 v35, 0xbfb8aa3b, v27
	v_rcp_f32_e32 v30, v30
	v_rcp_f32_e32 v31, v31
	v_exp_f32_e32 v34, v34
	v_exp_f32_e32 v35, v35
	v_pk_mul_f32 v[30:31], v[32:33], v[30:31]
	v_add_f32_e32 v32, 1.0, v34
	v_add_f32_e32 v33, 1.0, v35
	v_mul_f32_e32 v34, 0xbfb8aa3b, v28
	v_mul_f32_e32 v35, 0xbfb8aa3b, v29
	v_exp_f32_e32 v34, v34
	v_exp_f32_e32 v35, v35
	v_rcp_f32_e32 v32, v32
	v_rcp_f32_e32 v33, v33
	v_add_f32_e32 v34, 1.0, v34
	v_add_f32_e32 v35, 1.0, v35
	v_rcp_f32_e32 v34, v34
	v_rcp_f32_e32 v35, v35
	v_pk_mul_f32 v[26:27], v[26:27], v[32:33]
	v_pk_mul_f32 v[24:25], v[30:31], v[24:25]
	v_pk_mul_f32 v[26:27], v[26:27], v[18:19]
	v_pk_mul_f32 v[18:19], v[28:29], v[34:35]
	v_add_u32_e32 v30, 0xa0, v151
	v_pk_mul_f32 v[28:29], v[18:19], v[20:21]
	v_mul_f32_e32 v21, 0xbfb8aa3b, v14
	v_cvt_pk_bf16_f32 v18, v22, v23
	v_exp_f32_e32 v22, v21
	v_mul_f32_e32 v21, 0xbfb8aa3b, v15
	v_exp_f32_e32 v23, v21
	v_cvt_pk_bf16_f32 v19, v24, v25
	v_mad_i64_i32 v[24:25], s[22:23], v30, s55, v[114:115]
	v_cvt_pk_bf16_f32 v20, v26, v27
	v_cvt_pk_bf16_f32 v21, v28, v29
	v_add_f32_e32 v22, 1.0, v22
	v_add_f32_e32 v23, 1.0, v23
	v_lshl_add_u64 v[24:25], v[24:25], 0, v[116:117]
	v_rcp_f32_e32 v22, v22
	v_rcp_f32_e32 v23, v23
	global_store_dwordx4 v[24:25], v[18:21], off
	v_pk_mul_f32 v[14:15], v[14:15], v[22:23]
	s_nop 0
	v_mul_f32_e32 v18, 0xbfb8aa3b, v16
	v_mul_f32_e32 v19, 0xbfb8aa3b, v17
	v_exp_f32_e32 v18, v18
	v_exp_f32_e32 v19, v19
	v_pk_mul_f32 v[6:7], v[14:15], v[6:7]
	v_add_f32_e32 v14, 1.0, v18
	v_add_f32_e32 v15, 1.0, v19
	v_mul_f32_e32 v18, 0xbfb8aa3b, v10
	v_mul_f32_e32 v19, 0xbfb8aa3b, v11
	v_rcp_f32_e32 v14, v14
	v_rcp_f32_e32 v15, v15
	v_exp_f32_e32 v18, v18
	v_exp_f32_e32 v19, v19
	v_pk_mul_f32 v[14:15], v[16:17], v[14:15]
	v_add_f32_e32 v16, 1.0, v18
	v_add_f32_e32 v17, 1.0, v19
	v_mul_f32_e32 v18, 0xbfb8aa3b, v12
	v_mul_f32_e32 v19, 0xbfb8aa3b, v13
	v_exp_f32_e32 v18, v18
	v_exp_f32_e32 v19, v19
	v_rcp_f32_e32 v16, v16
	v_rcp_f32_e32 v17, v17
	v_add_f32_e32 v18, 1.0, v18
	v_add_f32_e32 v19, 1.0, v19
	v_rcp_f32_e32 v18, v18
	v_rcp_f32_e32 v19, v19
	v_pk_mul_f32 v[10:11], v[10:11], v[16:17]
	v_pk_mul_f32 v[8:9], v[14:15], v[8:9]
	v_pk_mul_f32 v[10:11], v[10:11], v[2:3]
	v_pk_mul_f32 v[2:3], v[12:13], v[18:19]
	v_add_u32_e32 v14, 0xb0, v151
	v_pk_mul_f32 v[12:13], v[2:3], v[4:5]
	v_cvt_pk_bf16_f32 v2, v6, v7
	v_mad_i64_i32 v[6:7], s[22:23], v14, s55, v[114:115]
	v_cvt_pk_bf16_f32 v3, v8, v9
	v_cvt_pk_bf16_f32 v4, v10, v11
	v_cvt_pk_bf16_f32 v5, v12, v13
	v_lshl_add_u64 v[6:7], v[6:7], 0, v[116:117]
	global_store_dwordx4 v[6:7], v[2:5], off
	s_cbranch_vccnz .LBB0_1203
	s_andn2_b64 vcc, exec, s[4:5]
	s_cbranch_vccnz .LBB0_1202
	s_barrier
	s_branch .LBB0_1202

; #define PG8_STAGE(bufoff, gbase, voff) do { _Pragma("unroll") for (int _i = 0; _i < 2; ++_i) \
;         __builtin_amdgcn_global_load_lds((const unsigned*)((const char*)(gbase) + (voff)[_i]), (LAS unsigned*)(lds + (bufoff) + ldsw + _i * 8192), 16, 0, 0); } while (0)
; #define PG8_LDA(dst, b, h) do { _Pragma("unroll") for (int m = 0; m < 4; ++m) _Pragma("unroll") for (int k = 0; k < 2; ++k) dst[m][k] = *(const LAS bf16x8*)(lds + PG8_SA(b, h) + aoff + m * 2048 + k * 1024); } while (0)
; #define PG8_LDB(dst, b, h) do { _Pragma("unroll") for (int n = 0; n < 2; ++n) _Pragma("unroll") for (int k = 0; k < 2; ++k) dst[n][k] = *(const LAS bf16x8*)(lds + PG8_SB(b, h) + boff + n * 2048 + k * 1024); } while (0)
; #define PG8_MMA(ai, bj, At, Bt) do { __builtin_amdgcn_s_setprio(1); _Pragma("unroll") for (int m = 0; m < 4; ++m) _Pragma("unroll") for (int n = 0; n < 2; ++n) _Pragma("unroll") for (int k = 0; k < 2; ++k) \
;         acc[ai][bj][m][n] = __builtin_amdgcn_mfma_f32_16x16x32_bf16(Bt[n][k], At[m][k], acc[ai][bj][m][n], 0, 0, 0); __builtin_amdgcn_s_setprio(0); } while (0)
; #define PG8_WAIT_V(n) asm volatile("s_waitcnt vmcnt(" #n ")" ::: "memory")
; #define PG8_WAIT_L(n) asm volatile("s_waitcnt lgkmcnt(" #n ")" ::: "memory")
; #define PG8_BAR __builtin_amdgcn_s_barrier()
; template <class Epi, bool SEG = false>
; __device__ __forceinline__ void gemm_phase(LAS unsigned char* lds, const Gemm g, const StaticOrder& S, const Epi& E, const float* stat2 = nullptr) {
;     ...
;         for (int t = tb; t < te; t += 2) {
;             const bool last = (t == nt - 2);
;             const char* a1 = cA + (size_t)(t + 1) * kstep;
;             const char* a2 = last ? nA : cA + (size_t)(t + 2) * kstep; const char* b2 = last ? nB : cB + (size_t)(t + 2) * kstep;
;             const char* a3 = a2 + kstep; const char* b3 = b2 + kstep;
;             PG8_LDB(B0, 0, 0); PG8_LDB(B1, 0, 1); PG8_SCHED; PG8_LDA(At, 0, 0); PG8_STAGE(PG8_SA(1, 1), a1 + hstepA, voffA);
;             PG8_WAIT_V(8); PG8_WAIT_L(0); PG8_BAR; PG8_MMA(0, 0, At, B0); PG8_MMA(0, 1, At, B1); PG8_BAR; PG8_SCHED;
;             PG8_LDA(At, 0, 1); PG8_STAGE(PG8_SB(0, 0), b2, voffB); PG8_STAGE(PG8_SB(0, 1), b2 + hstepB, voffB); PG8_STAGE(PG8_SA(0, 0), a2, voffA);
;             PG8_WAIT_V(8); PG8_WAIT_L(0); PG8_BAR; PG8_MMA(1, 0, At, B0); PG8_MMA(1, 1, At, B1); PG8_BAR; PG8_SCHED;
.LBB0_1288:
	ds_read_b128 v[146:149], v152
	ds_read_b128 v[156:159], v152 offset:1024
	ds_read_b128 v[160:163], v152 offset:2048
	ds_read_b128 v[164:167], v152 offset:3072
	ds_read_b128 v[168:171], v153
	ds_read_b128 v[172:175], v153 offset:1024
	ds_read_b128 v[176:179], v153 offset:2048
	ds_read_b128 v[180:183], v153 offset:3072
	s_add_u32 s22, s4, 0xffea0080
	s_addc_u32 s23, s5, -1
	s_cmpk_eq_i32 s59, 0x54
	s_cselect_b32 s25, s19, s23
	s_cselect_b32 s24, s18, s22
	s_cselect_b32 s23, s21, s58
	s_cselect_b32 s22, s20, s57
	v_lshl_add_u64 v[216:217], s[4:5], 0, v[138:139]
	s_add_i32 m0, s37, 0xc000
	ds_read_b128 v[184:187], v154
	ds_read_b128 v[188:191], v154 offset:1024
	ds_read_b128 v[192:195], v154 offset:2048
	ds_read_b128 v[196:199], v154 offset:3072
	ds_read_b128 v[200:203], v154 offset:4096
	ds_read_b128 v[204:207], v154 offset:5120
	ds_read_b128 v[208:211], v154 offset:6144
	ds_read_b128 v[212:215], v154 offset:7168
	global_load_lds_dwordx4 v[216:217], off
	v_lshl_add_u64 v[216:217], s[4:5], 0, v[140:141]
	s_add_i32 m0, s37, 0xe000
	s_nop 0
	global_load_lds_dwordx4 v[216:217], off
	s_cmp_eq_u32 s32, 0
	s_cbranch_scc0 .Lt1_rx4_0
	s_waitcnt vmcnt(8)
.Lt1_j4_0:
	s_waitcnt lgkmcnt(0)
	s_barrier
	s_setprio 1
	s_waitcnt lgkmcnt(0)
	v_mfma_f32_16x16x32_bf16 v[126:129], v[146:149], v[184:187], v[126:129]
	v_mfma_f32_16x16x32_bf16 v[122:125], v[160:163], v[184:187], v[122:125]
	v_mfma_f32_16x16x32_bf16 v[110:113], v[146:149], v[192:195], v[110:113]
	v_mfma_f32_16x16x32_bf16 v[106:109], v[160:163], v[192:195], v[106:109]
	v_mfma_f32_16x16x32_bf16 v[94:97], v[146:149], v[200:203], v[94:97]
	v_mfma_f32_16x16x32_bf16 v[90:93], v[160:163], v[200:203], v[90:93]
	v_mfma_f32_16x16x32_bf16 v[78:81], v[146:149], v[208:211], v[78:81]
	v_mfma_f32_16x16x32_bf16 v[74:77], v[160:163], v[208:211], v[74:77]
	v_mfma_f32_16x16x32_bf16 v[126:129], v[156:159], v[188:191], v[126:129]
	v_mfma_f32_16x16x32_bf16 v[122:125], v[164:167], v[188:191], v[122:125]
	v_mfma_f32_16x16x32_bf16 v[110:113], v[156:159], v[196:199], v[110:113]
	v_mfma_f32_16x16x32_bf16 v[106:109], v[164:167], v[196:199], v[106:109]
	v_mfma_f32_16x16x32_bf16 v[94:97], v[156:159], v[204:207], v[94:97]
	v_mfma_f32_16x16x32_bf16 v[90:93], v[164:167], v[204:207], v[90:93]
	v_mfma_f32_16x16x32_bf16 v[78:81], v[156:159], v[212:215], v[78:81]
	v_mfma_f32_16x16x32_bf16 v[74:77], v[164:167], v[212:215], v[74:77]
	s_setprio 0
	s_setprio 1
	v_mfma_f32_16x16x32_bf16 v[118:121], v[168:171], v[184:187], v[118:121]
	v_mfma_f32_16x16x32_bf16 v[114:117], v[176:179], v[184:187], v[114:117]
	v_mfma_f32_16x16x32_bf16 v[102:105], v[168:171], v[192:195], v[102:105]
	v_mfma_f32_16x16x32_bf16 v[98:101], v[176:179], v[192:195], v[98:101]
	v_mfma_f32_16x16x32_bf16 v[86:89], v[168:171], v[200:203], v[86:89]
	v_mfma_f32_16x16x32_bf16 v[82:85], v[176:179], v[200:203], v[82:85]
	v_mfma_f32_16x16x32_bf16 v[70:73], v[168:171], v[208:211], v[70:73]
	v_mfma_f32_16x16x32_bf16 v[66:69], v[176:179], v[208:211], v[66:69]
	v_mfma_f32_16x16x32_bf16 v[118:121], v[172:175], v[188:191], v[118:121]
	v_mfma_f32_16x16x32_bf16 v[114:117], v[180:183], v[188:191], v[114:117]
	v_mfma_f32_16x16x32_bf16 v[102:105], v[172:175], v[196:199], v[102:105]
	v_mfma_f32_16x16x32_bf16 v[98:101], v[180:183], v[196:199], v[98:101]
	v_mfma_f32_16x16x32_bf16 v[86:89], v[172:175], v[204:207], v[86:89]
	v_mfma_f32_16x16x32_bf16 v[82:85], v[180:183], v[204:207], v[82:85]
	v_mfma_f32_16x16x32_bf16 v[70:73], v[172:175], v[212:215], v[70:73]
	v_mfma_f32_16x16x32_bf16 v[66:69], v[180:183], v[212:215], v[66:69]
	s_setprio 0
	s_barrier
	s_add_i32 s30, s47, s36
	v_lshl_add_u64 v[216:217], s[22:23], 0, v[132:133]
	s_mov_b32 m0, s30
	ds_read_b128 v[184:187], v154 offset:16384
	ds_read_b128 v[188:191], v154 offset:17408
	ds_read_b128 v[192:195], v154 offset:18432
	ds_read_b128 v[196:199], v154 offset:19456
	ds_read_b128 v[200:203], v154 offset:20480
	ds_read_b128 v[204:207], v154 offset:21504
	ds_read_b128 v[208:211], v154 offset:22528
	ds_read_b128 v[212:215], v154 offset:23552
	global_load_lds_dwordx4 v[216:217], off
	s_add_i32 m0, s30, 0x2000
	s_add_u32 s30, s22, 0x160000
	v_lshl_add_u64 v[218:219], s[22:23], 0, v[136:137]
	s_addc_u32 s31, s23, 0
	s_add_i32 s60, s52, s36
	global_load_lds_dwordx4 v[218:219], off
	v_lshl_add_u64 v[220:221], s[30:31], 0, v[132:133]
	s_mov_b32 m0, s60
	v_lshl_add_u64 v[222:223], s[24:25], 0, v[134:135]
	global_load_lds_dwordx4 v[220:221], off
	v_lshl_add_u64 v[220:221], s[30:31], 0, v[136:137]
	s_add_i32 m0, s60, 0x2000
	s_nop 0
	global_load_lds_dwordx4 v[220:221], off
	v_lshl_add_u64 v[220:221], s[24:25], 0, v[130:131]
	s_mov_b32 m0, s37
	s_nop 0
	global_load_lds_dwordx4 v[220:221], off
	s_mov_b32 m0, s38
	s_nop 0
	global_load_lds_dwordx4 v[222:223], off
	s_cmp_eq_u32 s32, 0
	s_cbranch_scc0 .Lt1_rx4_1
	s_waitcnt vmcnt(8)
; #define PG8_STAGE(bufoff, gbase, voff) do { _Pragma("unroll") for (int _i = 0; _i < 2; ++_i) \
;         __builtin_amdgcn_global_load_lds((const unsigned*)((const char*)(gbase) + (voff)[_i]), (LAS unsigned*)(lds + (bufoff) + ldsw + _i * 8192), 16, 0, 0); } while (0)
; #define PG8_LDA(dst, b, h) do { _Pragma("unroll") for (int m = 0; m < 4; ++m) _Pragma("unroll") for (int k = 0; k < 2; ++k) dst[m][k] = *(const LAS bf16x8*)(lds + PG8_SA(b, h) + aoff + m * 2048 + k * 1024); } while (0)
; #define PG8_LDB(dst, b, h) do { _Pragma("unroll") for (int n = 0; n < 2; ++n) _Pragma("unroll") for (int k = 0; k < 2; ++k) dst[n][k] = *(const LAS bf16x8*)(lds + PG8_SB(b, h) + boff + n * 2048 + k * 1024); } while (0)
; #define PG8_MMA(ai, bj, At, Bt) do { __builtin_amdgcn_s_setprio(1); _Pragma("unroll") for (int m = 0; m < 4; ++m) _Pragma("unroll") for (int n = 0; n < 2; ++n) _Pragma("unroll") for (int k = 0; k < 2; ++k) \
;         acc[ai][bj][m][n] = __builtin_amdgcn_mfma_f32_16x16x32_bf16(Bt[n][k], At[m][k], acc[ai][bj][m][n], 0, 0, 0); __builtin_amdgcn_s_setprio(0); } while (0)
; #define PG8_WAIT_V(n) asm volatile("s_waitcnt vmcnt(" #n ")" ::: "memory")
; #define PG8_WAIT_L(n) asm volatile("s_waitcnt lgkmcnt(" #n ")" ::: "memory")
; #define PG8_BAR __builtin_amdgcn_s_barrier()
; #define PG8_SCHED __builtin_amdgcn_sched_barrier(0)
; template <class Epi, bool SEG = false>
; __device__ __forceinline__ void gemm_phase(LAS unsigned char* lds, const Gemm g, const StaticOrder& S, const Epi& E, const float* stat2 = nullptr) {
;     ...
;             PG8_WAIT_V(8); PG8_WAIT_L(0); PG8_BAR; PG8_MMA(1, 0, At, B0); PG8_MMA(1, 1, At, B1); PG8_BAR; PG8_SCHED;
;             PG8_LDB(B0, 1, 0); PG8_LDB(B1, 1, 1); PG8_SCHED; PG8_LDA(At, 1, 0); PG8_STAGE(PG8_SA(0, 1), a2 + hstepA, voffA);
;             PG8_WAIT_V(8); PG8_WAIT_L(0); PG8_BAR; PG8_MMA(0, 0, At, B0); PG8_MMA(0, 1, At, B1); PG8_BAR; PG8_SCHED;
;             PG8_LDA(At, 1, 1); PG8_STAGE(PG8_SB(1, 0), b3, voffB); PG8_STAGE(PG8_SB(1, 1), b3 + hstepB, voffB); PG8_STAGE(PG8_SA(1, 0), a3, voffA);
;             PG8_WAIT_V(8); PG8_WAIT_L(0); PG8_BAR; PG8_MMA(1, 0, At, B0); PG8_MMA(1, 1, At, B1); PG8_BAR; PG8_SCHED;
.Lt1_j4_1:
	s_waitcnt lgkmcnt(0)
	s_barrier
	s_setprio 1
	s_waitcnt lgkmcnt(0)
	v_mfma_f32_16x16x32_bf16 v[62:65], v[146:149], v[184:187], v[62:65]
	v_mfma_f32_16x16x32_bf16 v[58:61], v[160:163], v[184:187], v[58:61]
	v_mfma_f32_16x16x32_bf16 v[46:49], v[146:149], v[192:195], v[46:49]
	v_mfma_f32_16x16x32_bf16 v[42:45], v[160:163], v[192:195], v[42:45]
	v_mfma_f32_16x16x32_bf16 v[30:33], v[146:149], v[200:203], v[30:33]
	v_mfma_f32_16x16x32_bf16 v[26:29], v[160:163], v[200:203], v[26:29]
	v_mfma_f32_16x16x32_bf16 v[14:17], v[146:149], v[208:211], v[14:17]
	v_mfma_f32_16x16x32_bf16 v[10:13], v[160:163], v[208:211], v[10:13]
	v_mfma_f32_16x16x32_bf16 v[62:65], v[156:159], v[188:191], v[62:65]
	v_mfma_f32_16x16x32_bf16 v[58:61], v[164:167], v[188:191], v[58:61]
	v_mfma_f32_16x16x32_bf16 v[46:49], v[156:159], v[196:199], v[46:49]
	v_mfma_f32_16x16x32_bf16 v[42:45], v[164:167], v[196:199], v[42:45]
	v_mfma_f32_16x16x32_bf16 v[30:33], v[156:159], v[204:207], v[30:33]
	v_mfma_f32_16x16x32_bf16 v[26:29], v[164:167], v[204:207], v[26:29]
	v_mfma_f32_16x16x32_bf16 v[14:17], v[156:159], v[212:215], v[14:17]
	v_mfma_f32_16x16x32_bf16 v[10:13], v[164:167], v[212:215], v[10:13]
	s_setprio 0
	s_setprio 1
	v_mfma_f32_16x16x32_bf16 v[54:57], v[168:171], v[184:187], v[54:57]
	v_mfma_f32_16x16x32_bf16 v[50:53], v[176:179], v[184:187], v[50:53]
	v_mfma_f32_16x16x32_bf16 v[38:41], v[168:171], v[192:195], v[38:41]
	v_mfma_f32_16x16x32_bf16 v[34:37], v[176:179], v[192:195], v[34:37]
	v_mfma_f32_16x16x32_bf16 v[22:25], v[168:171], v[200:203], v[22:25]
	v_mfma_f32_16x16x32_bf16 v[18:21], v[176:179], v[200:203], v[18:21]
	v_mfma_f32_16x16x32_bf16 v[6:9], v[168:171], v[208:211], v[6:9]
	v_mfma_f32_16x16x32_bf16 v[2:5], v[176:179], v[208:211], v[2:5]
	v_mfma_f32_16x16x32_bf16 v[54:57], v[172:175], v[188:191], v[54:57]
	v_mfma_f32_16x16x32_bf16 v[50:53], v[180:183], v[188:191], v[50:53]
	v_mfma_f32_16x16x32_bf16 v[38:41], v[172:175], v[196:199], v[38:41]
	v_mfma_f32_16x16x32_bf16 v[34:37], v[180:183], v[196:199], v[34:37]
	v_mfma_f32_16x16x32_bf16 v[22:25], v[172:175], v[204:207], v[22:25]
	v_mfma_f32_16x16x32_bf16 v[18:21], v[180:183], v[204:207], v[18:21]
	v_mfma_f32_16x16x32_bf16 v[6:9], v[172:175], v[212:215], v[6:9]
	v_mfma_f32_16x16x32_bf16 v[2:5], v[180:183], v[212:215], v[2:5]
	s_setprio 0
	s_barrier
	s_add_i32 s30, 0, 0x18000
	s_add_i32 s31, 0, 0x1c000
	v_add_u32_e32 v164, s30, v150
	v_add_u32_e32 v180, s31, v150
	ds_read_b128 v[146:149], v164
	ds_read_b128 v[156:159], v164 offset:1024
	ds_read_b128 v[160:163], v164 offset:2048
	ds_read_b128 v[164:167], v164 offset:3072
	ds_read_b128 v[168:171], v180
	ds_read_b128 v[172:175], v180 offset:1024
	ds_read_b128 v[176:179], v180 offset:2048
	ds_read_b128 v[180:183], v180 offset:3072
	s_add_u32 s24, s24, 0x160000
	s_addc_u32 s25, s25, 0
	s_mov_b32 m0, s39
	v_lshl_add_u64 v[224:225], s[24:25], 0, v[130:131]
	ds_read_b128 v[184:187], v154 offset:32768
	ds_read_b128 v[188:191], v154 offset:33792
	ds_read_b128 v[192:195], v154 offset:34816
	ds_read_b128 v[196:199], v154 offset:35840
	ds_read_b128 v[200:203], v154 offset:36864
	ds_read_b128 v[204:207], v154 offset:37888
	ds_read_b128 v[208:211], v154 offset:38912
	ds_read_b128 v[212:215], v154 offset:39936
	global_load_lds_dwordx4 v[224:225], off
	v_lshl_add_u64 v[224:225], s[24:25], 0, v[134:135]
	s_mov_b32 m0, s42
	s_nop 0
	global_load_lds_dwordx4 v[224:225], off
	s_waitcnt vmcnt(8)
	s_waitcnt lgkmcnt(0)
	s_barrier
	s_setprio 1
	s_waitcnt lgkmcnt(0)
	v_mfma_f32_16x16x32_bf16 v[126:129], v[146:149], v[184:187], v[126:129]
	v_mfma_f32_16x16x32_bf16 v[122:125], v[160:163], v[184:187], v[122:125]
	v_mfma_f32_16x16x32_bf16 v[110:113], v[146:149], v[192:195], v[110:113]
	v_mfma_f32_16x16x32_bf16 v[106:109], v[160:163], v[192:195], v[106:109]
	v_mfma_f32_16x16x32_bf16 v[94:97], v[146:149], v[200:203], v[94:97]
	v_mfma_f32_16x16x32_bf16 v[90:93], v[160:163], v[200:203], v[90:93]
	v_mfma_f32_16x16x32_bf16 v[78:81], v[146:149], v[208:211], v[78:81]
	v_mfma_f32_16x16x32_bf16 v[74:77], v[160:163], v[208:211], v[74:77]
	v_mfma_f32_16x16x32_bf16 v[126:129], v[156:159], v[188:191], v[126:129]
	v_mfma_f32_16x16x32_bf16 v[122:125], v[164:167], v[188:191], v[122:125]
	v_mfma_f32_16x16x32_bf16 v[110:113], v[156:159], v[196:199], v[110:113]
	v_mfma_f32_16x16x32_bf16 v[106:109], v[164:167], v[196:199], v[106:109]
	v_mfma_f32_16x16x32_bf16 v[94:97], v[156:159], v[204:207], v[94:97]
	v_mfma_f32_16x16x32_bf16 v[90:93], v[164:167], v[204:207], v[90:93]
	v_mfma_f32_16x16x32_bf16 v[78:81], v[156:159], v[212:215], v[78:81]
	v_mfma_f32_16x16x32_bf16 v[74:77], v[164:167], v[212:215], v[74:77]
	s_setprio 0
	s_setprio 1
	v_mfma_f32_16x16x32_bf16 v[118:121], v[168:171], v[184:187], v[118:121]
	v_mfma_f32_16x16x32_bf16 v[114:117], v[176:179], v[184:187], v[114:117]
	v_mfma_f32_16x16x32_bf16 v[102:105], v[168:171], v[192:195], v[102:105]
	v_mfma_f32_16x16x32_bf16 v[98:101], v[176:179], v[192:195], v[98:101]
	v_mfma_f32_16x16x32_bf16 v[86:89], v[168:171], v[200:203], v[86:89]
	v_mfma_f32_16x16x32_bf16 v[82:85], v[176:179], v[200:203], v[82:85]
	v_mfma_f32_16x16x32_bf16 v[70:73], v[168:171], v[208:211], v[70:73]
	v_mfma_f32_16x16x32_bf16 v[66:69], v[176:179], v[208:211], v[66:69]
	v_mfma_f32_16x16x32_bf16 v[118:121], v[172:175], v[188:191], v[118:121]
	v_mfma_f32_16x16x32_bf16 v[114:117], v[180:183], v[188:191], v[114:117]
	v_mfma_f32_16x16x32_bf16 v[102:105], v[172:175], v[196:199], v[102:105]
	v_mfma_f32_16x16x32_bf16 v[98:101], v[180:183], v[196:199], v[98:101]
	v_mfma_f32_16x16x32_bf16 v[86:89], v[172:175], v[204:207], v[86:89]
	v_mfma_f32_16x16x32_bf16 v[82:85], v[180:183], v[204:207], v[82:85]
	v_mfma_f32_16x16x32_bf16 v[70:73], v[172:175], v[212:215], v[70:73]
	v_mfma_f32_16x16x32_bf16 v[66:69], v[180:183], v[212:215], v[66:69]
	s_setprio 0
	s_barrier
; #define PG8_STAGE(bufoff, gbase, voff) do { _Pragma("unroll") for (int _i = 0; _i < 2; ++_i) \
;         __builtin_amdgcn_global_load_lds((const unsigned*)((const char*)(gbase) + (voff)[_i]), (LAS unsigned*)(lds + (bufoff) + ldsw + _i * 8192), 16, 0, 0); } while (0)
; #define PG8_LDA(dst, b, h) do { _Pragma("unroll") for (int m = 0; m < 4; ++m) _Pragma("unroll") for (int k = 0; k < 2; ++k) dst[m][k] = *(const LAS bf16x8*)(lds + PG8_SA(b, h) + aoff + m * 2048 + k * 1024); } while (0)
; #define PG8_WAIT_V(n) asm volatile("s_waitcnt vmcnt(" #n ")" ::: "memory")
; #define PG8_BAR __builtin_amdgcn_s_barrier()
; template <class Epi, bool SEG = false>
; __device__ __forceinline__ void gemm_phase(LAS unsigned char* lds, const Gemm g, const StaticOrder& S, const Epi& E, const float* stat2 = nullptr) {
;     ...
;             PG8_LDA(At, 1, 1); PG8_STAGE(PG8_SB(1, 0), b3, voffB); PG8_STAGE(PG8_SB(1, 1), b3 + hstepB, voffB); PG8_STAGE(PG8_SA(1, 0), a3, voffA);
;             PG8_WAIT_V(8); PG8_WAIT_L(0); PG8_BAR; PG8_MMA(1, 0, At, B0); PG8_MMA(1, 1, At, B1); PG8_BAR; PG8_SCHED;
;         }
;         }
;         if (wr == 0) PG8_BAR;
;         if constexpr (SEG) seg_scale(acc, lds, ui & 1, 2, wr, fr);
;         E(acc, cur, wr, wc, fr, fq);
;         if constexpr (SEG) { if (has_next) seg_fill(lds, stat2, nxt.pm, (ui + 1) & 1); }
;         if (!has_next) break;
;     __device__ __forceinline__ void operator()(const Acc& acc, const pg8::Unit& u, int wr, int wc, int fr, int fq) const {
;         const int row0 = u.pm * 256 + wr * 64 + fr, col0 = u.pn * 256 + wc * 32 + 8 * fq;
;         const bool st = (u.pn < stat_pn);
; #pragma unroll
;         for (int ai = 0; ai < 2; ++ai)
; #pragma unroll
;             for (int m = 0; m < 4; ++m) {
;                 const int row = row0 + ai * 128 + m * 16; bf16_t* rowp = O + (size_t)row * ldc + col0; float ss = 0.f;
; #pragma unroll
;                 for (int bj = 0; bj < 2; ++bj) { const f32x4 v0 = acc[ai][bj][m][0], v1 = acc[ai][bj][m][1];
;                     ss += (v0[0] * v0[0] + v0[1] * v0[1]) + (v0[2] * v0[2] + v0[3] * v0[3]) + (v1[0] * v1[0] + v1[1] * v1[1]) + (v1[2] * v1[2] + v1[3] * v1[3]);
;                     *(u32x4*)(rowp + bj * 128) = pack8(v0, v1); }
;                 if (st) { ss += __shfl_xor(ss, 16); ss += __shfl_xor(ss, 32); if (fq == 0) stat[(size_t)row * 16 + u.pn * 4 + wc] = ss; }
;             }
	s_add_i32 s24, s30, s36
	v_lshl_add_u64 v[216:217], v[216:217], 0, s[14:15]
	s_mov_b32 m0, s24
	ds_read_b128 v[184:187], v154 offset:49152
	ds_read_b128 v[188:191], v154 offset:50176
	ds_read_b128 v[192:195], v154 offset:51200
	ds_read_b128 v[196:199], v154 offset:52224
	ds_read_b128 v[200:203], v154 offset:53248
	ds_read_b128 v[204:207], v154 offset:54272
	ds_read_b128 v[208:211], v154 offset:55296
	ds_read_b128 v[212:215], v154 offset:56320
	global_load_lds_dwordx4 v[216:217], off
	s_add_i32 m0, s24, 0x2000
	s_add_u32 s22, s22, 0x160080
	v_lshl_add_u64 v[216:217], v[218:219], 0, s[14:15]
	s_addc_u32 s23, s23, 0
	s_add_i32 s24, s31, s36
	global_load_lds_dwordx4 v[216:217], off
	v_lshl_add_u64 v[216:217], s[22:23], 0, v[132:133]
	s_mov_b32 m0, s24
	s_nop 0
	global_load_lds_dwordx4 v[216:217], off
	v_lshl_add_u64 v[216:217], s[22:23], 0, v[136:137]
	s_add_i32 m0, s24, 0x2000
	s_nop 0
	global_load_lds_dwordx4 v[216:217], off
	v_lshl_add_u64 v[216:217], v[220:221], 0, s[14:15]
	s_mov_b32 m0, s43
	s_nop 0
	global_load_lds_dwordx4 v[216:217], off
	v_lshl_add_u64 v[216:217], v[222:223], 0, s[14:15]
	s_mov_b32 m0, s44
	s_nop 0
	global_load_lds_dwordx4 v[216:217], off
	s_waitcnt vmcnt(8)
	s_waitcnt lgkmcnt(0)
	s_barrier
	s_setprio 1
	s_waitcnt lgkmcnt(0)
	v_mfma_f32_16x16x32_bf16 v[62:65], v[146:149], v[184:187], v[62:65]
	v_mfma_f32_16x16x32_bf16 v[58:61], v[160:163], v[184:187], v[58:61]
	v_mfma_f32_16x16x32_bf16 v[46:49], v[146:149], v[192:195], v[46:49]
	v_mfma_f32_16x16x32_bf16 v[42:45], v[160:163], v[192:195], v[42:45]
	v_mfma_f32_16x16x32_bf16 v[30:33], v[146:149], v[200:203], v[30:33]
	v_mfma_f32_16x16x32_bf16 v[26:29], v[160:163], v[200:203], v[26:29]
	v_mfma_f32_16x16x32_bf16 v[14:17], v[146:149], v[208:211], v[14:17]
	v_mfma_f32_16x16x32_bf16 v[10:13], v[160:163], v[208:211], v[10:13]
	v_mfma_f32_16x16x32_bf16 v[62:65], v[156:159], v[188:191], v[62:65]
	v_mfma_f32_16x16x32_bf16 v[58:61], v[164:167], v[188:191], v[58:61]
	v_mfma_f32_16x16x32_bf16 v[46:49], v[156:159], v[196:199], v[46:49]
	v_mfma_f32_16x16x32_bf16 v[42:45], v[164:167], v[196:199], v[42:45]
	v_mfma_f32_16x16x32_bf16 v[30:33], v[156:159], v[204:207], v[30:33]
	v_mfma_f32_16x16x32_bf16 v[26:29], v[164:167], v[204:207], v[26:29]
	v_mfma_f32_16x16x32_bf16 v[14:17], v[156:159], v[212:215], v[14:17]
	v_mfma_f32_16x16x32_bf16 v[10:13], v[164:167], v[212:215], v[10:13]
	s_setprio 0
	s_setprio 1
	v_mfma_f32_16x16x32_bf16 v[54:57], v[168:171], v[184:187], v[54:57]
	v_mfma_f32_16x16x32_bf16 v[50:53], v[176:179], v[184:187], v[50:53]
	v_mfma_f32_16x16x32_bf16 v[38:41], v[168:171], v[192:195], v[38:41]
	v_mfma_f32_16x16x32_bf16 v[34:37], v[176:179], v[192:195], v[34:37]
	v_mfma_f32_16x16x32_bf16 v[22:25], v[168:171], v[200:203], v[22:25]
	v_mfma_f32_16x16x32_bf16 v[18:21], v[176:179], v[200:203], v[18:21]
	v_mfma_f32_16x16x32_bf16 v[6:9], v[168:171], v[208:211], v[6:9]
	v_mfma_f32_16x16x32_bf16 v[2:5], v[176:179], v[208:211], v[2:5]
	v_mfma_f32_16x16x32_bf16 v[54:57], v[172:175], v[188:191], v[54:57]
	v_mfma_f32_16x16x32_bf16 v[50:53], v[180:183], v[188:191], v[50:53]
	v_mfma_f32_16x16x32_bf16 v[38:41], v[172:175], v[196:199], v[38:41]
	v_mfma_f32_16x16x32_bf16 v[34:37], v[180:183], v[196:199], v[34:37]
	v_mfma_f32_16x16x32_bf16 v[22:25], v[172:175], v[204:207], v[22:25]
	v_mfma_f32_16x16x32_bf16 v[18:21], v[180:183], v[204:207], v[18:21]
	v_mfma_f32_16x16x32_bf16 v[6:9], v[172:175], v[212:215], v[6:9]
	v_mfma_f32_16x16x32_bf16 v[2:5], v[180:183], v[212:215], v[2:5]
	s_setprio 0
	s_barrier
	s_add_i32 s59, s59, 2
	s_add_u32 s4, s4, 0x100
	s_addc_u32 s5, s5, 0
	s_add_u32 s57, s57, 0x100
	s_addc_u32 s58, s58, 0
	s_cmpk_gt_u32 s59, 0x55
	s_cbranch_scc0 .LBB0_1288
	s_and_b64 vcc, exec, s[16:17]
	s_cbranch_vccz .LBB0_1291
	s_barrier
.LBB0_1291:
	s_mov_b32 s32, 1
	v_lshl_add_u32 v148, s56, 8, v1
	v_ashrrev_i32_e32 v149, 31, v148
	v_lshl_or_b32 v146, s8, 8, v151
	s_cmp_lt_i32 s8, 0
	v_lshlrev_b64 v[156:157], 12, v[148:149]
	s_cselect_b64 s[24:25], -1, 0
	s_lshl_b32 s22, s8, 2
	v_ashrrev_i32_e32 v147, 31, v146
	v_lshl_add_u64 v[156:157], s[12:13], 0, v[156:157]
	s_ashr_i32 s23, s22, 31
	v_lshl_add_u64 v[160:161], v[146:147], 1, v[156:157]
	v_cvt_pk_bf16_f32 v156, v126, v127
	v_cvt_pk_bf16_f32 v157, v128, v129
	v_cvt_pk_bf16_f32 v158, v122, v123
	v_cvt_pk_bf16_f32 v159, v124, v125
	s_cmp_gt_i32 s8, -1
	global_store_dwordx4 v[160:161], v[156:159], off
	s_nop 1
	v_cvt_pk_bf16_f32 v156, v118, v119
	v_cvt_pk_bf16_f32 v157, v120, v121
	v_cvt_pk_bf16_f32 v158, v114, v115
	v_cvt_pk_bf16_f32 v159, v116, v117
	global_store_dwordx4 v[160:161], v[156:159], off offset:256
	s_cbranch_scc1 .LBB0_1295
	v_mul_f32_e32 v117, v117, v117
	v_fmac_f32_e32 v117, v116, v116
	v_mul_f32_e32 v116, v119, v119
	v_mul_f32_e32 v125, v125, v125
	v_fmac_f32_e32 v116, v118, v118
	v_mul_f32_e32 v118, v121, v121
	v_fmac_f32_e32 v125, v124, v124
	v_mul_f32_e32 v124, v127, v127
	v_fmac_f32_e32 v118, v120, v120
	v_mul_f32_e32 v115, v115, v115
	v_fmac_f32_e32 v124, v126, v126
	v_mul_f32_e32 v126, v129, v129
	v_add_f32_e32 v116, v116, v118
	v_fmac_f32_e32 v115, v114, v114
	v_fmac_f32_e32 v126, v128, v128
	v_mul_f32_e32 v123, v123, v123
	v_add_f32_e32 v114, v116, v115
	v_and_b32_e32 v116, 64, v155
	v_add_f32_e32 v124, v124, v126
	v_fmac_f32_e32 v123, v122, v122
	v_xor_b32_e32 v115, 16, v155
	v_add_u32_e32 v116, 64, v116
	v_add_f32_e32 v122, v124, v123
	v_cmp_lt_i32_e32 vcc, v115, v116
	v_add_f32_e32 v122, v125, v122
	v_add_f32_e32 v114, v117, v114
	v_cndmask_b32_e32 v115, v155, v115, vcc
	v_add_f32_e32 v114, v122, v114
	v_lshlrev_b32_e32 v115, 2, v115
	ds_bpermute_b32 v115, v115, v114
	s_waitcnt lgkmcnt(0)
	v_add_f32_e32 v114, v114, v115
	v_xor_b32_e32 v115, 32, v155
	v_cmp_lt_i32_e32 vcc, v115, v116
	s_nop 1
	v_cndmask_b32_e32 v115, v155, v115, vcc
	v_lshlrev_b32_e32 v115, 2, v115
	ds_bpermute_b32 v115, v115, v114
	s_and_saveexec_b64 s[4:5], s[0:1]
	s_cbranch_execz .LBB0_1294
	v_lshlrev_b64 v[116:117], 6, v[148:149]
	v_lshl_add_u64 v[116:117], s[22:23], 2, v[116:117]
	s_lshl_b32 s8, s33, 2
	v_lshl_add_u64 v[116:117], v[116:117], 0, s[8:9]
	s_waitcnt lgkmcnt(0)
	v_add_f32_e32 v114, v114, v115
	flat_store_dword v[116:117], v114
